# v19: v18 + lever 7: K-loop LDS-DMA loads take scalar base + 32-bit lane offset (113 pieces), 76 per-piece 64-bit VALU address adds deleted
# speedup vs baseline: 1.0051x; 1.0043x over previous
; #define PG8_STAGE(bufoff, gbase, voff) do { _Pragma("unroll") for (int _i = 0; _i < 2; ++_i) \
;         __builtin_amdgcn_global_load_lds((const unsigned*)((const char*)(gbase) + (voff)[_i]), (PG8_LAS unsigned*)(lds + (bufoff) + ldsw + _i * 8192), 16, 0, 0); } while (0)
; #define PG8_LDA(dst, b, h) do { _Pragma("unroll") for (int m = 0; m < 4; ++m) _Pragma("unroll") for (int k = 0; k < 2; ++k) dst[m][k] = *(const PG8_LAS bf16x8*)(lds + PG8_SA(b, h) + aoff + m * 2048 + k * 1024); } while (0)
; #define PG8_LDB(dst, b, h) do { _Pragma("unroll") for (int n = 0; n < 2; ++n) _Pragma("unroll") for (int k = 0; k < 2; ++k) dst[n][k] = *(const PG8_LAS bf16x8*)(lds + PG8_SB(b, h) + boff + n * 2048 + k * 1024); } while (0)
; #define PG8_MMA(ai, bj, At, Bt) do { __builtin_amdgcn_s_setprio(1); _Pragma("unroll") for (int m = 0; m < 4; ++m) _Pragma("unroll") for (int n = 0; n < 2; ++n) _Pragma("unroll") for (int k = 0; k < 2; ++k) \
;         acc[ai][bj][m][n] = mma_<I8>(Bt[n][k], At[m][k], acc[ai][bj][m][n]); __builtin_amdgcn_s_setprio(0); } while (0)
; #define PG8_WAIT_V(n) asm volatile("s_waitcnt vmcnt(" #n ")" ::: "memory")
; #define PG8_WAIT_L(n) asm volatile("s_waitcnt lgkmcnt(" #n ")" ::: "memory")
; #define PG8_BAR __builtin_amdgcn_s_barrier()
; #define PG8_SCHED __builtin_amdgcn_sched_barrier(0)
; template <class Epi, class Sched, bool ALIGN_EPI = false, bool SP2 = false, bool I8 = false>
; __device__ __forceinline__ void gemm_phase(PG8_LAS unsigned char* lds, const Gemm g, const Sched& S, const Epi& E) {
;     ...
;             PG8_LDB(B0, 0, 0); PG8_LDB(B1, 0, 1); PG8_SCHED; PG8_LDA(At, 0, 0); PG8_STAGE(PG8_SA(1, 1), a1 + hstepA, voffA);
;             PG8_WAIT_V(8); PG8_WAIT_L(0); PG8_BAR; PG8_MMA(0, 0, At, B0); PG8_MMA(0, 1, At, B1); PG8_BAR; PG8_SCHED;
;             PG8_LDA(At, 0, 1); PG8_STAGE(PG8_SB(0, 0), b2, voffB); PG8_STAGE(PG8_SB(0, 1), b2 + hstepB, voffB); PG8_STAGE(PG8_SA(0, 0), a2, voffA);
;             PG8_WAIT_V(8); PG8_WAIT_L(0); PG8_BAR; PG8_MMA(1, 0, At, B0); PG8_MMA(1, 1, At, B1); PG8_BAR; PG8_SCHED;
;             PG8_LDB(B0, 1, 0); PG8_LDB(B1, 1, 1); PG8_SCHED; PG8_LDA(At, 1, 0); PG8_STAGE(PG8_SA(0, 1), a2 + hstepA, voffA);
;             PG8_WAIT_V(8); PG8_WAIT_L(0); PG8_BAR; PG8_MMA(0, 0, At, B0); PG8_MMA(0, 1, At, B1); PG8_BAR; PG8_SCHED;
.LBB0_483:
	ds_read_b128 v[58:61], v187
	ds_read_b128 v[62:65], v187 offset:1024
	ds_read_b128 v[74:77], v187 offset:2048
	ds_read_b128 v[78:81], v187 offset:3072
	ds_read_b128 v[162:165], v188
	ds_read_b128 v[166:169], v188 offset:1024
	ds_read_b128 v[170:173], v188 offset:2048
	ds_read_b128 v[190:193], v188 offset:3072
	s_add_u32 s34, s2, 0xfff80080
	s_addc_u32 s35, s3, -1
	s_cmp_eq_u32 s40, 28
	s_cselect_b32 s37, s7, s35
	s_cselect_b32 s36, s25, s34
	s_cselect_b32 s35, s23, s39
	s_cselect_b32 s34, s33, s38
	s_add_i32 m0, s31, 0xc000
	ds_read_b128 v[194:197], v189
	ds_read_b128 v[198:201], v189 offset:1024
	ds_read_b128 v[202:205], v189 offset:2048
	ds_read_b128 v[206:209], v189 offset:3072
	ds_read_b128 v[210:213], v189 offset:4096
	ds_read_b128 v[214:217], v189 offset:5120
	ds_read_b128 v[218:221], v189 offset:6144
	ds_read_b128 v[222:225], v189 offset:7168
	global_load_lds_dwordx4 v154, s[2:3]
	s_add_i32 m0, s31, 0xe000
	s_nop 0
	global_load_lds_dwordx4 v156, s[2:3]
	s_waitcnt vmcnt(8)
	s_waitcnt lgkmcnt(0)
	s_barrier
	s_waitcnt lgkmcnt(0)
	v_mfma_i32_16x16x64_i8 v[142:145], v[58:61], v[194:197], v[142:145]
	v_mfma_i32_16x16x64_i8 v[138:141], v[74:77], v[194:197], v[138:141]
	v_mfma_i32_16x16x64_i8 v[126:129], v[58:61], v[202:205], v[126:129]
	v_mfma_i32_16x16x64_i8 v[122:125], v[74:77], v[202:205], v[122:125]
	v_mfma_i32_16x16x64_i8 v[110:113], v[58:61], v[210:213], v[110:113]
	v_mfma_i32_16x16x64_i8 v[106:109], v[74:77], v[210:213], v[106:109]
	v_mfma_i32_16x16x64_i8 v[94:97], v[58:61], v[218:221], v[94:97]
	v_mfma_i32_16x16x64_i8 v[90:93], v[74:77], v[218:221], v[90:93]
	v_mfma_i32_16x16x64_i8 v[142:145], v[62:65], v[198:201], v[142:145]
	v_mfma_i32_16x16x64_i8 v[138:141], v[78:81], v[198:201], v[138:141]
	v_mfma_i32_16x16x64_i8 v[126:129], v[62:65], v[206:209], v[126:129]
	v_mfma_i32_16x16x64_i8 v[122:125], v[78:81], v[206:209], v[122:125]
	v_mfma_i32_16x16x64_i8 v[110:113], v[62:65], v[214:217], v[110:113]
	v_mfma_i32_16x16x64_i8 v[106:109], v[78:81], v[214:217], v[106:109]
	v_mfma_i32_16x16x64_i8 v[94:97], v[62:65], v[222:225], v[94:97]
	v_mfma_i32_16x16x64_i8 v[90:93], v[78:81], v[222:225], v[90:93]
	v_mfma_i32_16x16x64_i8 v[134:137], v[162:165], v[194:197], v[134:137]
	v_mfma_i32_16x16x64_i8 v[130:133], v[170:173], v[194:197], v[130:133]
	v_mfma_i32_16x16x64_i8 v[118:121], v[162:165], v[202:205], v[118:121]
	v_mfma_i32_16x16x64_i8 v[114:117], v[170:173], v[202:205], v[114:117]
	v_mfma_i32_16x16x64_i8 v[102:105], v[162:165], v[210:213], v[102:105]
	v_mfma_i32_16x16x64_i8 v[98:101], v[170:173], v[210:213], v[98:101]
	v_mfma_i32_16x16x64_i8 v[86:89], v[162:165], v[218:221], v[86:89]
	v_mfma_i32_16x16x64_i8 v[82:85], v[170:173], v[218:221], v[82:85]
	v_mfma_i32_16x16x64_i8 v[134:137], v[166:169], v[198:201], v[134:137]
	v_mfma_i32_16x16x64_i8 v[130:133], v[190:193], v[198:201], v[130:133]
	v_mfma_i32_16x16x64_i8 v[118:121], v[166:169], v[206:209], v[118:121]
	v_mfma_i32_16x16x64_i8 v[114:117], v[190:193], v[206:209], v[114:117]
	v_mfma_i32_16x16x64_i8 v[102:105], v[166:169], v[214:217], v[102:105]
	v_mfma_i32_16x16x64_i8 v[98:101], v[190:193], v[214:217], v[98:101]
	v_mfma_i32_16x16x64_i8 v[86:89], v[166:169], v[222:225], v[86:89]
	v_mfma_i32_16x16x64_i8 v[82:85], v[190:193], v[222:225], v[82:85]
	s_barrier
	s_add_i32 s41, s8, s68
	v_lshl_add_u64 v[174:175], s[34:35], 0, v[148:149]
	s_mov_b32 m0, s41
	ds_read_b128 v[194:197], v189 offset:16384
	ds_read_b128 v[198:201], v189 offset:17408
	ds_read_b128 v[202:205], v189 offset:18432
	ds_read_b128 v[206:209], v189 offset:19456
	ds_read_b128 v[210:213], v189 offset:20480
	ds_read_b128 v[214:217], v189 offset:21504
	ds_read_b128 v[218:221], v189 offset:22528
	ds_read_b128 v[222:225], v189 offset:23552
	global_load_lds_dwordx4 v148, s[34:35]
	s_add_i32 m0, s41, 0x2000
	s_add_u32 vcc_lo, s34, 0x80000
	v_lshl_add_u64 v[226:227], s[34:35], 0, v[152:153]
	s_addc_u32 vcc_hi, s35, 0
	s_add_i32 s41, s9, s68
	global_load_lds_dwordx4 v152, s[34:35]
	v_lshl_add_u64 v[228:229], vcc, 0, v[148:149]
	s_mov_b32 m0, s41
	v_lshl_add_u64 v[230:231], s[36:37], 0, v[150:151]
	global_load_lds_dwordx4 v[228:229], off
	v_lshl_add_u64 v[228:229], vcc, 0, v[152:153]
	s_add_i32 m0, s41, 0x2000
	s_nop 0
	global_load_lds_dwordx4 v[228:229], off
	v_lshl_add_u64 v[228:229], s[36:37], 0, v[146:147]
	s_mov_b32 m0, s31
	s_nop 0
	global_load_lds_dwordx4 v146, s[36:37]
	s_mov_b32 m0, s69
	s_nop 0
	global_load_lds_dwordx4 v150, s[36:37]
	s_waitcnt vmcnt(8)
	s_waitcnt lgkmcnt(0)
	s_barrier
	s_waitcnt lgkmcnt(0)
	v_mfma_i32_16x16x64_i8 v[70:73], v[58:61], v[194:197], v[70:73]
	v_mfma_i32_16x16x64_i8 v[66:69], v[74:77], v[194:197], v[66:69]
	v_mfma_i32_16x16x64_i8 v[46:49], v[58:61], v[202:205], v[46:49]
	v_mfma_i32_16x16x64_i8 v[42:45], v[74:77], v[202:205], v[42:45]
	v_mfma_i32_16x16x64_i8 v[30:33], v[58:61], v[210:213], v[30:33]
	v_mfma_i32_16x16x64_i8 v[26:29], v[74:77], v[210:213], v[26:29]
	v_mfma_i32_16x16x64_i8 v[14:17], v[58:61], v[218:221], v[14:17]
	v_mfma_i32_16x16x64_i8 v[10:13], v[74:77], v[218:221], v[10:13]
	v_mfma_i32_16x16x64_i8 v[70:73], v[62:65], v[198:201], v[70:73]
	v_mfma_i32_16x16x64_i8 v[66:69], v[78:81], v[198:201], v[66:69]
	v_mfma_i32_16x16x64_i8 v[46:49], v[62:65], v[206:209], v[46:49]
	v_mfma_i32_16x16x64_i8 v[42:45], v[78:81], v[206:209], v[42:45]
	v_mfma_i32_16x16x64_i8 v[30:33], v[62:65], v[214:217], v[30:33]
	v_mfma_i32_16x16x64_i8 v[26:29], v[78:81], v[214:217], v[26:29]
	v_mfma_i32_16x16x64_i8 v[14:17], v[62:65], v[222:225], v[14:17]
	v_mfma_i32_16x16x64_i8 v[10:13], v[78:81], v[222:225], v[10:13]
	v_mfma_i32_16x16x64_i8 v[54:57], v[162:165], v[194:197], v[54:57]
	v_mfma_i32_16x16x64_i8 v[50:53], v[170:173], v[194:197], v[50:53]
	v_mfma_i32_16x16x64_i8 v[38:41], v[162:165], v[202:205], v[38:41]
	v_mfma_i32_16x16x64_i8 v[34:37], v[170:173], v[202:205], v[34:37]
	v_mfma_i32_16x16x64_i8 v[22:25], v[162:165], v[210:213], v[22:25]
	v_mfma_i32_16x16x64_i8 v[18:21], v[170:173], v[210:213], v[18:21]
	v_mfma_i32_16x16x64_i8 v[6:9], v[162:165], v[218:221], v[6:9]
	v_mfma_i32_16x16x64_i8 v[2:5], v[170:173], v[218:221], v[2:5]
	v_mfma_i32_16x16x64_i8 v[54:57], v[166:169], v[198:201], v[54:57]
	v_mfma_i32_16x16x64_i8 v[50:53], v[190:193], v[198:201], v[50:53]
	v_mfma_i32_16x16x64_i8 v[38:41], v[166:169], v[206:209], v[38:41]
	v_mfma_i32_16x16x64_i8 v[34:37], v[190:193], v[206:209], v[34:37]
	v_mfma_i32_16x16x64_i8 v[22:25], v[166:169], v[214:217], v[22:25]
	v_mfma_i32_16x16x64_i8 v[18:21], v[190:193], v[214:217], v[18:21]
	v_mfma_i32_16x16x64_i8 v[6:9], v[166:169], v[222:225], v[6:9]
	v_mfma_i32_16x16x64_i8 v[2:5], v[190:193], v[222:225], v[2:5]
	s_barrier
; #define PG8_STAGE(bufoff, gbase, voff) do { _Pragma("unroll") for (int _i = 0; _i < 2; ++_i) \
;         __builtin_amdgcn_global_load_lds((const unsigned*)((const char*)(gbase) + (voff)[_i]), (PG8_LAS unsigned*)(lds + (bufoff) + ldsw + _i * 8192), 16, 0, 0); } while (0)
; #define PG8_LDA(dst, b, h) do { _Pragma("unroll") for (int m = 0; m < 4; ++m) _Pragma("unroll") for (int k = 0; k < 2; ++k) dst[m][k] = *(const PG8_LAS bf16x8*)(lds + PG8_SA(b, h) + aoff + m * 2048 + k * 1024); } while (0)
; #define PG8_LDB(dst, b, h) do { _Pragma("unroll") for (int n = 0; n < 2; ++n) _Pragma("unroll") for (int k = 0; k < 2; ++k) dst[n][k] = *(const PG8_LAS bf16x8*)(lds + PG8_SB(b, h) + boff + n * 2048 + k * 1024); } while (0)
; #define PG8_MMA(ai, bj, At, Bt) do { __builtin_amdgcn_s_setprio(1); _Pragma("unroll") for (int m = 0; m < 4; ++m) _Pragma("unroll") for (int n = 0; n < 2; ++n) _Pragma("unroll") for (int k = 0; k < 2; ++k) \
;         acc[ai][bj][m][n] = mma_<I8>(Bt[n][k], At[m][k], acc[ai][bj][m][n]); __builtin_amdgcn_s_setprio(0); } while (0)
; #define PG8_WAIT_V(n) asm volatile("s_waitcnt vmcnt(" #n ")" ::: "memory")
; #define PG8_WAIT_L(n) asm volatile("s_waitcnt lgkmcnt(" #n ")" ::: "memory")
; #define PG8_BAR __builtin_amdgcn_s_barrier()
; #define PG8_SCHED __builtin_amdgcn_sched_barrier(0)
; template <class Epi, class Sched, bool ALIGN_EPI = false, bool SP2 = false, bool I8 = false>
; __device__ __forceinline__ void gemm_phase(PG8_LAS unsigned char* lds, const Gemm g, const Sched& S, const Epi& E) {
;     ...
;             PG8_LDB(B0, 1, 0); PG8_LDB(B1, 1, 1); PG8_SCHED; PG8_LDA(At, 1, 0); PG8_STAGE(PG8_SA(0, 1), a2 + hstepA, voffA);
;             PG8_WAIT_V(8); PG8_WAIT_L(0); PG8_BAR; PG8_MMA(0, 0, At, B0); PG8_MMA(0, 1, At, B1); PG8_BAR; PG8_SCHED;
;             PG8_LDA(At, 1, 1); PG8_STAGE(PG8_SB(1, 0), b3, voffB); PG8_STAGE(PG8_SB(1, 1), b3 + hstepB, voffB); PG8_STAGE(PG8_SA(1, 0), a3, voffA);
;             PG8_WAIT_V(8); PG8_WAIT_L(0); PG8_BAR; PG8_MMA(1, 0, At, B0); PG8_MMA(1, 1, At, B1); PG8_BAR; PG8_SCHED;
	s_add_i32 s41, 0, 0x18000
	s_add_i32 s95, 0, 0x1c000
	v_add_u32_e32 v78, s41, v181
	v_add_u32_e32 v190, s95, v181
	ds_read_b128 v[58:61], v78
	ds_read_b128 v[62:65], v78 offset:1024
	ds_read_b128 v[74:77], v78 offset:2048
	ds_read_b128 v[78:81], v78 offset:3072
	ds_read_b128 v[162:165], v190
	ds_read_b128 v[166:169], v190 offset:1024
	ds_read_b128 v[170:173], v190 offset:2048
	ds_read_b128 v[190:193], v190 offset:3072
	s_add_u32 s36, s36, 0x80000
	s_addc_u32 s37, s37, 0
	s_mov_b32 m0, s70
	ds_read_b128 v[194:197], v189 offset:32768
	ds_read_b128 v[198:201], v189 offset:33792
	ds_read_b128 v[202:205], v189 offset:34816
	ds_read_b128 v[206:209], v189 offset:35840
	ds_read_b128 v[210:213], v189 offset:36864
	ds_read_b128 v[214:217], v189 offset:37888
	ds_read_b128 v[218:221], v189 offset:38912
	ds_read_b128 v[222:225], v189 offset:39936
	global_load_lds_dwordx4 v146, s[36:37]
	s_mov_b32 m0, s71
	s_nop 0
	global_load_lds_dwordx4 v150, s[36:37]
	s_waitcnt vmcnt(8)
	s_waitcnt lgkmcnt(0)
	s_barrier
	s_waitcnt lgkmcnt(0)
	v_mfma_i32_16x16x64_i8 v[142:145], v[58:61], v[194:197], v[142:145]
	v_mfma_i32_16x16x64_i8 v[138:141], v[74:77], v[194:197], v[138:141]
	v_mfma_i32_16x16x64_i8 v[126:129], v[58:61], v[202:205], v[126:129]
	v_mfma_i32_16x16x64_i8 v[122:125], v[74:77], v[202:205], v[122:125]
	v_mfma_i32_16x16x64_i8 v[110:113], v[58:61], v[210:213], v[110:113]
	v_mfma_i32_16x16x64_i8 v[106:109], v[74:77], v[210:213], v[106:109]
	v_mfma_i32_16x16x64_i8 v[94:97], v[58:61], v[218:221], v[94:97]
	v_mfma_i32_16x16x64_i8 v[90:93], v[74:77], v[218:221], v[90:93]
	v_mfma_i32_16x16x64_i8 v[142:145], v[62:65], v[198:201], v[142:145]
	v_mfma_i32_16x16x64_i8 v[138:141], v[78:81], v[198:201], v[138:141]
	v_mfma_i32_16x16x64_i8 v[126:129], v[62:65], v[206:209], v[126:129]
	v_mfma_i32_16x16x64_i8 v[122:125], v[78:81], v[206:209], v[122:125]
	v_mfma_i32_16x16x64_i8 v[110:113], v[62:65], v[214:217], v[110:113]
	v_mfma_i32_16x16x64_i8 v[106:109], v[78:81], v[214:217], v[106:109]
	v_mfma_i32_16x16x64_i8 v[94:97], v[62:65], v[222:225], v[94:97]
	v_mfma_i32_16x16x64_i8 v[90:93], v[78:81], v[222:225], v[90:93]
	v_mfma_i32_16x16x64_i8 v[134:137], v[162:165], v[194:197], v[134:137]
	v_mfma_i32_16x16x64_i8 v[130:133], v[170:173], v[194:197], v[130:133]
	v_mfma_i32_16x16x64_i8 v[118:121], v[162:165], v[202:205], v[118:121]
	v_mfma_i32_16x16x64_i8 v[114:117], v[170:173], v[202:205], v[114:117]
	v_mfma_i32_16x16x64_i8 v[102:105], v[162:165], v[210:213], v[102:105]
	v_mfma_i32_16x16x64_i8 v[98:101], v[170:173], v[210:213], v[98:101]
	v_mfma_i32_16x16x64_i8 v[86:89], v[162:165], v[218:221], v[86:89]
	v_mfma_i32_16x16x64_i8 v[82:85], v[170:173], v[218:221], v[82:85]
	v_mfma_i32_16x16x64_i8 v[134:137], v[166:169], v[198:201], v[134:137]
	v_mfma_i32_16x16x64_i8 v[130:133], v[190:193], v[198:201], v[130:133]
	v_mfma_i32_16x16x64_i8 v[118:121], v[166:169], v[206:209], v[118:121]
	v_mfma_i32_16x16x64_i8 v[114:117], v[190:193], v[206:209], v[114:117]
	v_mfma_i32_16x16x64_i8 v[102:105], v[166:169], v[214:217], v[102:105]
	v_mfma_i32_16x16x64_i8 v[98:101], v[190:193], v[214:217], v[98:101]
	v_mfma_i32_16x16x64_i8 v[86:89], v[166:169], v[222:225], v[86:89]
	v_mfma_i32_16x16x64_i8 v[82:85], v[190:193], v[222:225], v[82:85]
	s_barrier
	s_add_i32 s36, s41, s68
	v_lshl_add_u64 v[174:175], v[174:175], 0, s[18:19]
	s_mov_b32 m0, s36
	ds_read_b128 v[194:197], v189 offset:49152
	ds_read_b128 v[198:201], v189 offset:50176
	ds_read_b128 v[202:205], v189 offset:51200
	ds_read_b128 v[206:209], v189 offset:52224
	ds_read_b128 v[210:213], v189 offset:53248
	ds_read_b128 v[214:217], v189 offset:54272
	ds_read_b128 v[218:221], v189 offset:55296
	ds_read_b128 v[222:225], v189 offset:56320
	global_load_lds_dwordx4 v[174:175], off
	s_add_i32 m0, s36, 0x2000
	s_add_u32 s34, s34, 0x80080
	v_lshl_add_u64 v[174:175], v[226:227], 0, s[18:19]
	s_addc_u32 s35, s35, 0
	s_add_i32 s36, s95, s68
	global_load_lds_dwordx4 v[174:175], off
	s_mov_b32 m0, s36
	s_nop 0
	global_load_lds_dwordx4 v148, s[34:35]
	s_add_i32 m0, s36, 0x2000
	s_nop 0
	global_load_lds_dwordx4 v152, s[34:35]
	v_lshl_add_u64 v[174:175], v[228:229], 0, s[18:19]
	s_mov_b32 m0, s89
	s_nop 0
	global_load_lds_dwordx4 v[174:175], off
	v_lshl_add_u64 v[174:175], v[230:231], 0, s[18:19]
	s_mov_b32 m0, s92
	s_nop 0
	global_load_lds_dwordx4 v[174:175], off
	s_waitcnt vmcnt(8)
	s_waitcnt lgkmcnt(0)
	s_barrier
	s_waitcnt lgkmcnt(0)
	v_mfma_i32_16x16x64_i8 v[70:73], v[58:61], v[194:197], v[70:73]
	v_mfma_i32_16x16x64_i8 v[66:69], v[74:77], v[194:197], v[66:69]
	v_mfma_i32_16x16x64_i8 v[46:49], v[58:61], v[202:205], v[46:49]
	v_mfma_i32_16x16x64_i8 v[42:45], v[74:77], v[202:205], v[42:45]
	v_mfma_i32_16x16x64_i8 v[30:33], v[58:61], v[210:213], v[30:33]
	v_mfma_i32_16x16x64_i8 v[26:29], v[74:77], v[210:213], v[26:29]
	v_mfma_i32_16x16x64_i8 v[14:17], v[58:61], v[218:221], v[14:17]
	v_mfma_i32_16x16x64_i8 v[10:13], v[74:77], v[218:221], v[10:13]
	v_mfma_i32_16x16x64_i8 v[70:73], v[62:65], v[198:201], v[70:73]
	v_mfma_i32_16x16x64_i8 v[66:69], v[78:81], v[198:201], v[66:69]
	v_mfma_i32_16x16x64_i8 v[46:49], v[62:65], v[206:209], v[46:49]
	v_mfma_i32_16x16x64_i8 v[42:45], v[78:81], v[206:209], v[42:45]
	v_mfma_i32_16x16x64_i8 v[30:33], v[62:65], v[214:217], v[30:33]
	v_mfma_i32_16x16x64_i8 v[26:29], v[78:81], v[214:217], v[26:29]
	v_mfma_i32_16x16x64_i8 v[14:17], v[62:65], v[222:225], v[14:17]
	v_mfma_i32_16x16x64_i8 v[10:13], v[78:81], v[222:225], v[10:13]
	v_mfma_i32_16x16x64_i8 v[54:57], v[162:165], v[194:197], v[54:57]
	v_mfma_i32_16x16x64_i8 v[50:53], v[170:173], v[194:197], v[50:53]
	v_mfma_i32_16x16x64_i8 v[38:41], v[162:165], v[202:205], v[38:41]
	v_mfma_i32_16x16x64_i8 v[34:37], v[170:173], v[202:205], v[34:37]
	v_mfma_i32_16x16x64_i8 v[22:25], v[162:165], v[210:213], v[22:25]
	v_mfma_i32_16x16x64_i8 v[18:21], v[170:173], v[210:213], v[18:21]
	v_mfma_i32_16x16x64_i8 v[6:9], v[162:165], v[218:221], v[6:9]
	v_mfma_i32_16x16x64_i8 v[2:5], v[170:173], v[218:221], v[2:5]
	v_mfma_i32_16x16x64_i8 v[54:57], v[166:169], v[198:201], v[54:57]
	v_mfma_i32_16x16x64_i8 v[50:53], v[190:193], v[198:201], v[50:53]
	v_mfma_i32_16x16x64_i8 v[38:41], v[166:169], v[206:209], v[38:41]
	v_mfma_i32_16x16x64_i8 v[34:37], v[190:193], v[206:209], v[34:37]
	v_mfma_i32_16x16x64_i8 v[22:25], v[166:169], v[214:217], v[22:25]
	v_mfma_i32_16x16x64_i8 v[18:21], v[190:193], v[214:217], v[18:21]
	v_mfma_i32_16x16x64_i8 v[6:9], v[166:169], v[222:225], v[6:9]
	v_mfma_i32_16x16x64_i8 v[2:5], v[190:193], v[222:225], v[2:5]
	s_barrier
	s_add_i32 s40, s40, 2
	s_add_u32 s2, s2, 0x100
	s_addc_u32 s3, s3, 0
	s_add_u32 s38, s38, 0x100
	s_addc_u32 s39, s39, 0
	s_cmp_gt_u32 s40, 29
	s_cbranch_scc0 .LBB0_483
	s_and_b64 vcc, exec, s[20:21]
	s_cbranch_vccz .LBB0_486
	s_barrier

; #define PG8_STAGE(bufoff, gbase, voff) do { _Pragma("unroll") for (int _i = 0; _i < 2; ++_i) \
;         __builtin_amdgcn_global_load_lds((const unsigned*)((const char*)(gbase) + (voff)[_i]), (PG8_LAS unsigned*)(lds + (bufoff) + ldsw + _i * 8192), 16, 0, 0); } while (0)
; #define PG8_LDA(dst, b, h) do { _Pragma("unroll") for (int m = 0; m < 4; ++m) _Pragma("unroll") for (int k = 0; k < 2; ++k) dst[m][k] = *(const PG8_LAS bf16x8*)(lds + PG8_SA(b, h) + aoff + m * 2048 + k * 1024); } while (0)
; #define PG8_LDB(dst, b, h) do { _Pragma("unroll") for (int n = 0; n < 2; ++n) _Pragma("unroll") for (int k = 0; k < 2; ++k) dst[n][k] = *(const PG8_LAS bf16x8*)(lds + PG8_SB(b, h) + boff + n * 2048 + k * 1024); } while (0)
; #define PG8_MMA(ai, bj, At, Bt) do { __builtin_amdgcn_s_setprio(1); _Pragma("unroll") for (int m = 0; m < 4; ++m) _Pragma("unroll") for (int n = 0; n < 2; ++n) _Pragma("unroll") for (int k = 0; k < 2; ++k) \
;         acc[ai][bj][m][n] = mma_<I8>(Bt[n][k], At[m][k], acc[ai][bj][m][n]); __builtin_amdgcn_s_setprio(0); } while (0)
; #define PG8_WAIT_V(n) asm volatile("s_waitcnt vmcnt(" #n ")" ::: "memory")
; #define PG8_WAIT_L(n) asm volatile("s_waitcnt lgkmcnt(" #n ")" ::: "memory")
; #define PG8_BAR __builtin_amdgcn_s_barrier()
; #define PG8_SCHED __builtin_amdgcn_sched_barrier(0)
; template <class Epi, class Sched, bool ALIGN_EPI = false, bool SP2 = false, bool I8 = false>
; __device__ __forceinline__ void gemm_phase(PG8_LAS unsigned char* lds, const Gemm g, const Sched& S, const Epi& E) {
;     ...
;             PG8_LDB(B0, 0, 0); PG8_LDB(B1, 0, 1); PG8_SCHED; PG8_LDA(At, 0, 0); PG8_STAGE(PG8_SA(1, 1), a1 + hstepA, voffA);
;             PG8_WAIT_V(8); PG8_WAIT_L(0); PG8_BAR; PG8_MMA(0, 0, At, B0); PG8_MMA(0, 1, At, B1); PG8_BAR; PG8_SCHED;
;             PG8_LDA(At, 0, 1); PG8_STAGE(PG8_SB(0, 0), b2, voffB); PG8_STAGE(PG8_SB(0, 1), b2 + hstepB, voffB); PG8_STAGE(PG8_SA(0, 0), a2, voffA);
;             PG8_WAIT_V(8); PG8_WAIT_L(0); PG8_BAR; PG8_MMA(1, 0, At, B0); PG8_MMA(1, 1, At, B1); PG8_BAR; PG8_SCHED;
;             PG8_LDB(B0, 1, 0); PG8_LDB(B1, 1, 1); PG8_SCHED; PG8_LDA(At, 1, 0); PG8_STAGE(PG8_SA(0, 1), a2 + hstepA, voffA);
;             PG8_WAIT_V(8); PG8_WAIT_L(0); PG8_BAR; PG8_MMA(0, 0, At, B0); PG8_MMA(0, 1, At, B1); PG8_BAR; PG8_SCHED;
.LBB0_541:
	ds_read_b128 v[154:157], v149
	ds_read_b128 v[158:161], v149 offset:1024
	ds_read_b128 v[162:165], v149 offset:2048
	ds_read_b128 v[166:169], v149 offset:3072
	ds_read_b128 v[170:173], v151
	ds_read_b128 v[174:177], v151 offset:1024
	ds_read_b128 v[178:181], v151 offset:2048
	ds_read_b128 v[188:191], v151 offset:3072
	s_add_u32 s34, s30, 0xfff00080
	s_addc_u32 s35, s31, -1
	s_cmp_eq_u32 s94, 60
	s_cselect_b32 s37, s7, s35
	s_cselect_b32 s36, s25, s34
	s_cselect_b32 s35, s23, s93
	s_cselect_b32 s34, s29, s92
	s_add_i32 m0, s39, 0xc000
	ds_read_b128 v[192:195], v153
	ds_read_b128 v[196:199], v153 offset:1024
	ds_read_b128 v[200:203], v153 offset:2048
	ds_read_b128 v[204:207], v153 offset:3072
	ds_read_b128 v[208:211], v153 offset:4096
	ds_read_b128 v[212:215], v153 offset:5120
	ds_read_b128 v[216:219], v153 offset:6144
	ds_read_b128 v[220:223], v153 offset:7168
	global_load_lds_dwordx4 v138, s[30:31]
	s_add_i32 m0, s39, 0xe000
	s_nop 0
	global_load_lds_dwordx4 v140, s[30:31]
	s_waitcnt vmcnt(8)
	s_waitcnt lgkmcnt(0)
	s_barrier
	s_waitcnt lgkmcnt(0)
	v_mfma_f32_16x16x32_bf16 v[126:129], v[154:157], v[192:195], v[126:129]
	v_mfma_f32_16x16x32_bf16 v[122:125], v[162:165], v[192:195], v[122:125]
	v_mfma_f32_16x16x32_bf16 v[110:113], v[154:157], v[200:203], v[110:113]
	v_mfma_f32_16x16x32_bf16 v[106:109], v[162:165], v[200:203], v[106:109]
	v_mfma_f32_16x16x32_bf16 v[94:97], v[154:157], v[208:211], v[94:97]
	v_mfma_f32_16x16x32_bf16 v[90:93], v[162:165], v[208:211], v[90:93]
	v_mfma_f32_16x16x32_bf16 v[78:81], v[154:157], v[216:219], v[78:81]
	v_mfma_f32_16x16x32_bf16 v[74:77], v[162:165], v[216:219], v[74:77]
	v_mfma_f32_16x16x32_bf16 v[126:129], v[158:161], v[196:199], v[126:129]
	v_mfma_f32_16x16x32_bf16 v[122:125], v[166:169], v[196:199], v[122:125]
	v_mfma_f32_16x16x32_bf16 v[110:113], v[158:161], v[204:207], v[110:113]
	v_mfma_f32_16x16x32_bf16 v[106:109], v[166:169], v[204:207], v[106:109]
	v_mfma_f32_16x16x32_bf16 v[94:97], v[158:161], v[212:215], v[94:97]
	v_mfma_f32_16x16x32_bf16 v[90:93], v[166:169], v[212:215], v[90:93]
	v_mfma_f32_16x16x32_bf16 v[78:81], v[158:161], v[220:223], v[78:81]
	v_mfma_f32_16x16x32_bf16 v[74:77], v[166:169], v[220:223], v[74:77]
	v_mfma_f32_16x16x32_bf16 v[118:121], v[170:173], v[192:195], v[118:121]
	v_mfma_f32_16x16x32_bf16 v[114:117], v[178:181], v[192:195], v[114:117]
	v_mfma_f32_16x16x32_bf16 v[102:105], v[170:173], v[200:203], v[102:105]
	v_mfma_f32_16x16x32_bf16 v[98:101], v[178:181], v[200:203], v[98:101]
	v_mfma_f32_16x16x32_bf16 v[86:89], v[170:173], v[208:211], v[86:89]
	v_mfma_f32_16x16x32_bf16 v[82:85], v[178:181], v[208:211], v[82:85]
	v_mfma_f32_16x16x32_bf16 v[70:73], v[170:173], v[216:219], v[70:73]
	v_mfma_f32_16x16x32_bf16 v[66:69], v[178:181], v[216:219], v[66:69]
	v_mfma_f32_16x16x32_bf16 v[118:121], v[174:177], v[196:199], v[118:121]
	v_mfma_f32_16x16x32_bf16 v[114:117], v[188:191], v[196:199], v[114:117]
	v_mfma_f32_16x16x32_bf16 v[102:105], v[174:177], v[204:207], v[102:105]
	v_mfma_f32_16x16x32_bf16 v[98:101], v[188:191], v[204:207], v[98:101]
	v_mfma_f32_16x16x32_bf16 v[86:89], v[174:177], v[212:215], v[86:89]
	v_mfma_f32_16x16x32_bf16 v[82:85], v[188:191], v[212:215], v[82:85]
	v_mfma_f32_16x16x32_bf16 v[70:73], v[174:177], v[220:223], v[70:73]
	v_mfma_f32_16x16x32_bf16 v[66:69], v[188:191], v[220:223], v[66:69]
	s_barrier
	s_add_i32 s95, s88, s38
	v_lshl_add_u64 v[224:225], s[34:35], 0, v[132:133]
	s_mov_b32 m0, s95
	ds_read_b128 v[192:195], v153 offset:16384
	ds_read_b128 v[196:199], v153 offset:17408
	ds_read_b128 v[200:203], v153 offset:18432
	ds_read_b128 v[204:207], v153 offset:19456
	ds_read_b128 v[208:211], v153 offset:20480
	ds_read_b128 v[212:215], v153 offset:21504
	ds_read_b128 v[216:219], v153 offset:22528
	ds_read_b128 v[220:223], v153 offset:23552
	global_load_lds_dwordx4 v132, s[34:35]
	s_add_i32 m0, s95, 0x2000
	s_add_u32 vcc_lo, s34, 0x100000
	v_lshl_add_u64 v[226:227], s[34:35], 0, v[136:137]
	s_addc_u32 vcc_hi, s35, 0
	s_add_i32 s95, s89, s38
	global_load_lds_dwordx4 v136, s[34:35]
	v_lshl_add_u64 v[228:229], vcc, 0, v[132:133]
	s_mov_b32 m0, s95
	v_lshl_add_u64 v[230:231], s[36:37], 0, v[134:135]
	global_load_lds_dwordx4 v[228:229], off
	v_lshl_add_u64 v[228:229], vcc, 0, v[136:137]
	s_add_i32 m0, s95, 0x2000
	s_nop 0
	global_load_lds_dwordx4 v[228:229], off
	v_lshl_add_u64 v[228:229], s[36:37], 0, v[130:131]
	s_mov_b32 m0, s39
	s_nop 0
	global_load_lds_dwordx4 v130, s[36:37]
	s_mov_b32 m0, s40
	s_nop 0
	global_load_lds_dwordx4 v134, s[36:37]
	s_waitcnt vmcnt(8)
	s_waitcnt lgkmcnt(0)
	s_barrier
; #define PG8_STAGE(bufoff, gbase, voff) do { _Pragma("unroll") for (int _i = 0; _i < 2; ++_i) \
;         __builtin_amdgcn_global_load_lds((const unsigned*)((const char*)(gbase) + (voff)[_i]), (PG8_LAS unsigned*)(lds + (bufoff) + ldsw + _i * 8192), 16, 0, 0); } while (0)
; #define PG8_LDA(dst, b, h) do { _Pragma("unroll") for (int m = 0; m < 4; ++m) _Pragma("unroll") for (int k = 0; k < 2; ++k) dst[m][k] = *(const PG8_LAS bf16x8*)(lds + PG8_SA(b, h) + aoff + m * 2048 + k * 1024); } while (0)
; #define PG8_LDB(dst, b, h) do { _Pragma("unroll") for (int n = 0; n < 2; ++n) _Pragma("unroll") for (int k = 0; k < 2; ++k) dst[n][k] = *(const PG8_LAS bf16x8*)(lds + PG8_SB(b, h) + boff + n * 2048 + k * 1024); } while (0)
; #define PG8_MMA(ai, bj, At, Bt) do { __builtin_amdgcn_s_setprio(1); _Pragma("unroll") for (int m = 0; m < 4; ++m) _Pragma("unroll") for (int n = 0; n < 2; ++n) _Pragma("unroll") for (int k = 0; k < 2; ++k) \
;         acc[ai][bj][m][n] = mma_<I8>(Bt[n][k], At[m][k], acc[ai][bj][m][n]); __builtin_amdgcn_s_setprio(0); } while (0)
; #define PG8_WAIT_V(n) asm volatile("s_waitcnt vmcnt(" #n ")" ::: "memory")
; #define PG8_WAIT_L(n) asm volatile("s_waitcnt lgkmcnt(" #n ")" ::: "memory")
; #define PG8_BAR __builtin_amdgcn_s_barrier()
; #define PG8_SCHED __builtin_amdgcn_sched_barrier(0)
; template <class Epi, class Sched, bool ALIGN_EPI = false, bool SP2 = false, bool I8 = false>
; __device__ __forceinline__ void gemm_phase(PG8_LAS unsigned char* lds, const Gemm g, const Sched& S, const Epi& E) {
;     ...
;             PG8_WAIT_V(8); PG8_WAIT_L(0); PG8_BAR; PG8_MMA(1, 0, At, B0); PG8_MMA(1, 1, At, B1); PG8_BAR; PG8_SCHED;
;             PG8_LDB(B0, 1, 0); PG8_LDB(B1, 1, 1); PG8_SCHED; PG8_LDA(At, 1, 0); PG8_STAGE(PG8_SA(0, 1), a2 + hstepA, voffA);
;             PG8_WAIT_V(8); PG8_WAIT_L(0); PG8_BAR; PG8_MMA(0, 0, At, B0); PG8_MMA(0, 1, At, B1); PG8_BAR; PG8_SCHED;
	s_waitcnt lgkmcnt(0)
	v_mfma_f32_16x16x32_bf16 v[62:65], v[154:157], v[192:195], v[62:65]
	v_mfma_f32_16x16x32_bf16 v[58:61], v[162:165], v[192:195], v[58:61]
	v_mfma_f32_16x16x32_bf16 v[46:49], v[154:157], v[200:203], v[46:49]
	v_mfma_f32_16x16x32_bf16 v[42:45], v[162:165], v[200:203], v[42:45]
	v_mfma_f32_16x16x32_bf16 v[30:33], v[154:157], v[208:211], v[30:33]
	v_mfma_f32_16x16x32_bf16 v[26:29], v[162:165], v[208:211], v[26:29]
	v_mfma_f32_16x16x32_bf16 v[14:17], v[154:157], v[216:219], v[14:17]
	v_mfma_f32_16x16x32_bf16 v[10:13], v[162:165], v[216:219], v[10:13]
	v_mfma_f32_16x16x32_bf16 v[62:65], v[158:161], v[196:199], v[62:65]
	v_mfma_f32_16x16x32_bf16 v[58:61], v[166:169], v[196:199], v[58:61]
	v_mfma_f32_16x16x32_bf16 v[46:49], v[158:161], v[204:207], v[46:49]
	v_mfma_f32_16x16x32_bf16 v[42:45], v[166:169], v[204:207], v[42:45]
	v_mfma_f32_16x16x32_bf16 v[30:33], v[158:161], v[212:215], v[30:33]
	v_mfma_f32_16x16x32_bf16 v[26:29], v[166:169], v[212:215], v[26:29]
	v_mfma_f32_16x16x32_bf16 v[14:17], v[158:161], v[220:223], v[14:17]
	v_mfma_f32_16x16x32_bf16 v[10:13], v[166:169], v[220:223], v[10:13]
	v_mfma_f32_16x16x32_bf16 v[54:57], v[170:173], v[192:195], v[54:57]
	v_mfma_f32_16x16x32_bf16 v[50:53], v[178:181], v[192:195], v[50:53]
	v_mfma_f32_16x16x32_bf16 v[38:41], v[170:173], v[200:203], v[38:41]
	v_mfma_f32_16x16x32_bf16 v[34:37], v[178:181], v[200:203], v[34:37]
	v_mfma_f32_16x16x32_bf16 v[22:25], v[170:173], v[208:211], v[22:25]
	v_mfma_f32_16x16x32_bf16 v[18:21], v[178:181], v[208:211], v[18:21]
	v_mfma_f32_16x16x32_bf16 v[6:9], v[170:173], v[216:219], v[6:9]
	v_mfma_f32_16x16x32_bf16 v[2:5], v[178:181], v[216:219], v[2:5]
	v_mfma_f32_16x16x32_bf16 v[54:57], v[174:177], v[196:199], v[54:57]
	v_mfma_f32_16x16x32_bf16 v[50:53], v[188:191], v[196:199], v[50:53]
	v_mfma_f32_16x16x32_bf16 v[38:41], v[174:177], v[204:207], v[38:41]
	v_mfma_f32_16x16x32_bf16 v[34:37], v[188:191], v[204:207], v[34:37]
	v_mfma_f32_16x16x32_bf16 v[22:25], v[174:177], v[212:215], v[22:25]
	v_mfma_f32_16x16x32_bf16 v[18:21], v[188:191], v[212:215], v[18:21]
	v_mfma_f32_16x16x32_bf16 v[6:9], v[174:177], v[220:223], v[6:9]
	v_mfma_f32_16x16x32_bf16 v[2:5], v[188:191], v[220:223], v[2:5]
	s_barrier
	s_add_i32 s95, 0, 0x18000
	s_add_i32 vcc_lo, 0, 0x1c000
	v_add_u32_e32 v166, s95, v147
	v_add_u32_e32 v187, vcc_lo, v147
	ds_read_b128 v[154:157], v166
	ds_read_b128 v[158:161], v166 offset:1024
	ds_read_b128 v[162:165], v166 offset:2048
	ds_read_b128 v[166:169], v166 offset:3072
	ds_read_b128 v[170:173], v187
	ds_read_b128 v[174:177], v187 offset:1024
	ds_read_b128 v[178:181], v187 offset:2048
	ds_read_b128 v[188:191], v187 offset:3072
	s_add_u32 s36, s36, 0x100000
	s_addc_u32 s37, s37, 0
	s_mov_b32 m0, s41
	ds_read_b128 v[192:195], v153 offset:32768
	ds_read_b128 v[196:199], v153 offset:33792
	ds_read_b128 v[200:203], v153 offset:34816
	ds_read_b128 v[204:207], v153 offset:35840
	ds_read_b128 v[208:211], v153 offset:36864
	ds_read_b128 v[212:215], v153 offset:37888
	ds_read_b128 v[216:219], v153 offset:38912
	ds_read_b128 v[220:223], v153 offset:39936
	global_load_lds_dwordx4 v130, s[36:37]
	s_mov_b32 m0, s46
	s_nop 0
	global_load_lds_dwordx4 v134, s[36:37]
	s_waitcnt vmcnt(8)
	s_waitcnt lgkmcnt(0)
	s_barrier
	s_waitcnt lgkmcnt(0)
	v_mfma_f32_16x16x32_bf16 v[126:129], v[154:157], v[192:195], v[126:129]
	v_mfma_f32_16x16x32_bf16 v[122:125], v[162:165], v[192:195], v[122:125]
	v_mfma_f32_16x16x32_bf16 v[110:113], v[154:157], v[200:203], v[110:113]
	v_mfma_f32_16x16x32_bf16 v[106:109], v[162:165], v[200:203], v[106:109]
	v_mfma_f32_16x16x32_bf16 v[94:97], v[154:157], v[208:211], v[94:97]
	v_mfma_f32_16x16x32_bf16 v[90:93], v[162:165], v[208:211], v[90:93]
	v_mfma_f32_16x16x32_bf16 v[78:81], v[154:157], v[216:219], v[78:81]
	v_mfma_f32_16x16x32_bf16 v[74:77], v[162:165], v[216:219], v[74:77]
	v_mfma_f32_16x16x32_bf16 v[126:129], v[158:161], v[196:199], v[126:129]
	v_mfma_f32_16x16x32_bf16 v[122:125], v[166:169], v[196:199], v[122:125]
	v_mfma_f32_16x16x32_bf16 v[110:113], v[158:161], v[204:207], v[110:113]
	v_mfma_f32_16x16x32_bf16 v[106:109], v[166:169], v[204:207], v[106:109]
	v_mfma_f32_16x16x32_bf16 v[94:97], v[158:161], v[212:215], v[94:97]
	v_mfma_f32_16x16x32_bf16 v[90:93], v[166:169], v[212:215], v[90:93]
	v_mfma_f32_16x16x32_bf16 v[78:81], v[158:161], v[220:223], v[78:81]
	v_mfma_f32_16x16x32_bf16 v[74:77], v[166:169], v[220:223], v[74:77]
	v_mfma_f32_16x16x32_bf16 v[118:121], v[170:173], v[192:195], v[118:121]
	v_mfma_f32_16x16x32_bf16 v[114:117], v[178:181], v[192:195], v[114:117]
	v_mfma_f32_16x16x32_bf16 v[102:105], v[170:173], v[200:203], v[102:105]
	v_mfma_f32_16x16x32_bf16 v[98:101], v[178:181], v[200:203], v[98:101]
	v_mfma_f32_16x16x32_bf16 v[86:89], v[170:173], v[208:211], v[86:89]
	v_mfma_f32_16x16x32_bf16 v[82:85], v[178:181], v[208:211], v[82:85]
	v_mfma_f32_16x16x32_bf16 v[70:73], v[170:173], v[216:219], v[70:73]
	v_mfma_f32_16x16x32_bf16 v[66:69], v[178:181], v[216:219], v[66:69]
	v_mfma_f32_16x16x32_bf16 v[118:121], v[174:177], v[196:199], v[118:121]
	v_mfma_f32_16x16x32_bf16 v[114:117], v[188:191], v[196:199], v[114:117]
	v_mfma_f32_16x16x32_bf16 v[102:105], v[174:177], v[204:207], v[102:105]
	v_mfma_f32_16x16x32_bf16 v[98:101], v[188:191], v[204:207], v[98:101]
	v_mfma_f32_16x16x32_bf16 v[86:89], v[174:177], v[212:215], v[86:89]
	v_mfma_f32_16x16x32_bf16 v[82:85], v[188:191], v[212:215], v[82:85]
	v_mfma_f32_16x16x32_bf16 v[70:73], v[174:177], v[220:223], v[70:73]
	v_mfma_f32_16x16x32_bf16 v[66:69], v[188:191], v[220:223], v[66:69]
	s_barrier
; #define PG8_STAGE(bufoff, gbase, voff) do { _Pragma("unroll") for (int _i = 0; _i < 2; ++_i) \
;         __builtin_amdgcn_global_load_lds((const unsigned*)((const char*)(gbase) + (voff)[_i]), (PG8_LAS unsigned*)(lds + (bufoff) + ldsw + _i * 8192), 16, 0, 0); } while (0)
; #define PG8_LDA(dst, b, h) do { _Pragma("unroll") for (int m = 0; m < 4; ++m) _Pragma("unroll") for (int k = 0; k < 2; ++k) dst[m][k] = *(const PG8_LAS bf16x8*)(lds + PG8_SA(b, h) + aoff + m * 2048 + k * 1024); } while (0)
; #define PG8_MMA(ai, bj, At, Bt) do { __builtin_amdgcn_s_setprio(1); _Pragma("unroll") for (int m = 0; m < 4; ++m) _Pragma("unroll") for (int n = 0; n < 2; ++n) _Pragma("unroll") for (int k = 0; k < 2; ++k) \
;         acc[ai][bj][m][n] = mma_<I8>(Bt[n][k], At[m][k], acc[ai][bj][m][n]); __builtin_amdgcn_s_setprio(0); } while (0)
; #define PG8_WAIT_V(n) asm volatile("s_waitcnt vmcnt(" #n ")" ::: "memory")
; #define PG8_WAIT_L(n) asm volatile("s_waitcnt lgkmcnt(" #n ")" ::: "memory")
; #define PG8_BAR __builtin_amdgcn_s_barrier()
; #define PG8_SCHED __builtin_amdgcn_sched_barrier(0)
; template <class Epi, class Sched, bool ALIGN_EPI = false, bool SP2 = false, bool I8 = false>
; __device__ __forceinline__ void gemm_phase(PG8_LAS unsigned char* lds, const Gemm g, const Sched& S, const Epi& E) {
;     ...
;             PG8_WAIT_V(8); PG8_WAIT_L(0); PG8_BAR; PG8_MMA(0, 0, At, B0); PG8_MMA(0, 1, At, B1); PG8_BAR; PG8_SCHED;
;             PG8_LDA(At, 1, 1); PG8_STAGE(PG8_SB(1, 0), b3, voffB); PG8_STAGE(PG8_SB(1, 1), b3 + hstepB, voffB); PG8_STAGE(PG8_SA(1, 0), a3, voffA);
;             PG8_WAIT_V(8); PG8_WAIT_L(0); PG8_BAR; PG8_MMA(1, 0, At, B0); PG8_MMA(1, 1, At, B1); PG8_BAR; PG8_SCHED;
	s_add_i32 s36, s95, s38
	v_lshl_add_u64 v[224:225], v[224:225], 0, s[18:19]
	s_mov_b32 m0, s36
	ds_read_b128 v[192:195], v153 offset:49152
	ds_read_b128 v[196:199], v153 offset:50176
	ds_read_b128 v[200:203], v153 offset:51200
	ds_read_b128 v[204:207], v153 offset:52224
	ds_read_b128 v[208:211], v153 offset:53248
	ds_read_b128 v[212:215], v153 offset:54272
	ds_read_b128 v[216:219], v153 offset:55296
	ds_read_b128 v[220:223], v153 offset:56320
	global_load_lds_dwordx4 v[224:225], off
	s_add_i32 m0, s36, 0x2000
	s_add_u32 s34, s34, 0x100080
	v_lshl_add_u64 v[224:225], v[226:227], 0, s[18:19]
	s_addc_u32 s35, s35, 0
	s_add_i32 s36, vcc_lo, s38
	global_load_lds_dwordx4 v[224:225], off
	s_mov_b32 m0, s36
	s_nop 0
	global_load_lds_dwordx4 v132, s[34:35]
	s_add_i32 m0, s36, 0x2000
	s_nop 0
	global_load_lds_dwordx4 v136, s[34:35]
	v_lshl_add_u64 v[224:225], v[228:229], 0, s[18:19]
	s_mov_b32 m0, s68
	s_nop 0
	global_load_lds_dwordx4 v[224:225], off
	v_lshl_add_u64 v[224:225], v[230:231], 0, s[18:19]
	s_mov_b32 m0, s69
	s_nop 0
	global_load_lds_dwordx4 v[224:225], off
	s_waitcnt vmcnt(8)
	s_waitcnt lgkmcnt(0)
	s_barrier
	s_waitcnt lgkmcnt(0)
	v_mfma_f32_16x16x32_bf16 v[62:65], v[154:157], v[192:195], v[62:65]
	v_mfma_f32_16x16x32_bf16 v[58:61], v[162:165], v[192:195], v[58:61]
	v_mfma_f32_16x16x32_bf16 v[46:49], v[154:157], v[200:203], v[46:49]
	v_mfma_f32_16x16x32_bf16 v[42:45], v[162:165], v[200:203], v[42:45]
	v_mfma_f32_16x16x32_bf16 v[30:33], v[154:157], v[208:211], v[30:33]
	v_mfma_f32_16x16x32_bf16 v[26:29], v[162:165], v[208:211], v[26:29]
	v_mfma_f32_16x16x32_bf16 v[14:17], v[154:157], v[216:219], v[14:17]
	v_mfma_f32_16x16x32_bf16 v[10:13], v[162:165], v[216:219], v[10:13]
	v_mfma_f32_16x16x32_bf16 v[62:65], v[158:161], v[196:199], v[62:65]
	v_mfma_f32_16x16x32_bf16 v[58:61], v[166:169], v[196:199], v[58:61]
	v_mfma_f32_16x16x32_bf16 v[46:49], v[158:161], v[204:207], v[46:49]
	v_mfma_f32_16x16x32_bf16 v[42:45], v[166:169], v[204:207], v[42:45]
	v_mfma_f32_16x16x32_bf16 v[30:33], v[158:161], v[212:215], v[30:33]
	v_mfma_f32_16x16x32_bf16 v[26:29], v[166:169], v[212:215], v[26:29]
	v_mfma_f32_16x16x32_bf16 v[14:17], v[158:161], v[220:223], v[14:17]
	v_mfma_f32_16x16x32_bf16 v[10:13], v[166:169], v[220:223], v[10:13]
	v_mfma_f32_16x16x32_bf16 v[54:57], v[170:173], v[192:195], v[54:57]
	v_mfma_f32_16x16x32_bf16 v[50:53], v[178:181], v[192:195], v[50:53]
	v_mfma_f32_16x16x32_bf16 v[38:41], v[170:173], v[200:203], v[38:41]
	v_mfma_f32_16x16x32_bf16 v[34:37], v[178:181], v[200:203], v[34:37]
	v_mfma_f32_16x16x32_bf16 v[22:25], v[170:173], v[208:211], v[22:25]
	v_mfma_f32_16x16x32_bf16 v[18:21], v[178:181], v[208:211], v[18:21]
	v_mfma_f32_16x16x32_bf16 v[6:9], v[170:173], v[216:219], v[6:9]
	v_mfma_f32_16x16x32_bf16 v[2:5], v[178:181], v[216:219], v[2:5]
	v_mfma_f32_16x16x32_bf16 v[54:57], v[174:177], v[196:199], v[54:57]
	v_mfma_f32_16x16x32_bf16 v[50:53], v[188:191], v[196:199], v[50:53]
	v_mfma_f32_16x16x32_bf16 v[38:41], v[174:177], v[204:207], v[38:41]
	v_mfma_f32_16x16x32_bf16 v[34:37], v[188:191], v[204:207], v[34:37]
	v_mfma_f32_16x16x32_bf16 v[22:25], v[174:177], v[212:215], v[22:25]
	v_mfma_f32_16x16x32_bf16 v[18:21], v[188:191], v[212:215], v[18:21]
	v_mfma_f32_16x16x32_bf16 v[6:9], v[174:177], v[220:223], v[6:9]
	v_mfma_f32_16x16x32_bf16 v[2:5], v[188:191], v[220:223], v[2:5]
	s_barrier
	s_add_i32 s94, s94, 2
	s_add_u32 s30, s30, 0x100
	s_addc_u32 s31, s31, 0
	s_add_u32 s92, s92, 0x100
	s_addc_u32 s93, s93, 0
	s_cmp_gt_u32 s94, 61
	s_cbranch_scc0 .LBB0_541
	s_and_b64 vcc, exec, s[20:21]
	s_cbranch_vccz .LBB0_544
	s_barrier

; #define PG8_STAGE(bufoff, gbase, voff) do { _Pragma("unroll") for (int _i = 0; _i < 2; ++_i) \
;         __builtin_amdgcn_global_load_lds((const unsigned*)((const char*)(gbase) + (voff)[_i]), (PG8_LAS unsigned*)(lds + (bufoff) + ldsw + _i * 8192), 16, 0, 0); } while (0)
; #define PG8_LDA(dst, b, h) do { _Pragma("unroll") for (int m = 0; m < 4; ++m) _Pragma("unroll") for (int k = 0; k < 2; ++k) dst[m][k] = *(const PG8_LAS bf16x8*)(lds + PG8_SA(b, h) + aoff + m * 2048 + k * 1024); } while (0)
; #define PG8_LDB(dst, b, h) do { _Pragma("unroll") for (int n = 0; n < 2; ++n) _Pragma("unroll") for (int k = 0; k < 2; ++k) dst[n][k] = *(const PG8_LAS bf16x8*)(lds + PG8_SB(b, h) + boff + n * 2048 + k * 1024); } while (0)
; #define PG8_MMA(ai, bj, At, Bt) do { __builtin_amdgcn_s_setprio(1); _Pragma("unroll") for (int m = 0; m < 4; ++m) _Pragma("unroll") for (int n = 0; n < 2; ++n) _Pragma("unroll") for (int k = 0; k < 2; ++k) \
;         acc[ai][bj][m][n] = mma_<I8>(Bt[n][k], At[m][k], acc[ai][bj][m][n]); __builtin_amdgcn_s_setprio(0); } while (0)
; #define PG8_WAIT_V(n) asm volatile("s_waitcnt vmcnt(" #n ")" ::: "memory")
; #define PG8_WAIT_L(n) asm volatile("s_waitcnt lgkmcnt(" #n ")" ::: "memory")
; #define PG8_BAR __builtin_amdgcn_s_barrier()
; #define PG8_SCHED __builtin_amdgcn_sched_barrier(0)
; template <class Epi, class Sched, bool ALIGN_EPI = false, bool SP2 = false, bool I8 = false>
; __device__ __forceinline__ void gemm_phase(PG8_LAS unsigned char* lds, const Gemm g, const Sched& S, const Epi& E) {
;     ...
;             PG8_LDB(B0, 0, 0); PG8_LDB(B1, 0, 1); PG8_SCHED; PG8_LDA(At, 0, 0); PG8_STAGE(PG8_SA(1, 1), a1 + hstepA, voffA);
;             PG8_WAIT_V(8); PG8_WAIT_L(0); PG8_BAR; PG8_MMA(0, 0, At, B0); PG8_MMA(0, 1, At, B1); PG8_BAR; PG8_SCHED;
;             PG8_LDA(At, 0, 1); PG8_STAGE(PG8_SB(0, 0), b2, voffB); PG8_STAGE(PG8_SB(0, 1), b2 + hstepB, voffB); PG8_STAGE(PG8_SA(0, 0), a2, voffA);
;             PG8_WAIT_V(8); PG8_WAIT_L(0); PG8_BAR; PG8_MMA(1, 0, At, B0); PG8_MMA(1, 1, At, B1); PG8_BAR; PG8_SCHED;
;             PG8_LDB(B0, 1, 0); PG8_LDB(B1, 1, 1); PG8_SCHED; PG8_LDA(At, 1, 0); PG8_STAGE(PG8_SA(0, 1), a2 + hstepA, voffA);
;             PG8_WAIT_V(8); PG8_WAIT_L(0); PG8_BAR; PG8_MMA(0, 0, At, B0); PG8_MMA(0, 1, At, B1); PG8_BAR; PG8_SCHED;
.LBB0_607:
	ds_read_b128 v[58:61], v177
	ds_read_b128 v[62:65], v177 offset:1024
	ds_read_b128 v[74:77], v177 offset:2048
	ds_read_b128 v[78:81], v177 offset:3072
	ds_read_b128 v[162:165], v178
	ds_read_b128 v[166:169], v178 offset:1024
	ds_read_b128 v[170:173], v178 offset:2048
	ds_read_b128 v[180:183], v178 offset:3072
	s_add_u32 s34, s2, 0xfff80080
	s_addc_u32 s35, s3, -1
	s_cmp_eq_u32 s39, 28
	s_cselect_b32 s37, s7, s35
	s_cselect_b32 s36, s9, s34
	s_cselect_b32 s35, s23, s38
	s_cselect_b32 s34, s25, s31
	s_add_i32 m0, s69, 0xc000
	ds_read_b128 v[184:187], v179
	ds_read_b128 v[188:191], v179 offset:1024
	ds_read_b128 v[192:195], v179 offset:2048
	ds_read_b128 v[196:199], v179 offset:3072
	ds_read_b128 v[200:203], v179 offset:4096
	ds_read_b128 v[204:207], v179 offset:5120
	ds_read_b128 v[208:211], v179 offset:6144
	ds_read_b128 v[212:215], v179 offset:7168
	global_load_lds_dwordx4 v154, s[2:3]
	s_add_i32 m0, s69, 0xe000
	s_nop 0
	global_load_lds_dwordx4 v156, s[2:3]
	s_waitcnt vmcnt(8)
	s_waitcnt lgkmcnt(0)
	s_barrier
	s_waitcnt lgkmcnt(0)
	v_mfma_i32_16x16x64_i8 v[142:145], v[58:61], v[184:187], v[142:145]
	v_mfma_i32_16x16x64_i8 v[138:141], v[74:77], v[184:187], v[138:141]
	v_mfma_i32_16x16x64_i8 v[126:129], v[58:61], v[192:195], v[126:129]
	v_mfma_i32_16x16x64_i8 v[122:125], v[74:77], v[192:195], v[122:125]
	v_mfma_i32_16x16x64_i8 v[110:113], v[58:61], v[200:203], v[110:113]
	v_mfma_i32_16x16x64_i8 v[106:109], v[74:77], v[200:203], v[106:109]
	v_mfma_i32_16x16x64_i8 v[94:97], v[58:61], v[208:211], v[94:97]
	v_mfma_i32_16x16x64_i8 v[90:93], v[74:77], v[208:211], v[90:93]
	v_mfma_i32_16x16x64_i8 v[142:145], v[62:65], v[188:191], v[142:145]
	v_mfma_i32_16x16x64_i8 v[138:141], v[78:81], v[188:191], v[138:141]
	v_mfma_i32_16x16x64_i8 v[126:129], v[62:65], v[196:199], v[126:129]
	v_mfma_i32_16x16x64_i8 v[122:125], v[78:81], v[196:199], v[122:125]
	v_mfma_i32_16x16x64_i8 v[110:113], v[62:65], v[204:207], v[110:113]
	v_mfma_i32_16x16x64_i8 v[106:109], v[78:81], v[204:207], v[106:109]
	v_mfma_i32_16x16x64_i8 v[94:97], v[62:65], v[212:215], v[94:97]
	v_mfma_i32_16x16x64_i8 v[90:93], v[78:81], v[212:215], v[90:93]
	v_mfma_i32_16x16x64_i8 v[134:137], v[162:165], v[184:187], v[134:137]
	v_mfma_i32_16x16x64_i8 v[130:133], v[170:173], v[184:187], v[130:133]
	v_mfma_i32_16x16x64_i8 v[118:121], v[162:165], v[192:195], v[118:121]
	v_mfma_i32_16x16x64_i8 v[114:117], v[170:173], v[192:195], v[114:117]
	v_mfma_i32_16x16x64_i8 v[102:105], v[162:165], v[200:203], v[102:105]
	v_mfma_i32_16x16x64_i8 v[98:101], v[170:173], v[200:203], v[98:101]
	v_mfma_i32_16x16x64_i8 v[86:89], v[162:165], v[208:211], v[86:89]
	v_mfma_i32_16x16x64_i8 v[82:85], v[170:173], v[208:211], v[82:85]
	v_mfma_i32_16x16x64_i8 v[134:137], v[166:169], v[188:191], v[134:137]
	v_mfma_i32_16x16x64_i8 v[130:133], v[180:183], v[188:191], v[130:133]
	v_mfma_i32_16x16x64_i8 v[118:121], v[166:169], v[196:199], v[118:121]
	v_mfma_i32_16x16x64_i8 v[114:117], v[180:183], v[196:199], v[114:117]
	v_mfma_i32_16x16x64_i8 v[102:105], v[166:169], v[204:207], v[102:105]
	v_mfma_i32_16x16x64_i8 v[98:101], v[180:183], v[204:207], v[98:101]
	v_mfma_i32_16x16x64_i8 v[86:89], v[166:169], v[212:215], v[86:89]
	v_mfma_i32_16x16x64_i8 v[82:85], v[180:183], v[212:215], v[82:85]
	s_barrier
	s_add_i32 s40, s33, s68
	v_lshl_add_u64 v[174:175], s[34:35], 0, v[148:149]
	s_mov_b32 m0, s40
	ds_read_b128 v[184:187], v179 offset:16384
	ds_read_b128 v[188:191], v179 offset:17408
	ds_read_b128 v[192:195], v179 offset:18432
	ds_read_b128 v[196:199], v179 offset:19456
	ds_read_b128 v[200:203], v179 offset:20480
	ds_read_b128 v[204:207], v179 offset:21504
	ds_read_b128 v[208:211], v179 offset:22528
	ds_read_b128 v[212:215], v179 offset:23552
	global_load_lds_dwordx4 v148, s[34:35]
	s_add_i32 m0, s40, 0x2000
	s_add_u32 s40, s34, 0x80000
	v_lshl_add_u64 v[216:217], s[34:35], 0, v[152:153]
	s_addc_u32 s41, s35, 0
	s_add_i32 vcc_lo, s8, s68
	global_load_lds_dwordx4 v152, s[34:35]
	s_mov_b32 m0, vcc_lo
	v_lshl_add_u64 v[220:221], s[36:37], 0, v[150:151]
	global_load_lds_dwordx4 v148, s[40:41]
	s_add_i32 m0, vcc_lo, 0x2000
	s_nop 0
	global_load_lds_dwordx4 v152, s[40:41]
	v_lshl_add_u64 v[218:219], s[36:37], 0, v[146:147]
	s_mov_b32 m0, s69
	s_nop 0
	global_load_lds_dwordx4 v146, s[36:37]
	s_mov_b32 m0, s70
	s_nop 0
	global_load_lds_dwordx4 v150, s[36:37]
	s_waitcnt vmcnt(8)
	s_waitcnt lgkmcnt(0)
	s_barrier
	s_waitcnt lgkmcnt(0)
	v_mfma_i32_16x16x64_i8 v[70:73], v[58:61], v[184:187], v[70:73]
	v_mfma_i32_16x16x64_i8 v[66:69], v[74:77], v[184:187], v[66:69]
	v_mfma_i32_16x16x64_i8 v[46:49], v[58:61], v[192:195], v[46:49]
	v_mfma_i32_16x16x64_i8 v[42:45], v[74:77], v[192:195], v[42:45]
	v_mfma_i32_16x16x64_i8 v[30:33], v[58:61], v[200:203], v[30:33]
	v_mfma_i32_16x16x64_i8 v[26:29], v[74:77], v[200:203], v[26:29]
	v_mfma_i32_16x16x64_i8 v[14:17], v[58:61], v[208:211], v[14:17]
	v_mfma_i32_16x16x64_i8 v[10:13], v[74:77], v[208:211], v[10:13]
	v_mfma_i32_16x16x64_i8 v[70:73], v[62:65], v[188:191], v[70:73]
	v_mfma_i32_16x16x64_i8 v[66:69], v[78:81], v[188:191], v[66:69]
	v_mfma_i32_16x16x64_i8 v[46:49], v[62:65], v[196:199], v[46:49]
	v_mfma_i32_16x16x64_i8 v[42:45], v[78:81], v[196:199], v[42:45]
	v_mfma_i32_16x16x64_i8 v[30:33], v[62:65], v[204:207], v[30:33]
	v_mfma_i32_16x16x64_i8 v[26:29], v[78:81], v[204:207], v[26:29]
	v_mfma_i32_16x16x64_i8 v[14:17], v[62:65], v[212:215], v[14:17]
	v_mfma_i32_16x16x64_i8 v[10:13], v[78:81], v[212:215], v[10:13]
	v_mfma_i32_16x16x64_i8 v[54:57], v[162:165], v[184:187], v[54:57]
	v_mfma_i32_16x16x64_i8 v[50:53], v[170:173], v[184:187], v[50:53]
	v_mfma_i32_16x16x64_i8 v[38:41], v[162:165], v[192:195], v[38:41]
	v_mfma_i32_16x16x64_i8 v[34:37], v[170:173], v[192:195], v[34:37]
	v_mfma_i32_16x16x64_i8 v[22:25], v[162:165], v[200:203], v[22:25]
	v_mfma_i32_16x16x64_i8 v[18:21], v[170:173], v[200:203], v[18:21]
	v_mfma_i32_16x16x64_i8 v[6:9], v[162:165], v[208:211], v[6:9]
	v_mfma_i32_16x16x64_i8 v[2:5], v[170:173], v[208:211], v[2:5]
	v_mfma_i32_16x16x64_i8 v[54:57], v[166:169], v[188:191], v[54:57]
	v_mfma_i32_16x16x64_i8 v[50:53], v[180:183], v[188:191], v[50:53]
	v_mfma_i32_16x16x64_i8 v[38:41], v[166:169], v[196:199], v[38:41]
	v_mfma_i32_16x16x64_i8 v[34:37], v[180:183], v[196:199], v[34:37]
	v_mfma_i32_16x16x64_i8 v[22:25], v[166:169], v[204:207], v[22:25]
	v_mfma_i32_16x16x64_i8 v[18:21], v[180:183], v[204:207], v[18:21]
	v_mfma_i32_16x16x64_i8 v[6:9], v[166:169], v[212:215], v[6:9]
	v_mfma_i32_16x16x64_i8 v[2:5], v[180:183], v[212:215], v[2:5]
	s_barrier
; #define PG8_STAGE(bufoff, gbase, voff) do { _Pragma("unroll") for (int _i = 0; _i < 2; ++_i) \
;         __builtin_amdgcn_global_load_lds((const unsigned*)((const char*)(gbase) + (voff)[_i]), (PG8_LAS unsigned*)(lds + (bufoff) + ldsw + _i * 8192), 16, 0, 0); } while (0)
; #define PG8_LDA(dst, b, h) do { _Pragma("unroll") for (int m = 0; m < 4; ++m) _Pragma("unroll") for (int k = 0; k < 2; ++k) dst[m][k] = *(const PG8_LAS bf16x8*)(lds + PG8_SA(b, h) + aoff + m * 2048 + k * 1024); } while (0)
; #define PG8_LDB(dst, b, h) do { _Pragma("unroll") for (int n = 0; n < 2; ++n) _Pragma("unroll") for (int k = 0; k < 2; ++k) dst[n][k] = *(const PG8_LAS bf16x8*)(lds + PG8_SB(b, h) + boff + n * 2048 + k * 1024); } while (0)
; #define PG8_MMA(ai, bj, At, Bt) do { __builtin_amdgcn_s_setprio(1); _Pragma("unroll") for (int m = 0; m < 4; ++m) _Pragma("unroll") for (int n = 0; n < 2; ++n) _Pragma("unroll") for (int k = 0; k < 2; ++k) \
;         acc[ai][bj][m][n] = mma_<I8>(Bt[n][k], At[m][k], acc[ai][bj][m][n]); __builtin_amdgcn_s_setprio(0); } while (0)
; #define PG8_WAIT_V(n) asm volatile("s_waitcnt vmcnt(" #n ")" ::: "memory")
; #define PG8_WAIT_L(n) asm volatile("s_waitcnt lgkmcnt(" #n ")" ::: "memory")
; #define PG8_BAR __builtin_amdgcn_s_barrier()
; #define PG8_SCHED __builtin_amdgcn_sched_barrier(0)
; template <class Epi, class Sched, bool ALIGN_EPI = false, bool SP2 = false, bool I8 = false>
; __device__ __forceinline__ void gemm_phase(PG8_LAS unsigned char* lds, const Gemm g, const Sched& S, const Epi& E) {
;     ...
;             PG8_LDB(B0, 1, 0); PG8_LDB(B1, 1, 1); PG8_SCHED; PG8_LDA(At, 1, 0); PG8_STAGE(PG8_SA(0, 1), a2 + hstepA, voffA);
;             PG8_WAIT_V(8); PG8_WAIT_L(0); PG8_BAR; PG8_MMA(0, 0, At, B0); PG8_MMA(0, 1, At, B1); PG8_BAR; PG8_SCHED;
;             PG8_LDA(At, 1, 1); PG8_STAGE(PG8_SB(1, 0), b3, voffB); PG8_STAGE(PG8_SB(1, 1), b3 + hstepB, voffB); PG8_STAGE(PG8_SA(1, 0), a3, voffA);
;             PG8_WAIT_V(8); PG8_WAIT_L(0); PG8_BAR; PG8_MMA(1, 0, At, B0); PG8_MMA(1, 1, At, B1); PG8_BAR; PG8_SCHED;
	s_add_i32 s40, 0, 0x18000
	s_add_i32 s41, 0, 0x1c000
	v_add_u32_e32 v78, s40, v176
	v_add_u32_e32 v180, s41, v176
	ds_read_b128 v[58:61], v78
	ds_read_b128 v[62:65], v78 offset:1024
	ds_read_b128 v[74:77], v78 offset:2048
	ds_read_b128 v[78:81], v78 offset:3072
	ds_read_b128 v[162:165], v180
	ds_read_b128 v[166:169], v180 offset:1024
	ds_read_b128 v[170:173], v180 offset:2048
	ds_read_b128 v[180:183], v180 offset:3072
	s_add_u32 s36, s36, 0x80000
	s_addc_u32 s37, s37, 0
	s_mov_b32 m0, s71
	ds_read_b128 v[184:187], v179 offset:32768
	ds_read_b128 v[188:191], v179 offset:33792
	ds_read_b128 v[192:195], v179 offset:34816
	ds_read_b128 v[196:199], v179 offset:35840
	ds_read_b128 v[200:203], v179 offset:36864
	ds_read_b128 v[204:207], v179 offset:37888
	ds_read_b128 v[208:211], v179 offset:38912
	ds_read_b128 v[212:215], v179 offset:39936
	global_load_lds_dwordx4 v146, s[36:37]
	s_mov_b32 m0, s88
	s_nop 0
	global_load_lds_dwordx4 v150, s[36:37]
	s_waitcnt vmcnt(8)
	s_waitcnt lgkmcnt(0)
	s_barrier
	s_waitcnt lgkmcnt(0)
	v_mfma_i32_16x16x64_i8 v[142:145], v[58:61], v[184:187], v[142:145]
	v_mfma_i32_16x16x64_i8 v[138:141], v[74:77], v[184:187], v[138:141]
	v_mfma_i32_16x16x64_i8 v[126:129], v[58:61], v[192:195], v[126:129]
	v_mfma_i32_16x16x64_i8 v[122:125], v[74:77], v[192:195], v[122:125]
	v_mfma_i32_16x16x64_i8 v[110:113], v[58:61], v[200:203], v[110:113]
	v_mfma_i32_16x16x64_i8 v[106:109], v[74:77], v[200:203], v[106:109]
	v_mfma_i32_16x16x64_i8 v[94:97], v[58:61], v[208:211], v[94:97]
	v_mfma_i32_16x16x64_i8 v[90:93], v[74:77], v[208:211], v[90:93]
	v_mfma_i32_16x16x64_i8 v[142:145], v[62:65], v[188:191], v[142:145]
	v_mfma_i32_16x16x64_i8 v[138:141], v[78:81], v[188:191], v[138:141]
	v_mfma_i32_16x16x64_i8 v[126:129], v[62:65], v[196:199], v[126:129]
	v_mfma_i32_16x16x64_i8 v[122:125], v[78:81], v[196:199], v[122:125]
	v_mfma_i32_16x16x64_i8 v[110:113], v[62:65], v[204:207], v[110:113]
	v_mfma_i32_16x16x64_i8 v[106:109], v[78:81], v[204:207], v[106:109]
	v_mfma_i32_16x16x64_i8 v[94:97], v[62:65], v[212:215], v[94:97]
	v_mfma_i32_16x16x64_i8 v[90:93], v[78:81], v[212:215], v[90:93]
	v_mfma_i32_16x16x64_i8 v[134:137], v[162:165], v[184:187], v[134:137]
	v_mfma_i32_16x16x64_i8 v[130:133], v[170:173], v[184:187], v[130:133]
	v_mfma_i32_16x16x64_i8 v[118:121], v[162:165], v[192:195], v[118:121]
	v_mfma_i32_16x16x64_i8 v[114:117], v[170:173], v[192:195], v[114:117]
	v_mfma_i32_16x16x64_i8 v[102:105], v[162:165], v[200:203], v[102:105]
	v_mfma_i32_16x16x64_i8 v[98:101], v[170:173], v[200:203], v[98:101]
	v_mfma_i32_16x16x64_i8 v[86:89], v[162:165], v[208:211], v[86:89]
	v_mfma_i32_16x16x64_i8 v[82:85], v[170:173], v[208:211], v[82:85]
	v_mfma_i32_16x16x64_i8 v[134:137], v[166:169], v[188:191], v[134:137]
	v_mfma_i32_16x16x64_i8 v[130:133], v[180:183], v[188:191], v[130:133]
	v_mfma_i32_16x16x64_i8 v[118:121], v[166:169], v[196:199], v[118:121]
	v_mfma_i32_16x16x64_i8 v[114:117], v[180:183], v[196:199], v[114:117]
	v_mfma_i32_16x16x64_i8 v[102:105], v[166:169], v[204:207], v[102:105]
	v_mfma_i32_16x16x64_i8 v[98:101], v[180:183], v[204:207], v[98:101]
	v_mfma_i32_16x16x64_i8 v[86:89], v[166:169], v[212:215], v[86:89]
	v_mfma_i32_16x16x64_i8 v[82:85], v[180:183], v[212:215], v[82:85]
	s_barrier
	s_add_i32 s36, s40, s68
	v_lshl_add_u64 v[174:175], v[174:175], 0, s[18:19]
	s_mov_b32 m0, s36
	ds_read_b128 v[184:187], v179 offset:49152
	ds_read_b128 v[188:191], v179 offset:50176
	ds_read_b128 v[192:195], v179 offset:51200
	ds_read_b128 v[196:199], v179 offset:52224
	ds_read_b128 v[200:203], v179 offset:53248
	ds_read_b128 v[204:207], v179 offset:54272
	ds_read_b128 v[208:211], v179 offset:55296
	ds_read_b128 v[212:215], v179 offset:56320
	global_load_lds_dwordx4 v[174:175], off
	s_add_i32 m0, s36, 0x2000
	s_add_u32 s34, s34, 0x80080
	v_lshl_add_u64 v[174:175], v[216:217], 0, s[18:19]
	s_addc_u32 s35, s35, 0
	s_add_i32 s36, s41, s68
	global_load_lds_dwordx4 v[174:175], off
	s_mov_b32 m0, s36
	s_nop 0
	global_load_lds_dwordx4 v148, s[34:35]
	s_add_i32 m0, s36, 0x2000
	s_nop 0
	global_load_lds_dwordx4 v152, s[34:35]
	v_lshl_add_u64 v[174:175], v[218:219], 0, s[18:19]
	s_mov_b32 m0, s92
	s_nop 0
	global_load_lds_dwordx4 v[174:175], off
	v_lshl_add_u64 v[174:175], v[220:221], 0, s[18:19]
	s_mov_b32 m0, s93
	s_nop 0
	global_load_lds_dwordx4 v[174:175], off
	s_waitcnt vmcnt(8)
	s_waitcnt lgkmcnt(0)
	s_barrier
	s_waitcnt lgkmcnt(0)
	v_mfma_i32_16x16x64_i8 v[70:73], v[58:61], v[184:187], v[70:73]
	v_mfma_i32_16x16x64_i8 v[66:69], v[74:77], v[184:187], v[66:69]
	v_mfma_i32_16x16x64_i8 v[46:49], v[58:61], v[192:195], v[46:49]
	v_mfma_i32_16x16x64_i8 v[42:45], v[74:77], v[192:195], v[42:45]
	v_mfma_i32_16x16x64_i8 v[30:33], v[58:61], v[200:203], v[30:33]
	v_mfma_i32_16x16x64_i8 v[26:29], v[74:77], v[200:203], v[26:29]
	v_mfma_i32_16x16x64_i8 v[14:17], v[58:61], v[208:211], v[14:17]
	v_mfma_i32_16x16x64_i8 v[10:13], v[74:77], v[208:211], v[10:13]
	v_mfma_i32_16x16x64_i8 v[70:73], v[62:65], v[188:191], v[70:73]
	v_mfma_i32_16x16x64_i8 v[66:69], v[78:81], v[188:191], v[66:69]
	v_mfma_i32_16x16x64_i8 v[46:49], v[62:65], v[196:199], v[46:49]
	v_mfma_i32_16x16x64_i8 v[42:45], v[78:81], v[196:199], v[42:45]
	v_mfma_i32_16x16x64_i8 v[30:33], v[62:65], v[204:207], v[30:33]
	v_mfma_i32_16x16x64_i8 v[26:29], v[78:81], v[204:207], v[26:29]
	v_mfma_i32_16x16x64_i8 v[14:17], v[62:65], v[212:215], v[14:17]
	v_mfma_i32_16x16x64_i8 v[10:13], v[78:81], v[212:215], v[10:13]
	v_mfma_i32_16x16x64_i8 v[54:57], v[162:165], v[184:187], v[54:57]
	v_mfma_i32_16x16x64_i8 v[50:53], v[170:173], v[184:187], v[50:53]
	v_mfma_i32_16x16x64_i8 v[38:41], v[162:165], v[192:195], v[38:41]
	v_mfma_i32_16x16x64_i8 v[34:37], v[170:173], v[192:195], v[34:37]
	v_mfma_i32_16x16x64_i8 v[22:25], v[162:165], v[200:203], v[22:25]
	v_mfma_i32_16x16x64_i8 v[18:21], v[170:173], v[200:203], v[18:21]
	v_mfma_i32_16x16x64_i8 v[6:9], v[162:165], v[208:211], v[6:9]
	v_mfma_i32_16x16x64_i8 v[2:5], v[170:173], v[208:211], v[2:5]
	v_mfma_i32_16x16x64_i8 v[54:57], v[166:169], v[188:191], v[54:57]
	v_mfma_i32_16x16x64_i8 v[50:53], v[180:183], v[188:191], v[50:53]
	v_mfma_i32_16x16x64_i8 v[38:41], v[166:169], v[196:199], v[38:41]
	v_mfma_i32_16x16x64_i8 v[34:37], v[180:183], v[196:199], v[34:37]
	v_mfma_i32_16x16x64_i8 v[22:25], v[166:169], v[204:207], v[22:25]
	v_mfma_i32_16x16x64_i8 v[18:21], v[180:183], v[204:207], v[18:21]
	v_mfma_i32_16x16x64_i8 v[6:9], v[166:169], v[212:215], v[6:9]
	v_mfma_i32_16x16x64_i8 v[2:5], v[180:183], v[212:215], v[2:5]
	s_barrier
	s_add_i32 s39, s39, 2
	s_add_u32 s2, s2, 0x100
	s_addc_u32 s3, s3, 0
	s_add_u32 s31, s31, 0x100
	s_addc_u32 s38, s38, 0
	s_cmp_gt_u32 s39, 29
	s_cbranch_scc0 .LBB0_607
	s_and_b64 vcc, exec, s[20:21]
	s_cbranch_vccz .LBB0_610
	s_barrier

; #define PG8_STAGE(bufoff, gbase, voff) do { _Pragma("unroll") for (int _i = 0; _i < 2; ++_i) \
;         __builtin_amdgcn_global_load_lds((const unsigned*)((const char*)(gbase) + (voff)[_i]), (PG8_LAS unsigned*)(lds + (bufoff) + ldsw + _i * 8192), 16, 0, 0); } while (0)
; #define PG8_LDA(dst, b, h) do { _Pragma("unroll") for (int m = 0; m < 4; ++m) _Pragma("unroll") for (int k = 0; k < 2; ++k) dst[m][k] = *(const PG8_LAS bf16x8*)(lds + PG8_SA(b, h) + aoff + m * 2048 + k * 1024); } while (0)
; #define PG8_LDB(dst, b, h) do { _Pragma("unroll") for (int n = 0; n < 2; ++n) _Pragma("unroll") for (int k = 0; k < 2; ++k) dst[n][k] = *(const PG8_LAS bf16x8*)(lds + PG8_SB(b, h) + boff + n * 2048 + k * 1024); } while (0)
; #define PG8_MMA(ai, bj, At, Bt) do { __builtin_amdgcn_s_setprio(1); _Pragma("unroll") for (int m = 0; m < 4; ++m) _Pragma("unroll") for (int n = 0; n < 2; ++n) _Pragma("unroll") for (int k = 0; k < 2; ++k) \
;         acc[ai][bj][m][n] = mma_<I8>(Bt[n][k], At[m][k], acc[ai][bj][m][n]); __builtin_amdgcn_s_setprio(0); } while (0)
; #define PG8_WAIT_V(n) asm volatile("s_waitcnt vmcnt(" #n ")" ::: "memory")
; #define PG8_WAIT_L(n) asm volatile("s_waitcnt lgkmcnt(" #n ")" ::: "memory")
; #define PG8_BAR __builtin_amdgcn_s_barrier()
; #define PG8_SCHED __builtin_amdgcn_sched_barrier(0)
; template <class Epi, class Sched, bool ALIGN_EPI = false, bool SP2 = false, bool I8 = false>
; __device__ __forceinline__ void gemm_phase(PG8_LAS unsigned char* lds, const Gemm g, const Sched& S, const Epi& E) {
;     ...
;             PG8_LDB(B0, 0, 0); PG8_LDB(B1, 0, 1); PG8_SCHED; PG8_LDA(At, 0, 0); PG8_STAGE(PG8_SA(1, 1), a1 + hstepA, voffA);
;             PG8_WAIT_V(8); PG8_WAIT_L(0); PG8_BAR; PG8_MMA(0, 0, At, B0); PG8_MMA(0, 1, At, B1); PG8_BAR; PG8_SCHED;
;             PG8_LDA(At, 0, 1); PG8_STAGE(PG8_SB(0, 0), b2, voffB); PG8_STAGE(PG8_SB(0, 1), b2 + hstepB, voffB); PG8_STAGE(PG8_SA(0, 0), a2, voffA);
;             PG8_WAIT_V(8); PG8_WAIT_L(0); PG8_BAR; PG8_MMA(1, 0, At, B0); PG8_MMA(1, 1, At, B1); PG8_BAR; PG8_SCHED;
;             PG8_LDB(B0, 1, 0); PG8_LDB(B1, 1, 1); PG8_SCHED; PG8_LDA(At, 1, 0); PG8_STAGE(PG8_SA(0, 1), a2 + hstepA, voffA);
;             PG8_WAIT_V(8); PG8_WAIT_L(0); PG8_BAR; PG8_MMA(0, 0, At, B0); PG8_MMA(0, 1, At, B1); PG8_BAR; PG8_SCHED;
.LBB0_1092:
	ds_read_b128 v[58:61], v172
	ds_read_b128 v[62:65], v172 offset:1024
	ds_read_b128 v[74:77], v172 offset:2048
	ds_read_b128 v[78:81], v172 offset:3072
	ds_read_b128 v[164:167], v173
	ds_read_b128 v[168:171], v173 offset:1024
	ds_read_b128 v[176:179], v173 offset:2048
	ds_read_b128 v[180:183], v173 offset:3072
	s_add_i32 s47, s22, 2
	s_add_u32 s23, s8, 0xfffe0080
	s_addc_u32 s24, s9, -1
	s_cmp_eq_u32 s3, s22
	s_cselect_b32 s22, s20, s17
	s_cselect_b32 s25, s1, s24
	s_cselect_b32 s24, s0, s23
	s_cselect_b32 s23, s21, s19
	s_add_i32 m0, s33, 0xc000
	ds_read_b128 v[184:187], v174
	ds_read_b128 v[188:191], v174 offset:1024
	ds_read_b128 v[192:195], v174 offset:2048
	ds_read_b128 v[196:199], v174 offset:3072
	ds_read_b128 v[200:203], v174 offset:4096
	ds_read_b128 v[204:207], v174 offset:5120
	ds_read_b128 v[208:211], v174 offset:6144
	ds_read_b128 v[212:215], v174 offset:7168
	global_load_lds_dwordx4 v156, s[8:9]
	s_add_i32 m0, s33, 0xe000
	s_nop 0
	global_load_lds_dwordx4 v158, s[8:9]
	s_waitcnt vmcnt(8)
	s_waitcnt lgkmcnt(0)
	s_barrier
	s_waitcnt lgkmcnt(0)
	v_mfma_f32_16x16x32_bf16 v[142:145], v[58:61], v[184:187], v[142:145]
	v_mfma_f32_16x16x32_bf16 v[138:141], v[74:77], v[184:187], v[138:141]
	v_mfma_f32_16x16x32_bf16 v[126:129], v[58:61], v[192:195], v[126:129]
	v_mfma_f32_16x16x32_bf16 v[122:125], v[74:77], v[192:195], v[122:125]
	v_mfma_f32_16x16x32_bf16 v[110:113], v[58:61], v[200:203], v[110:113]
	v_mfma_f32_16x16x32_bf16 v[106:109], v[74:77], v[200:203], v[106:109]
	v_mfma_f32_16x16x32_bf16 v[94:97], v[58:61], v[208:211], v[94:97]
	v_mfma_f32_16x16x32_bf16 v[90:93], v[74:77], v[208:211], v[90:93]
	v_mfma_f32_16x16x32_bf16 v[142:145], v[62:65], v[188:191], v[142:145]
	v_mfma_f32_16x16x32_bf16 v[138:141], v[78:81], v[188:191], v[138:141]
	v_mfma_f32_16x16x32_bf16 v[126:129], v[62:65], v[196:199], v[126:129]
	v_mfma_f32_16x16x32_bf16 v[122:125], v[78:81], v[196:199], v[122:125]
	v_mfma_f32_16x16x32_bf16 v[110:113], v[62:65], v[204:207], v[110:113]
	v_mfma_f32_16x16x32_bf16 v[106:109], v[78:81], v[204:207], v[106:109]
	v_mfma_f32_16x16x32_bf16 v[94:97], v[62:65], v[212:215], v[94:97]
	v_mfma_f32_16x16x32_bf16 v[90:93], v[78:81], v[212:215], v[90:93]
	v_mfma_f32_16x16x32_bf16 v[134:137], v[164:167], v[184:187], v[134:137]
	v_mfma_f32_16x16x32_bf16 v[130:133], v[176:179], v[184:187], v[130:133]
	v_mfma_f32_16x16x32_bf16 v[118:121], v[164:167], v[192:195], v[118:121]
	v_mfma_f32_16x16x32_bf16 v[114:117], v[176:179], v[192:195], v[114:117]
	v_mfma_f32_16x16x32_bf16 v[102:105], v[164:167], v[200:203], v[102:105]
	v_mfma_f32_16x16x32_bf16 v[98:101], v[176:179], v[200:203], v[98:101]
	v_mfma_f32_16x16x32_bf16 v[86:89], v[164:167], v[208:211], v[86:89]
	v_mfma_f32_16x16x32_bf16 v[82:85], v[176:179], v[208:211], v[82:85]
	v_mfma_f32_16x16x32_bf16 v[134:137], v[168:171], v[188:191], v[134:137]
	v_mfma_f32_16x16x32_bf16 v[130:133], v[180:183], v[188:191], v[130:133]
	v_mfma_f32_16x16x32_bf16 v[118:121], v[168:171], v[196:199], v[118:121]
	v_mfma_f32_16x16x32_bf16 v[114:117], v[180:183], v[196:199], v[114:117]
	v_mfma_f32_16x16x32_bf16 v[102:105], v[168:171], v[204:207], v[102:105]
	v_mfma_f32_16x16x32_bf16 v[98:101], v[180:183], v[204:207], v[98:101]
	v_mfma_f32_16x16x32_bf16 v[86:89], v[168:171], v[212:215], v[86:89]
	v_mfma_f32_16x16x32_bf16 v[82:85], v[180:183], v[212:215], v[82:85]
	s_barrier
	s_add_i32 s56, s44, s30
	v_lshl_add_u64 v[216:217], s[22:23], 0, v[148:149]
	s_mov_b32 m0, s56
	ds_read_b128 v[184:187], v174 offset:16384
	ds_read_b128 v[188:191], v174 offset:17408
	ds_read_b128 v[192:195], v174 offset:18432
	ds_read_b128 v[196:199], v174 offset:19456
	ds_read_b128 v[200:203], v174 offset:20480
	ds_read_b128 v[204:207], v174 offset:21504
	ds_read_b128 v[208:211], v174 offset:22528
	ds_read_b128 v[212:215], v174 offset:23552
	global_load_lds_dwordx4 v148, s[22:23]
	s_add_i32 m0, s56, 0x2000
	s_add_u32 s56, s22, 0x20000
	v_lshl_add_u64 v[218:219], s[22:23], 0, v[152:153]
	s_addc_u32 s57, s23, 0
	s_add_i32 s58, s45, s30
	global_load_lds_dwordx4 v152, s[22:23]
	s_mov_b32 m0, s58
	v_lshl_add_u64 v[222:223], s[24:25], 0, v[150:151]
	global_load_lds_dwordx4 v148, s[56:57]
	s_add_i32 m0, s58, 0x2000
	s_nop 0
	global_load_lds_dwordx4 v152, s[56:57]
	v_lshl_add_u64 v[220:221], s[24:25], 0, v[146:147]
	s_mov_b32 m0, s33
	s_nop 0
	global_load_lds_dwordx4 v146, s[24:25]
	s_mov_b32 m0, s34
	s_nop 0
	global_load_lds_dwordx4 v150, s[24:25]
	s_waitcnt vmcnt(8)
	s_waitcnt lgkmcnt(0)
	s_barrier
	s_waitcnt lgkmcnt(0)
	v_mfma_f32_16x16x32_bf16 v[70:73], v[58:61], v[184:187], v[70:73]
	v_mfma_f32_16x16x32_bf16 v[66:69], v[74:77], v[184:187], v[66:69]
	v_mfma_f32_16x16x32_bf16 v[46:49], v[58:61], v[192:195], v[46:49]
	v_mfma_f32_16x16x32_bf16 v[42:45], v[74:77], v[192:195], v[42:45]
	v_mfma_f32_16x16x32_bf16 v[30:33], v[58:61], v[200:203], v[30:33]
	v_mfma_f32_16x16x32_bf16 v[26:29], v[74:77], v[200:203], v[26:29]
	v_mfma_f32_16x16x32_bf16 v[14:17], v[58:61], v[208:211], v[14:17]
	v_mfma_f32_16x16x32_bf16 v[10:13], v[74:77], v[208:211], v[10:13]
	v_mfma_f32_16x16x32_bf16 v[70:73], v[62:65], v[188:191], v[70:73]
	v_mfma_f32_16x16x32_bf16 v[66:69], v[78:81], v[188:191], v[66:69]
	v_mfma_f32_16x16x32_bf16 v[46:49], v[62:65], v[196:199], v[46:49]
	v_mfma_f32_16x16x32_bf16 v[42:45], v[78:81], v[196:199], v[42:45]
	v_mfma_f32_16x16x32_bf16 v[30:33], v[62:65], v[204:207], v[30:33]
	v_mfma_f32_16x16x32_bf16 v[26:29], v[78:81], v[204:207], v[26:29]
	v_mfma_f32_16x16x32_bf16 v[14:17], v[62:65], v[212:215], v[14:17]
	v_mfma_f32_16x16x32_bf16 v[10:13], v[78:81], v[212:215], v[10:13]
	v_mfma_f32_16x16x32_bf16 v[54:57], v[164:167], v[184:187], v[54:57]
	v_mfma_f32_16x16x32_bf16 v[50:53], v[176:179], v[184:187], v[50:53]
	v_mfma_f32_16x16x32_bf16 v[38:41], v[164:167], v[192:195], v[38:41]
	v_mfma_f32_16x16x32_bf16 v[34:37], v[176:179], v[192:195], v[34:37]
	v_mfma_f32_16x16x32_bf16 v[22:25], v[164:167], v[200:203], v[22:25]
	v_mfma_f32_16x16x32_bf16 v[18:21], v[176:179], v[200:203], v[18:21]
	v_mfma_f32_16x16x32_bf16 v[6:9], v[164:167], v[208:211], v[6:9]
	v_mfma_f32_16x16x32_bf16 v[2:5], v[176:179], v[208:211], v[2:5]
	v_mfma_f32_16x16x32_bf16 v[54:57], v[168:171], v[188:191], v[54:57]
	v_mfma_f32_16x16x32_bf16 v[50:53], v[180:183], v[188:191], v[50:53]
	v_mfma_f32_16x16x32_bf16 v[38:41], v[168:171], v[196:199], v[38:41]
	v_mfma_f32_16x16x32_bf16 v[34:37], v[180:183], v[196:199], v[34:37]
	v_mfma_f32_16x16x32_bf16 v[22:25], v[168:171], v[204:207], v[22:25]
	v_mfma_f32_16x16x32_bf16 v[18:21], v[180:183], v[204:207], v[18:21]
	v_mfma_f32_16x16x32_bf16 v[6:9], v[168:171], v[212:215], v[6:9]
	v_mfma_f32_16x16x32_bf16 v[2:5], v[180:183], v[212:215], v[2:5]
	s_barrier
; #define PG8_STAGE(bufoff, gbase, voff) do { _Pragma("unroll") for (int _i = 0; _i < 2; ++_i) \
;         __builtin_amdgcn_global_load_lds((const unsigned*)((const char*)(gbase) + (voff)[_i]), (PG8_LAS unsigned*)(lds + (bufoff) + ldsw + _i * 8192), 16, 0, 0); } while (0)
; #define PG8_LDA(dst, b, h) do { _Pragma("unroll") for (int m = 0; m < 4; ++m) _Pragma("unroll") for (int k = 0; k < 2; ++k) dst[m][k] = *(const PG8_LAS bf16x8*)(lds + PG8_SA(b, h) + aoff + m * 2048 + k * 1024); } while (0)
; #define PG8_LDB(dst, b, h) do { _Pragma("unroll") for (int n = 0; n < 2; ++n) _Pragma("unroll") for (int k = 0; k < 2; ++k) dst[n][k] = *(const PG8_LAS bf16x8*)(lds + PG8_SB(b, h) + boff + n * 2048 + k * 1024); } while (0)
; #define PG8_MMA(ai, bj, At, Bt) do { __builtin_amdgcn_s_setprio(1); _Pragma("unroll") for (int m = 0; m < 4; ++m) _Pragma("unroll") for (int n = 0; n < 2; ++n) _Pragma("unroll") for (int k = 0; k < 2; ++k) \
;         acc[ai][bj][m][n] = mma_<I8>(Bt[n][k], At[m][k], acc[ai][bj][m][n]); __builtin_amdgcn_s_setprio(0); } while (0)
; #define PG8_WAIT_V(n) asm volatile("s_waitcnt vmcnt(" #n ")" ::: "memory")
; #define PG8_WAIT_L(n) asm volatile("s_waitcnt lgkmcnt(" #n ")" ::: "memory")
; #define PG8_BAR __builtin_amdgcn_s_barrier()
; #define PG8_SCHED __builtin_amdgcn_sched_barrier(0)
; template <class Epi, class Sched, bool ALIGN_EPI = false, bool SP2 = false, bool I8 = false>
; __device__ __forceinline__ void gemm_phase(PG8_LAS unsigned char* lds, const Gemm g, const Sched& S, const Epi& E) {
;     ...
;             PG8_LDB(B0, 1, 0); PG8_LDB(B1, 1, 1); PG8_SCHED; PG8_LDA(At, 1, 0); PG8_STAGE(PG8_SA(0, 1), a2 + hstepA, voffA);
;             PG8_WAIT_V(8); PG8_WAIT_L(0); PG8_BAR; PG8_MMA(0, 0, At, B0); PG8_MMA(0, 1, At, B1); PG8_BAR; PG8_SCHED;
;             PG8_LDA(At, 1, 1); PG8_STAGE(PG8_SB(1, 0), b3, voffB); PG8_STAGE(PG8_SB(1, 1), b3 + hstepB, voffB); PG8_STAGE(PG8_SA(1, 0), a3, voffA);
;             PG8_WAIT_V(8); PG8_WAIT_L(0); PG8_BAR; PG8_MMA(1, 0, At, B0); PG8_MMA(1, 1, At, B1); PG8_BAR; PG8_SCHED;
;     ...
;         if constexpr (ALIGN_EPI) { if (wr == 0) PG8_BAR; }
	s_add_i32 s56, 0, 0x18000
	s_add_i32 s57, 0, 0x1c000
	v_add_u32_e32 v78, s56, v1
	v_add_u32_e32 v154, s57, v1
	ds_read_b128 v[58:61], v78
	ds_read_b128 v[62:65], v78 offset:1024
	ds_read_b128 v[74:77], v78 offset:2048
	ds_read_b128 v[78:81], v78 offset:3072
	ds_read_b128 v[164:167], v154
	ds_read_b128 v[168:171], v154 offset:1024
	ds_read_b128 v[176:179], v154 offset:2048
	ds_read_b128 v[180:183], v154 offset:3072
	s_add_u32 s24, s24, 0x20000
	s_addc_u32 s25, s25, 0
	s_mov_b32 m0, s35
	ds_read_b128 v[184:187], v174 offset:32768
	ds_read_b128 v[188:191], v174 offset:33792
	ds_read_b128 v[192:195], v174 offset:34816
	ds_read_b128 v[196:199], v174 offset:35840
	ds_read_b128 v[200:203], v174 offset:36864
	ds_read_b128 v[204:207], v174 offset:37888
	ds_read_b128 v[208:211], v174 offset:38912
	ds_read_b128 v[212:215], v174 offset:39936
	global_load_lds_dwordx4 v146, s[24:25]
	s_mov_b32 m0, s36
	s_nop 0
	global_load_lds_dwordx4 v150, s[24:25]
	s_waitcnt vmcnt(8)
	s_waitcnt lgkmcnt(0)
	s_barrier
	s_waitcnt lgkmcnt(0)
	v_mfma_f32_16x16x32_bf16 v[142:145], v[58:61], v[184:187], v[142:145]
	v_mfma_f32_16x16x32_bf16 v[138:141], v[74:77], v[184:187], v[138:141]
	v_mfma_f32_16x16x32_bf16 v[126:129], v[58:61], v[192:195], v[126:129]
	v_mfma_f32_16x16x32_bf16 v[122:125], v[74:77], v[192:195], v[122:125]
	v_mfma_f32_16x16x32_bf16 v[110:113], v[58:61], v[200:203], v[110:113]
	v_mfma_f32_16x16x32_bf16 v[106:109], v[74:77], v[200:203], v[106:109]
	v_mfma_f32_16x16x32_bf16 v[94:97], v[58:61], v[208:211], v[94:97]
	v_mfma_f32_16x16x32_bf16 v[90:93], v[74:77], v[208:211], v[90:93]
	v_mfma_f32_16x16x32_bf16 v[142:145], v[62:65], v[188:191], v[142:145]
	v_mfma_f32_16x16x32_bf16 v[138:141], v[78:81], v[188:191], v[138:141]
	v_mfma_f32_16x16x32_bf16 v[126:129], v[62:65], v[196:199], v[126:129]
	v_mfma_f32_16x16x32_bf16 v[122:125], v[78:81], v[196:199], v[122:125]
	v_mfma_f32_16x16x32_bf16 v[110:113], v[62:65], v[204:207], v[110:113]
	v_mfma_f32_16x16x32_bf16 v[106:109], v[78:81], v[204:207], v[106:109]
	v_mfma_f32_16x16x32_bf16 v[94:97], v[62:65], v[212:215], v[94:97]
	v_mfma_f32_16x16x32_bf16 v[90:93], v[78:81], v[212:215], v[90:93]
	v_mfma_f32_16x16x32_bf16 v[134:137], v[164:167], v[184:187], v[134:137]
	v_mfma_f32_16x16x32_bf16 v[130:133], v[176:179], v[184:187], v[130:133]
	v_mfma_f32_16x16x32_bf16 v[118:121], v[164:167], v[192:195], v[118:121]
	v_mfma_f32_16x16x32_bf16 v[114:117], v[176:179], v[192:195], v[114:117]
	v_mfma_f32_16x16x32_bf16 v[102:105], v[164:167], v[200:203], v[102:105]
	v_mfma_f32_16x16x32_bf16 v[98:101], v[176:179], v[200:203], v[98:101]
	v_mfma_f32_16x16x32_bf16 v[86:89], v[164:167], v[208:211], v[86:89]
	v_mfma_f32_16x16x32_bf16 v[82:85], v[176:179], v[208:211], v[82:85]
	v_mfma_f32_16x16x32_bf16 v[134:137], v[168:171], v[188:191], v[134:137]
	v_mfma_f32_16x16x32_bf16 v[130:133], v[180:183], v[188:191], v[130:133]
	v_mfma_f32_16x16x32_bf16 v[118:121], v[168:171], v[196:199], v[118:121]
	v_mfma_f32_16x16x32_bf16 v[114:117], v[180:183], v[196:199], v[114:117]
	v_mfma_f32_16x16x32_bf16 v[102:105], v[168:171], v[204:207], v[102:105]
	v_mfma_f32_16x16x32_bf16 v[98:101], v[180:183], v[204:207], v[98:101]
	v_mfma_f32_16x16x32_bf16 v[86:89], v[168:171], v[212:215], v[86:89]
	v_mfma_f32_16x16x32_bf16 v[82:85], v[180:183], v[212:215], v[82:85]
	s_barrier
	s_add_i32 s24, s56, s30
	v_lshl_add_u64 v[216:217], v[216:217], 0, s[12:13]
	s_mov_b32 m0, s24
	ds_read_b128 v[184:187], v174 offset:49152
	ds_read_b128 v[188:191], v174 offset:50176
	ds_read_b128 v[192:195], v174 offset:51200
	ds_read_b128 v[196:199], v174 offset:52224
	ds_read_b128 v[200:203], v174 offset:53248
	ds_read_b128 v[204:207], v174 offset:54272
	ds_read_b128 v[208:211], v174 offset:55296
	ds_read_b128 v[212:215], v174 offset:56320
	global_load_lds_dwordx4 v[216:217], off
	s_add_i32 m0, s24, 0x2000
	s_add_u32 s22, s22, 0x20080
	v_lshl_add_u64 v[216:217], v[218:219], 0, s[12:13]
	s_addc_u32 s23, s23, 0
	s_add_i32 s24, s57, s30
	global_load_lds_dwordx4 v[216:217], off
	s_mov_b32 m0, s24
	s_nop 0
	global_load_lds_dwordx4 v148, s[22:23]
	s_add_i32 m0, s24, 0x2000
	s_nop 0
	global_load_lds_dwordx4 v152, s[22:23]
	v_lshl_add_u64 v[216:217], v[220:221], 0, s[12:13]
	s_mov_b32 m0, s40
	s_nop 0
	global_load_lds_dwordx4 v[216:217], off
	v_lshl_add_u64 v[216:217], v[222:223], 0, s[12:13]
	s_mov_b32 m0, s41
	s_nop 0
	global_load_lds_dwordx4 v[216:217], off
	s_waitcnt vmcnt(8)
	s_waitcnt lgkmcnt(0)
	s_barrier
	s_waitcnt lgkmcnt(0)
	v_mfma_f32_16x16x32_bf16 v[70:73], v[58:61], v[184:187], v[70:73]
	v_mfma_f32_16x16x32_bf16 v[66:69], v[74:77], v[184:187], v[66:69]
	v_mfma_f32_16x16x32_bf16 v[46:49], v[58:61], v[192:195], v[46:49]
	v_mfma_f32_16x16x32_bf16 v[42:45], v[74:77], v[192:195], v[42:45]
	v_mfma_f32_16x16x32_bf16 v[30:33], v[58:61], v[200:203], v[30:33]
	v_mfma_f32_16x16x32_bf16 v[26:29], v[74:77], v[200:203], v[26:29]
	v_mfma_f32_16x16x32_bf16 v[14:17], v[58:61], v[208:211], v[14:17]
	v_mfma_f32_16x16x32_bf16 v[10:13], v[74:77], v[208:211], v[10:13]
	v_mfma_f32_16x16x32_bf16 v[70:73], v[62:65], v[188:191], v[70:73]
	v_mfma_f32_16x16x32_bf16 v[66:69], v[78:81], v[188:191], v[66:69]
	v_mfma_f32_16x16x32_bf16 v[46:49], v[62:65], v[196:199], v[46:49]
	v_mfma_f32_16x16x32_bf16 v[42:45], v[78:81], v[196:199], v[42:45]
	v_mfma_f32_16x16x32_bf16 v[30:33], v[62:65], v[204:207], v[30:33]
	v_mfma_f32_16x16x32_bf16 v[26:29], v[78:81], v[204:207], v[26:29]
	v_mfma_f32_16x16x32_bf16 v[14:17], v[62:65], v[212:215], v[14:17]
	v_mfma_f32_16x16x32_bf16 v[10:13], v[78:81], v[212:215], v[10:13]
	v_mfma_f32_16x16x32_bf16 v[54:57], v[164:167], v[184:187], v[54:57]
	v_mfma_f32_16x16x32_bf16 v[50:53], v[176:179], v[184:187], v[50:53]
	v_mfma_f32_16x16x32_bf16 v[38:41], v[164:167], v[192:195], v[38:41]
	v_mfma_f32_16x16x32_bf16 v[34:37], v[176:179], v[192:195], v[34:37]
	v_mfma_f32_16x16x32_bf16 v[22:25], v[164:167], v[200:203], v[22:25]
	v_mfma_f32_16x16x32_bf16 v[18:21], v[176:179], v[200:203], v[18:21]
	v_mfma_f32_16x16x32_bf16 v[6:9], v[164:167], v[208:211], v[6:9]
	v_mfma_f32_16x16x32_bf16 v[2:5], v[176:179], v[208:211], v[2:5]
	v_mfma_f32_16x16x32_bf16 v[54:57], v[168:171], v[188:191], v[54:57]
	v_mfma_f32_16x16x32_bf16 v[50:53], v[180:183], v[188:191], v[50:53]
	v_mfma_f32_16x16x32_bf16 v[38:41], v[168:171], v[196:199], v[38:41]
	v_mfma_f32_16x16x32_bf16 v[34:37], v[180:183], v[196:199], v[34:37]
	v_mfma_f32_16x16x32_bf16 v[22:25], v[168:171], v[204:207], v[22:25]
	v_mfma_f32_16x16x32_bf16 v[18:21], v[180:183], v[204:207], v[18:21]
	v_mfma_f32_16x16x32_bf16 v[6:9], v[168:171], v[212:215], v[6:9]
	v_mfma_f32_16x16x32_bf16 v[2:5], v[180:183], v[212:215], v[2:5]
	s_barrier
	s_add_u32 s8, s8, 0x100
	s_addc_u32 s9, s9, 0
	s_add_u32 s17, s17, 0x100
	s_addc_u32 s19, s19, 0
	s_cmp_ge_u32 s47, s7
	s_mov_b32 s22, s47
	s_cbranch_scc0 .LBB0_1092
	s_and_b64 vcc, exec, s[14:15]
	s_cbranch_vccz .LBB0_1095
	s_barrier

; #define PG8_STAGE(bufoff, gbase, voff) do { _Pragma("unroll") for (int _i = 0; _i < 2; ++_i) \
;         __builtin_amdgcn_global_load_lds((const unsigned*)((const char*)(gbase) + (voff)[_i]), (PG8_LAS unsigned*)(lds + (bufoff) + ldsw + _i * 8192), 16, 0, 0); } while (0)
; #define PG8_LDA(dst, b, h) do { _Pragma("unroll") for (int m = 0; m < 4; ++m) _Pragma("unroll") for (int k = 0; k < 2; ++k) dst[m][k] = *(const PG8_LAS bf16x8*)(lds + PG8_SA(b, h) + aoff + m * 2048 + k * 1024); } while (0)
; #define PG8_LDB(dst, b, h) do { _Pragma("unroll") for (int n = 0; n < 2; ++n) _Pragma("unroll") for (int k = 0; k < 2; ++k) dst[n][k] = *(const PG8_LAS bf16x8*)(lds + PG8_SB(b, h) + boff + n * 2048 + k * 1024); } while (0)
; #define PG8_MMA(ai, bj, At, Bt) do { __builtin_amdgcn_s_setprio(1); _Pragma("unroll") for (int m = 0; m < 4; ++m) _Pragma("unroll") for (int n = 0; n < 2; ++n) _Pragma("unroll") for (int k = 0; k < 2; ++k) \
;         acc[ai][bj][m][n] = mma_<I8>(Bt[n][k], At[m][k], acc[ai][bj][m][n]); __builtin_amdgcn_s_setprio(0); } while (0)
; #define PG8_WAIT_V(n) asm volatile("s_waitcnt vmcnt(" #n ")" ::: "memory")
; #define PG8_WAIT_L(n) asm volatile("s_waitcnt lgkmcnt(" #n ")" ::: "memory")
; #define PG8_BAR __builtin_amdgcn_s_barrier()
; #define PG8_SCHED __builtin_amdgcn_sched_barrier(0)
; template <class Epi, class Sched, bool ALIGN_EPI = false, bool SP2 = false, bool I8 = false>
; __device__ __forceinline__ void gemm_phase(PG8_LAS unsigned char* lds, const Gemm g, const Sched& S, const Epi& E) {
;     ...
;             const char* a1 = cA + (size_t)(t + 1) * kstep;
;             const char* a2 = last ? nA : cA + (size_t)(t + 2) * kstep; const char* b2 = last ? nB : cB + (size_t)(t + 2) * kstep;
;             const char* a3 = a2 + kstep; const char* b3 = b2 + kstep;
;             if (last && has_next) S.a_ready(nxt);
;             if constexpr (SP2) {
;             PG8_LDB(B0, 0, 0); PG8_LDB(B1, 0, 1); PG8_SCHED; PG8_LDA(At, 0, 0); PG8_STAGE(PG8_SA(1, 1), a1 + hstepA, voffA);
;             PG8_WAIT_V(8); PG8_WAIT_L(0); PG8_BAR; PG8_MMA(0, 0, At, B0); PG8_MMA(0, 1, At, B1); PG8_BAR; PG8_SCHED;
;             PG8_LDA(At, 0, 1); PG8_STAGE(PG8_SB(0, 0), b2, voffB); PG8_STAGE(PG8_SB(0, 1), b2 + hstepB, voffB); PG8_STAGE(PG8_SA(0, 0), a2, voffA);
;             PG8_WAIT_V(8); PG8_WAIT_L(0); PG8_BAR; PG8_MMA(1, 0, At, B0); PG8_MMA(1, 1, At, B1); PG8_BAR; PG8_SCHED;
.LBB0_1538:
	ds_read_b128 v[146:149], v154
	ds_read_b128 v[150:153], v154 offset:1024
	ds_read_b128 v[158:161], v154 offset:2048
	ds_read_b128 v[162:165], v154 offset:3072
	ds_read_b128 v[166:169], v155
	ds_read_b128 v[170:173], v155 offset:1024
	ds_read_b128 v[174:177], v155 offset:2048
	ds_read_b128 v[178:181], v155 offset:3072
	s_add_u32 s24, s22, 0xfffe0080
	s_addc_u32 s25, s23, -1
	s_cmp_eq_u32 s49, 4
	s_cselect_b32 s27, s15, s25
	s_cselect_b32 s26, s45, s24
	s_cselect_b32 s25, s13, s48
	s_cselect_b32 s24, s46, s47
	s_add_i32 m0, s21, 0xc000
	ds_read_b128 v[182:185], v156
	ds_read_b128 v[186:189], v156 offset:1024
	ds_read_b128 v[190:193], v156 offset:2048
	ds_read_b128 v[194:197], v156 offset:3072
	ds_read_b128 v[198:201], v156 offset:4096
	ds_read_b128 v[202:205], v156 offset:5120
	ds_read_b128 v[206:209], v156 offset:6144
	ds_read_b128 v[210:213], v156 offset:7168
	global_load_lds_dwordx4 v138, s[22:23]
	s_add_i32 m0, s21, 0xe000
	s_nop 0
	global_load_lds_dwordx4 v140, s[22:23]
	s_waitcnt vmcnt(8)
	s_waitcnt lgkmcnt(0)
	s_barrier
	s_waitcnt lgkmcnt(0)
	v_mfma_f32_16x16x32_bf16 v[126:129], v[146:149], v[182:185], v[126:129]
	v_mfma_f32_16x16x32_bf16 v[122:125], v[158:161], v[182:185], v[122:125]
	v_mfma_f32_16x16x32_bf16 v[114:117], v[146:149], v[190:193], v[114:117]
	v_mfma_f32_16x16x32_bf16 v[106:109], v[158:161], v[190:193], v[106:109]
	v_mfma_f32_16x16x32_bf16 v[94:97], v[146:149], v[198:201], v[94:97]
	v_mfma_f32_16x16x32_bf16 v[90:93], v[158:161], v[198:201], v[90:93]
	v_mfma_f32_16x16x32_bf16 v[86:89], v[146:149], v[206:209], v[86:89]
	v_mfma_f32_16x16x32_bf16 v[82:85], v[158:161], v[206:209], v[82:85]
	v_mfma_f32_16x16x32_bf16 v[126:129], v[150:153], v[186:189], v[126:129]
	v_mfma_f32_16x16x32_bf16 v[122:125], v[162:165], v[186:189], v[122:125]
	v_mfma_f32_16x16x32_bf16 v[114:117], v[150:153], v[194:197], v[114:117]
	v_mfma_f32_16x16x32_bf16 v[106:109], v[162:165], v[194:197], v[106:109]
	v_mfma_f32_16x16x32_bf16 v[94:97], v[150:153], v[202:205], v[94:97]
	v_mfma_f32_16x16x32_bf16 v[90:93], v[162:165], v[202:205], v[90:93]
	v_mfma_f32_16x16x32_bf16 v[86:89], v[150:153], v[210:213], v[86:89]
	v_mfma_f32_16x16x32_bf16 v[82:85], v[162:165], v[210:213], v[82:85]
	v_mfma_f32_16x16x32_bf16 v[118:121], v[166:169], v[182:185], v[118:121]
	v_mfma_f32_16x16x32_bf16 v[110:113], v[174:177], v[182:185], v[110:113]
	v_mfma_f32_16x16x32_bf16 v[102:105], v[166:169], v[190:193], v[102:105]
	v_mfma_f32_16x16x32_bf16 v[98:101], v[174:177], v[190:193], v[98:101]
	v_mfma_f32_16x16x32_bf16 v[78:81], v[166:169], v[198:201], v[78:81]
	v_mfma_f32_16x16x32_bf16 v[74:77], v[174:177], v[198:201], v[74:77]
	v_mfma_f32_16x16x32_bf16 v[70:73], v[166:169], v[206:209], v[70:73]
	v_mfma_f32_16x16x32_bf16 v[66:69], v[174:177], v[206:209], v[66:69]
	v_mfma_f32_16x16x32_bf16 v[118:121], v[170:173], v[186:189], v[118:121]
	v_mfma_f32_16x16x32_bf16 v[110:113], v[178:181], v[186:189], v[110:113]
	v_mfma_f32_16x16x32_bf16 v[102:105], v[170:173], v[194:197], v[102:105]
	v_mfma_f32_16x16x32_bf16 v[98:101], v[178:181], v[194:197], v[98:101]
	v_mfma_f32_16x16x32_bf16 v[78:81], v[170:173], v[202:205], v[78:81]
	v_mfma_f32_16x16x32_bf16 v[74:77], v[178:181], v[202:205], v[74:77]
	v_mfma_f32_16x16x32_bf16 v[70:73], v[170:173], v[210:213], v[70:73]
	v_mfma_f32_16x16x32_bf16 v[66:69], v[178:181], v[210:213], v[66:69]
	s_barrier
	s_add_i32 s50, s42, s34
	v_lshl_add_u64 v[214:215], s[24:25], 0, v[132:133]
	s_mov_b32 m0, s50
	ds_read_b128 v[182:185], v156 offset:16384
	ds_read_b128 v[186:189], v156 offset:17408
	ds_read_b128 v[190:193], v156 offset:18432
	ds_read_b128 v[194:197], v156 offset:19456
	ds_read_b128 v[198:201], v156 offset:20480
	ds_read_b128 v[202:205], v156 offset:21504
	ds_read_b128 v[206:209], v156 offset:22528
	ds_read_b128 v[210:213], v156 offset:23552
	global_load_lds_dwordx4 v132, s[24:25]
	s_add_i32 m0, s50, 0x2000
	s_add_u32 s50, s24, 0x20000
	v_lshl_add_u64 v[216:217], s[24:25], 0, v[136:137]
	s_addc_u32 s51, s25, 0
	s_add_i32 s52, s43, s34
	global_load_lds_dwordx4 v136, s[24:25]
	s_mov_b32 m0, s52
	v_lshl_add_u64 v[220:221], s[26:27], 0, v[134:135]
	global_load_lds_dwordx4 v132, s[50:51]
	s_add_i32 m0, s52, 0x2000
	s_nop 0
	global_load_lds_dwordx4 v136, s[50:51]
	v_lshl_add_u64 v[218:219], s[26:27], 0, v[130:131]
	s_mov_b32 m0, s21
	s_nop 0
	global_load_lds_dwordx4 v130, s[26:27]
	s_mov_b32 m0, s35
	s_nop 0
	global_load_lds_dwordx4 v134, s[26:27]
	s_waitcnt vmcnt(8)
	s_waitcnt lgkmcnt(0)
	s_barrier
	s_waitcnt lgkmcnt(0)
	v_mfma_f32_16x16x32_bf16 v[62:65], v[146:149], v[182:185], v[62:65]
	v_mfma_f32_16x16x32_bf16 v[58:61], v[158:161], v[182:185], v[58:61]
	v_mfma_f32_16x16x32_bf16 v[54:57], v[146:149], v[190:193], v[54:57]
	v_mfma_f32_16x16x32_bf16 v[50:53], v[158:161], v[190:193], v[50:53]
	v_mfma_f32_16x16x32_bf16 v[30:33], v[146:149], v[198:201], v[30:33]
	v_mfma_f32_16x16x32_bf16 v[26:29], v[158:161], v[198:201], v[26:29]
	v_mfma_f32_16x16x32_bf16 v[22:25], v[146:149], v[206:209], v[22:25]
	v_mfma_f32_16x16x32_bf16 v[10:13], v[158:161], v[206:209], v[10:13]
	v_mfma_f32_16x16x32_bf16 v[62:65], v[150:153], v[186:189], v[62:65]
	v_mfma_f32_16x16x32_bf16 v[58:61], v[162:165], v[186:189], v[58:61]
	v_mfma_f32_16x16x32_bf16 v[54:57], v[150:153], v[194:197], v[54:57]
	v_mfma_f32_16x16x32_bf16 v[50:53], v[162:165], v[194:197], v[50:53]
	v_mfma_f32_16x16x32_bf16 v[30:33], v[150:153], v[202:205], v[30:33]
	v_mfma_f32_16x16x32_bf16 v[26:29], v[162:165], v[202:205], v[26:29]
	v_mfma_f32_16x16x32_bf16 v[22:25], v[150:153], v[210:213], v[22:25]
	v_mfma_f32_16x16x32_bf16 v[10:13], v[162:165], v[210:213], v[10:13]
	v_mfma_f32_16x16x32_bf16 v[46:49], v[166:169], v[182:185], v[46:49]
	v_mfma_f32_16x16x32_bf16 v[42:45], v[174:177], v[182:185], v[42:45]
	v_mfma_f32_16x16x32_bf16 v[38:41], v[166:169], v[190:193], v[38:41]
	v_mfma_f32_16x16x32_bf16 v[34:37], v[174:177], v[190:193], v[34:37]
	v_mfma_f32_16x16x32_bf16 v[18:21], v[166:169], v[198:201], v[18:21]
	v_mfma_f32_16x16x32_bf16 v[14:17], v[174:177], v[198:201], v[14:17]
	v_mfma_f32_16x16x32_bf16 v[6:9], v[166:169], v[206:209], v[6:9]
	v_mfma_f32_16x16x32_bf16 v[2:5], v[174:177], v[206:209], v[2:5]
	v_mfma_f32_16x16x32_bf16 v[46:49], v[170:173], v[186:189], v[46:49]
	v_mfma_f32_16x16x32_bf16 v[42:45], v[178:181], v[186:189], v[42:45]
	v_mfma_f32_16x16x32_bf16 v[38:41], v[170:173], v[194:197], v[38:41]
	v_mfma_f32_16x16x32_bf16 v[34:37], v[178:181], v[194:197], v[34:37]
	v_mfma_f32_16x16x32_bf16 v[18:21], v[170:173], v[202:205], v[18:21]
	v_mfma_f32_16x16x32_bf16 v[14:17], v[178:181], v[202:205], v[14:17]
	v_mfma_f32_16x16x32_bf16 v[6:9], v[170:173], v[210:213], v[6:9]
	v_mfma_f32_16x16x32_bf16 v[2:5], v[178:181], v[210:213], v[2:5]
	s_barrier
; #define PG8_STAGE(bufoff, gbase, voff) do { _Pragma("unroll") for (int _i = 0; _i < 2; ++_i) \
;         __builtin_amdgcn_global_load_lds((const unsigned*)((const char*)(gbase) + (voff)[_i]), (PG8_LAS unsigned*)(lds + (bufoff) + ldsw + _i * 8192), 16, 0, 0); } while (0)
; #define PG8_LDA(dst, b, h) do { _Pragma("unroll") for (int m = 0; m < 4; ++m) _Pragma("unroll") for (int k = 0; k < 2; ++k) dst[m][k] = *(const PG8_LAS bf16x8*)(lds + PG8_SA(b, h) + aoff + m * 2048 + k * 1024); } while (0)
; #define PG8_LDB(dst, b, h) do { _Pragma("unroll") for (int n = 0; n < 2; ++n) _Pragma("unroll") for (int k = 0; k < 2; ++k) dst[n][k] = *(const PG8_LAS bf16x8*)(lds + PG8_SB(b, h) + boff + n * 2048 + k * 1024); } while (0)
; #define PG8_MMA(ai, bj, At, Bt) do { __builtin_amdgcn_s_setprio(1); _Pragma("unroll") for (int m = 0; m < 4; ++m) _Pragma("unroll") for (int n = 0; n < 2; ++n) _Pragma("unroll") for (int k = 0; k < 2; ++k) \
;         acc[ai][bj][m][n] = mma_<I8>(Bt[n][k], At[m][k], acc[ai][bj][m][n]); __builtin_amdgcn_s_setprio(0); } while (0)
; #define PG8_WAIT_V(n) asm volatile("s_waitcnt vmcnt(" #n ")" ::: "memory")
; #define PG8_WAIT_L(n) asm volatile("s_waitcnt lgkmcnt(" #n ")" ::: "memory")
; #define PG8_BAR __builtin_amdgcn_s_barrier()
; #define PG8_SCHED __builtin_amdgcn_sched_barrier(0)
; template <class Epi, class Sched, bool ALIGN_EPI = false, bool SP2 = false, bool I8 = false>
; __device__ __forceinline__ void gemm_phase(PG8_LAS unsigned char* lds, const Gemm g, const Sched& S, const Epi& E) {
;     ...
;         for (int t = 0; t < nt; t += 2) {
;             const bool last = (t == nt - 2);
;     ...
;             PG8_LDB(B0, 1, 0); PG8_LDB(B1, 1, 1); PG8_SCHED; PG8_LDA(At, 1, 0); PG8_STAGE(PG8_SA(0, 1), a2 + hstepA, voffA);
;             PG8_WAIT_V(8); PG8_WAIT_L(0); PG8_BAR; PG8_MMA(0, 0, At, B0); PG8_MMA(0, 1, At, B1); PG8_BAR; PG8_SCHED;
;             PG8_LDA(At, 1, 1); PG8_STAGE(PG8_SB(1, 0), b3, voffB); PG8_STAGE(PG8_SB(1, 1), b3 + hstepB, voffB); PG8_STAGE(PG8_SA(1, 0), a3, voffA);
;             PG8_WAIT_V(8); PG8_WAIT_L(0); PG8_BAR; PG8_MMA(1, 0, At, B0); PG8_MMA(1, 1, At, B1); PG8_BAR; PG8_SCHED;
	s_add_i32 s50, 0, 0x18000
	v_add_u32_e32 v157, s50, v1
	s_add_i32 s51, 0, 0x1c000
	ds_read_b128 v[146:149], v157
	ds_read_b128 v[150:153], v157 offset:1024
	ds_read_b128 v[158:161], v157 offset:2048
	ds_read_b128 v[162:165], v157 offset:3072
	v_add_u32_e32 v157, s51, v1
	ds_read_b128 v[166:169], v157
	ds_read_b128 v[170:173], v157 offset:1024
	ds_read_b128 v[174:177], v157 offset:2048
	ds_read_b128 v[178:181], v157 offset:3072
	s_add_u32 s26, s26, 0x20000
	s_addc_u32 s27, s27, 0
	s_mov_b32 m0, s36
	ds_read_b128 v[182:185], v156 offset:32768
	ds_read_b128 v[186:189], v156 offset:33792
	ds_read_b128 v[190:193], v156 offset:34816
	ds_read_b128 v[194:197], v156 offset:35840
	ds_read_b128 v[198:201], v156 offset:36864
	ds_read_b128 v[202:205], v156 offset:37888
	ds_read_b128 v[206:209], v156 offset:38912
	ds_read_b128 v[210:213], v156 offset:39936
	global_load_lds_dwordx4 v130, s[26:27]
	s_mov_b32 m0, s37
	s_nop 0
	global_load_lds_dwordx4 v134, s[26:27]
	s_waitcnt vmcnt(8)
	s_waitcnt lgkmcnt(0)
	s_barrier
	s_waitcnt lgkmcnt(0)
	v_mfma_f32_16x16x32_bf16 v[126:129], v[146:149], v[182:185], v[126:129]
	v_mfma_f32_16x16x32_bf16 v[122:125], v[158:161], v[182:185], v[122:125]
	v_mfma_f32_16x16x32_bf16 v[114:117], v[146:149], v[190:193], v[114:117]
	v_mfma_f32_16x16x32_bf16 v[106:109], v[158:161], v[190:193], v[106:109]
	v_mfma_f32_16x16x32_bf16 v[94:97], v[146:149], v[198:201], v[94:97]
	v_mfma_f32_16x16x32_bf16 v[90:93], v[158:161], v[198:201], v[90:93]
	v_mfma_f32_16x16x32_bf16 v[86:89], v[146:149], v[206:209], v[86:89]
	v_mfma_f32_16x16x32_bf16 v[82:85], v[158:161], v[206:209], v[82:85]
	v_mfma_f32_16x16x32_bf16 v[126:129], v[150:153], v[186:189], v[126:129]
	v_mfma_f32_16x16x32_bf16 v[122:125], v[162:165], v[186:189], v[122:125]
	v_mfma_f32_16x16x32_bf16 v[114:117], v[150:153], v[194:197], v[114:117]
	v_mfma_f32_16x16x32_bf16 v[106:109], v[162:165], v[194:197], v[106:109]
	v_mfma_f32_16x16x32_bf16 v[94:97], v[150:153], v[202:205], v[94:97]
	v_mfma_f32_16x16x32_bf16 v[90:93], v[162:165], v[202:205], v[90:93]
	v_mfma_f32_16x16x32_bf16 v[86:89], v[150:153], v[210:213], v[86:89]
	v_mfma_f32_16x16x32_bf16 v[82:85], v[162:165], v[210:213], v[82:85]
	v_mfma_f32_16x16x32_bf16 v[118:121], v[166:169], v[182:185], v[118:121]
	v_mfma_f32_16x16x32_bf16 v[110:113], v[174:177], v[182:185], v[110:113]
	v_mfma_f32_16x16x32_bf16 v[102:105], v[166:169], v[190:193], v[102:105]
	v_mfma_f32_16x16x32_bf16 v[98:101], v[174:177], v[190:193], v[98:101]
	v_mfma_f32_16x16x32_bf16 v[78:81], v[166:169], v[198:201], v[78:81]
	v_mfma_f32_16x16x32_bf16 v[74:77], v[174:177], v[198:201], v[74:77]
	v_mfma_f32_16x16x32_bf16 v[70:73], v[166:169], v[206:209], v[70:73]
	v_mfma_f32_16x16x32_bf16 v[66:69], v[174:177], v[206:209], v[66:69]
	v_mfma_f32_16x16x32_bf16 v[118:121], v[170:173], v[186:189], v[118:121]
	v_mfma_f32_16x16x32_bf16 v[110:113], v[178:181], v[186:189], v[110:113]
	v_mfma_f32_16x16x32_bf16 v[102:105], v[170:173], v[194:197], v[102:105]
	v_mfma_f32_16x16x32_bf16 v[98:101], v[178:181], v[194:197], v[98:101]
	v_mfma_f32_16x16x32_bf16 v[78:81], v[170:173], v[202:205], v[78:81]
	v_mfma_f32_16x16x32_bf16 v[74:77], v[178:181], v[202:205], v[74:77]
	v_mfma_f32_16x16x32_bf16 v[70:73], v[170:173], v[210:213], v[70:73]
	v_mfma_f32_16x16x32_bf16 v[66:69], v[178:181], v[210:213], v[66:69]
	s_barrier
	s_add_i32 s26, s50, s34
	v_lshl_add_u64 v[214:215], v[214:215], 0, s[8:9]
	s_mov_b32 m0, s26
	ds_read_b128 v[182:185], v156 offset:49152
	ds_read_b128 v[186:189], v156 offset:50176
	ds_read_b128 v[190:193], v156 offset:51200
	ds_read_b128 v[194:197], v156 offset:52224
	ds_read_b128 v[198:201], v156 offset:53248
	ds_read_b128 v[202:205], v156 offset:54272
	ds_read_b128 v[206:209], v156 offset:55296
	ds_read_b128 v[210:213], v156 offset:56320
	global_load_lds_dwordx4 v[214:215], off
	s_add_i32 m0, s26, 0x2000
	s_add_u32 s24, s24, 0x20080
	v_lshl_add_u64 v[214:215], v[216:217], 0, s[8:9]
	s_addc_u32 s25, s25, 0
	s_add_i32 s26, s51, s34
	global_load_lds_dwordx4 v[214:215], off
	s_mov_b32 m0, s26
	s_nop 0
	global_load_lds_dwordx4 v132, s[24:25]
	s_add_i32 m0, s26, 0x2000
	s_nop 0
	global_load_lds_dwordx4 v136, s[24:25]
	v_lshl_add_u64 v[214:215], v[218:219], 0, s[8:9]
	s_mov_b32 m0, s39
	s_nop 0
	global_load_lds_dwordx4 v[214:215], off
	v_lshl_add_u64 v[214:215], v[220:221], 0, s[8:9]
	s_mov_b32 m0, s40
	s_nop 0
	global_load_lds_dwordx4 v[214:215], off
	s_waitcnt vmcnt(8)
	s_waitcnt lgkmcnt(0)
	s_barrier
	s_waitcnt lgkmcnt(0)
	v_mfma_f32_16x16x32_bf16 v[62:65], v[146:149], v[182:185], v[62:65]
	v_mfma_f32_16x16x32_bf16 v[58:61], v[158:161], v[182:185], v[58:61]
	v_mfma_f32_16x16x32_bf16 v[54:57], v[146:149], v[190:193], v[54:57]
	v_mfma_f32_16x16x32_bf16 v[50:53], v[158:161], v[190:193], v[50:53]
	v_mfma_f32_16x16x32_bf16 v[30:33], v[146:149], v[198:201], v[30:33]
	v_mfma_f32_16x16x32_bf16 v[26:29], v[158:161], v[198:201], v[26:29]
	v_mfma_f32_16x16x32_bf16 v[22:25], v[146:149], v[206:209], v[22:25]
	v_mfma_f32_16x16x32_bf16 v[10:13], v[158:161], v[206:209], v[10:13]
	v_mfma_f32_16x16x32_bf16 v[62:65], v[150:153], v[186:189], v[62:65]
	v_mfma_f32_16x16x32_bf16 v[58:61], v[162:165], v[186:189], v[58:61]
	v_mfma_f32_16x16x32_bf16 v[54:57], v[150:153], v[194:197], v[54:57]
	v_mfma_f32_16x16x32_bf16 v[50:53], v[162:165], v[194:197], v[50:53]
	v_mfma_f32_16x16x32_bf16 v[30:33], v[150:153], v[202:205], v[30:33]
	v_mfma_f32_16x16x32_bf16 v[26:29], v[162:165], v[202:205], v[26:29]
	v_mfma_f32_16x16x32_bf16 v[22:25], v[150:153], v[210:213], v[22:25]
	v_mfma_f32_16x16x32_bf16 v[10:13], v[162:165], v[210:213], v[10:13]
	v_mfma_f32_16x16x32_bf16 v[46:49], v[166:169], v[182:185], v[46:49]
	v_mfma_f32_16x16x32_bf16 v[42:45], v[174:177], v[182:185], v[42:45]
	v_mfma_f32_16x16x32_bf16 v[38:41], v[166:169], v[190:193], v[38:41]
	v_mfma_f32_16x16x32_bf16 v[34:37], v[174:177], v[190:193], v[34:37]
	v_mfma_f32_16x16x32_bf16 v[18:21], v[166:169], v[198:201], v[18:21]
	v_mfma_f32_16x16x32_bf16 v[14:17], v[174:177], v[198:201], v[14:17]
	v_mfma_f32_16x16x32_bf16 v[6:9], v[166:169], v[206:209], v[6:9]
	v_mfma_f32_16x16x32_bf16 v[2:5], v[174:177], v[206:209], v[2:5]
	v_mfma_f32_16x16x32_bf16 v[46:49], v[170:173], v[186:189], v[46:49]
	v_mfma_f32_16x16x32_bf16 v[42:45], v[178:181], v[186:189], v[42:45]
	v_mfma_f32_16x16x32_bf16 v[38:41], v[170:173], v[194:197], v[38:41]
	v_mfma_f32_16x16x32_bf16 v[34:37], v[178:181], v[194:197], v[34:37]
	v_mfma_f32_16x16x32_bf16 v[18:21], v[170:173], v[202:205], v[18:21]
	v_mfma_f32_16x16x32_bf16 v[14:17], v[178:181], v[202:205], v[14:17]
	v_mfma_f32_16x16x32_bf16 v[6:9], v[170:173], v[210:213], v[6:9]
	v_mfma_f32_16x16x32_bf16 v[2:5], v[178:181], v[210:213], v[2:5]
	s_barrier
	s_add_i32 s49, s49, 2
	s_add_u32 s22, s22, 0x100
	s_addc_u32 s23, s23, 0
	s_add_u32 s47, s47, 0x100
	s_addc_u32 s48, s48, 0
	s_cmp_gt_u32 s49, 5
	s_cbranch_scc0 .LBB0_1538
	s_and_b64 vcc, exec, s[10:11]
	s_cbranch_vccz .LBB0_1541
	s_barrier

; #define PG8_STAGE(bufoff, gbase, voff) do { _Pragma("unroll") for (int _i = 0; _i < 2; ++_i) \
;         __builtin_amdgcn_global_load_lds((const unsigned*)((const char*)(gbase) + (voff)[_i]), (PG8_LAS unsigned*)(lds + (bufoff) + ldsw + _i * 8192), 16, 0, 0); } while (0)
; #define PG8_LDA(dst, b, h) do { _Pragma("unroll") for (int m = 0; m < 4; ++m) _Pragma("unroll") for (int k = 0; k < 2; ++k) dst[m][k] = *(const PG8_LAS bf16x8*)(lds + PG8_SA(b, h) + aoff + m * 2048 + k * 1024); } while (0)
; #define PG8_LDB(dst, b, h) do { _Pragma("unroll") for (int n = 0; n < 2; ++n) _Pragma("unroll") for (int k = 0; k < 2; ++k) dst[n][k] = *(const PG8_LAS bf16x8*)(lds + PG8_SB(b, h) + boff + n * 2048 + k * 1024); } while (0)
; #define PG8_MMA(ai, bj, At, Bt) do { __builtin_amdgcn_s_setprio(1); _Pragma("unroll") for (int m = 0; m < 4; ++m) _Pragma("unroll") for (int n = 0; n < 2; ++n) _Pragma("unroll") for (int k = 0; k < 2; ++k) \
;         acc[ai][bj][m][n] = mma_<I8>(Bt[n][k], At[m][k], acc[ai][bj][m][n]); __builtin_amdgcn_s_setprio(0); } while (0)
; #define PG8_WAIT_V(n) asm volatile("s_waitcnt vmcnt(" #n ")" ::: "memory")
; #define PG8_WAIT_L(n) asm volatile("s_waitcnt lgkmcnt(" #n ")" ::: "memory")
; #define PG8_BAR __builtin_amdgcn_s_barrier()
; #define PG8_SCHED __builtin_amdgcn_sched_barrier(0)
; template <class Epi, class Sched, bool ALIGN_EPI = false, bool SP2 = false, bool I8 = false>
; __device__ __forceinline__ void gemm_phase(PG8_LAS unsigned char* lds, const Gemm g, const Sched& S, const Epi& E) {
;     ...
;             const char* a1 = cA + (size_t)(t + 1) * kstep;
;             const char* a2 = last ? nA : cA + (size_t)(t + 2) * kstep; const char* b2 = last ? nB : cB + (size_t)(t + 2) * kstep;
;             const char* a3 = a2 + kstep; const char* b3 = b2 + kstep;
;             if (last && has_next) S.a_ready(nxt);
;             if constexpr (SP2) {
;             PG8_LDB(B0, 0, 0); PG8_LDB(B1, 0, 1); PG8_SCHED; PG8_LDA(At, 0, 0); PG8_STAGE(PG8_SA(1, 1), a1 + hstepA, voffA);
;             PG8_WAIT_V(8); PG8_WAIT_L(0); PG8_BAR; PG8_MMA(0, 0, At, B0); PG8_MMA(0, 1, At, B1); PG8_BAR; PG8_SCHED;
;             PG8_LDA(At, 0, 1); PG8_STAGE(PG8_SB(0, 0), b2, voffB); PG8_STAGE(PG8_SB(0, 1), b2 + hstepB, voffB); PG8_STAGE(PG8_SA(0, 0), a2, voffA);
;             PG8_WAIT_V(8); PG8_WAIT_L(0); PG8_BAR; PG8_MMA(1, 0, At, B0); PG8_MMA(1, 1, At, B1); PG8_BAR; PG8_SCHED;
.LBB0_1565:
	ds_read_b128 v[130:133], v176
	ds_read_b128 v[134:137], v176 offset:1024
	ds_read_b128 v[138:141], v176 offset:2048
	ds_read_b128 v[142:145], v176 offset:3072
	ds_read_b128 v[162:165], v177
	ds_read_b128 v[166:169], v177 offset:1024
	ds_read_b128 v[170:173], v177 offset:2048
	ds_read_b128 v[180:183], v177 offset:3072
	s_add_u32 s30, s28, 0xfff80080
	s_addc_u32 s31, s29, -1
	s_cmp_eq_u32 s54, 28
	s_cselect_b32 s35, s7, s31
	s_cselect_b32 s34, s21, s30
	s_cselect_b32 s31, s19, s53
	s_cselect_b32 s30, s27, s52
	s_add_i32 m0, s40, 0xc000
	ds_read_b128 v[184:187], v178
	ds_read_b128 v[188:191], v178 offset:1024
	ds_read_b128 v[192:195], v178 offset:2048
	ds_read_b128 v[196:199], v178 offset:3072
	ds_read_b128 v[200:203], v178 offset:4096
	ds_read_b128 v[204:207], v178 offset:5120
	ds_read_b128 v[208:211], v178 offset:6144
	ds_read_b128 v[212:215], v178 offset:7168
	global_load_lds_dwordx4 v154, s[28:29]
	s_add_i32 m0, s40, 0xe000
	s_nop 0
	global_load_lds_dwordx4 v156, s[28:29]
	s_waitcnt vmcnt(8)
	s_waitcnt lgkmcnt(0)
	s_barrier
	s_waitcnt lgkmcnt(0)
	v_mfma_f32_16x16x32_bf16 v[126:129], v[130:133], v[184:187], v[126:129]
	v_mfma_f32_16x16x32_bf16 v[122:125], v[138:141], v[184:187], v[122:125]
	v_mfma_f32_16x16x32_bf16 v[110:113], v[130:133], v[192:195], v[110:113]
	v_mfma_f32_16x16x32_bf16 v[106:109], v[138:141], v[192:195], v[106:109]
	v_mfma_f32_16x16x32_bf16 v[94:97], v[130:133], v[200:203], v[94:97]
	v_mfma_f32_16x16x32_bf16 v[90:93], v[138:141], v[200:203], v[90:93]
	v_mfma_f32_16x16x32_bf16 v[78:81], v[130:133], v[208:211], v[78:81]
	v_mfma_f32_16x16x32_bf16 v[74:77], v[138:141], v[208:211], v[74:77]
	v_mfma_f32_16x16x32_bf16 v[126:129], v[134:137], v[188:191], v[126:129]
	v_mfma_f32_16x16x32_bf16 v[122:125], v[142:145], v[188:191], v[122:125]
	v_mfma_f32_16x16x32_bf16 v[110:113], v[134:137], v[196:199], v[110:113]
	v_mfma_f32_16x16x32_bf16 v[106:109], v[142:145], v[196:199], v[106:109]
	v_mfma_f32_16x16x32_bf16 v[94:97], v[134:137], v[204:207], v[94:97]
	v_mfma_f32_16x16x32_bf16 v[90:93], v[142:145], v[204:207], v[90:93]
	v_mfma_f32_16x16x32_bf16 v[78:81], v[134:137], v[212:215], v[78:81]
	v_mfma_f32_16x16x32_bf16 v[74:77], v[142:145], v[212:215], v[74:77]
	v_mfma_f32_16x16x32_bf16 v[118:121], v[162:165], v[184:187], v[118:121]
	v_mfma_f32_16x16x32_bf16 v[114:117], v[170:173], v[184:187], v[114:117]
	v_mfma_f32_16x16x32_bf16 v[102:105], v[162:165], v[192:195], v[102:105]
	v_mfma_f32_16x16x32_bf16 v[98:101], v[170:173], v[192:195], v[98:101]
	v_mfma_f32_16x16x32_bf16 v[86:89], v[162:165], v[200:203], v[86:89]
	v_mfma_f32_16x16x32_bf16 v[82:85], v[170:173], v[200:203], v[82:85]
	v_mfma_f32_16x16x32_bf16 v[70:73], v[162:165], v[208:211], v[70:73]
	v_mfma_f32_16x16x32_bf16 v[66:69], v[170:173], v[208:211], v[66:69]
	v_mfma_f32_16x16x32_bf16 v[118:121], v[166:169], v[188:191], v[118:121]
	v_mfma_f32_16x16x32_bf16 v[114:117], v[180:183], v[188:191], v[114:117]
	v_mfma_f32_16x16x32_bf16 v[102:105], v[166:169], v[196:199], v[102:105]
	v_mfma_f32_16x16x32_bf16 v[98:101], v[180:183], v[196:199], v[98:101]
	v_mfma_f32_16x16x32_bf16 v[86:89], v[166:169], v[204:207], v[86:89]
	v_mfma_f32_16x16x32_bf16 v[82:85], v[180:183], v[204:207], v[82:85]
	v_mfma_f32_16x16x32_bf16 v[70:73], v[166:169], v[212:215], v[70:73]
	v_mfma_f32_16x16x32_bf16 v[66:69], v[180:183], v[212:215], v[66:69]
	s_barrier
	s_add_i32 s55, s50, s39
	v_lshl_add_u64 v[174:175], s[30:31], 0, v[148:149]
	s_mov_b32 m0, s55
	ds_read_b128 v[184:187], v178 offset:16384
	ds_read_b128 v[188:191], v178 offset:17408
	ds_read_b128 v[192:195], v178 offset:18432
	ds_read_b128 v[196:199], v178 offset:19456
	ds_read_b128 v[200:203], v178 offset:20480
	ds_read_b128 v[204:207], v178 offset:21504
	ds_read_b128 v[208:211], v178 offset:22528
	ds_read_b128 v[212:215], v178 offset:23552
	global_load_lds_dwordx4 v148, s[30:31]
	s_add_i32 m0, s55, 0x2000
	s_add_u32 s56, s30, 0x80000
	v_lshl_add_u64 v[216:217], s[30:31], 0, v[152:153]
	s_addc_u32 s57, s31, 0
	s_add_i32 s55, s51, s39
	global_load_lds_dwordx4 v152, s[30:31]
	s_mov_b32 m0, s55
	v_lshl_add_u64 v[220:221], s[34:35], 0, v[150:151]
	global_load_lds_dwordx4 v148, s[56:57]
	s_add_i32 m0, s55, 0x2000
	s_nop 0
	global_load_lds_dwordx4 v152, s[56:57]
	v_lshl_add_u64 v[218:219], s[34:35], 0, v[146:147]
	s_mov_b32 m0, s40
	s_nop 0
	global_load_lds_dwordx4 v146, s[34:35]
	s_mov_b32 m0, s41
	s_nop 0
	global_load_lds_dwordx4 v150, s[34:35]
	s_waitcnt vmcnt(8)
	s_waitcnt lgkmcnt(0)
	s_barrier
	s_waitcnt lgkmcnt(0)
	v_mfma_f32_16x16x32_bf16 v[62:65], v[130:133], v[184:187], v[62:65]
	v_mfma_f32_16x16x32_bf16 v[58:61], v[138:141], v[184:187], v[58:61]
	v_mfma_f32_16x16x32_bf16 v[46:49], v[130:133], v[192:195], v[46:49]
	v_mfma_f32_16x16x32_bf16 v[42:45], v[138:141], v[192:195], v[42:45]
	v_mfma_f32_16x16x32_bf16 v[30:33], v[130:133], v[200:203], v[30:33]
	v_mfma_f32_16x16x32_bf16 v[26:29], v[138:141], v[200:203], v[26:29]
	v_mfma_f32_16x16x32_bf16 v[14:17], v[130:133], v[208:211], v[14:17]
	v_mfma_f32_16x16x32_bf16 v[10:13], v[138:141], v[208:211], v[10:13]
	v_mfma_f32_16x16x32_bf16 v[62:65], v[134:137], v[188:191], v[62:65]
	v_mfma_f32_16x16x32_bf16 v[58:61], v[142:145], v[188:191], v[58:61]
	v_mfma_f32_16x16x32_bf16 v[46:49], v[134:137], v[196:199], v[46:49]
	v_mfma_f32_16x16x32_bf16 v[42:45], v[142:145], v[196:199], v[42:45]
	v_mfma_f32_16x16x32_bf16 v[30:33], v[134:137], v[204:207], v[30:33]
	v_mfma_f32_16x16x32_bf16 v[26:29], v[142:145], v[204:207], v[26:29]
	v_mfma_f32_16x16x32_bf16 v[14:17], v[134:137], v[212:215], v[14:17]
	v_mfma_f32_16x16x32_bf16 v[10:13], v[142:145], v[212:215], v[10:13]
	v_mfma_f32_16x16x32_bf16 v[54:57], v[162:165], v[184:187], v[54:57]
	v_mfma_f32_16x16x32_bf16 v[50:53], v[170:173], v[184:187], v[50:53]
	v_mfma_f32_16x16x32_bf16 v[38:41], v[162:165], v[192:195], v[38:41]
	v_mfma_f32_16x16x32_bf16 v[34:37], v[170:173], v[192:195], v[34:37]
	v_mfma_f32_16x16x32_bf16 v[22:25], v[162:165], v[200:203], v[22:25]
	v_mfma_f32_16x16x32_bf16 v[18:21], v[170:173], v[200:203], v[18:21]
	v_mfma_f32_16x16x32_bf16 v[6:9], v[162:165], v[208:211], v[6:9]
	v_mfma_f32_16x16x32_bf16 v[2:5], v[170:173], v[208:211], v[2:5]
	v_mfma_f32_16x16x32_bf16 v[54:57], v[166:169], v[188:191], v[54:57]
	v_mfma_f32_16x16x32_bf16 v[50:53], v[180:183], v[188:191], v[50:53]
	v_mfma_f32_16x16x32_bf16 v[38:41], v[166:169], v[196:199], v[38:41]
	v_mfma_f32_16x16x32_bf16 v[34:37], v[180:183], v[196:199], v[34:37]
	v_mfma_f32_16x16x32_bf16 v[22:25], v[166:169], v[204:207], v[22:25]
	v_mfma_f32_16x16x32_bf16 v[18:21], v[180:183], v[204:207], v[18:21]
	v_mfma_f32_16x16x32_bf16 v[6:9], v[166:169], v[212:215], v[6:9]
	v_mfma_f32_16x16x32_bf16 v[2:5], v[180:183], v[212:215], v[2:5]
	s_barrier
; #define PG8_STAGE(bufoff, gbase, voff) do { _Pragma("unroll") for (int _i = 0; _i < 2; ++_i) \
;         __builtin_amdgcn_global_load_lds((const unsigned*)((const char*)(gbase) + (voff)[_i]), (PG8_LAS unsigned*)(lds + (bufoff) + ldsw + _i * 8192), 16, 0, 0); } while (0)
; #define PG8_LDA(dst, b, h) do { _Pragma("unroll") for (int m = 0; m < 4; ++m) _Pragma("unroll") for (int k = 0; k < 2; ++k) dst[m][k] = *(const PG8_LAS bf16x8*)(lds + PG8_SA(b, h) + aoff + m * 2048 + k * 1024); } while (0)
; #define PG8_LDB(dst, b, h) do { _Pragma("unroll") for (int n = 0; n < 2; ++n) _Pragma("unroll") for (int k = 0; k < 2; ++k) dst[n][k] = *(const PG8_LAS bf16x8*)(lds + PG8_SB(b, h) + boff + n * 2048 + k * 1024); } while (0)
; #define PG8_MMA(ai, bj, At, Bt) do { __builtin_amdgcn_s_setprio(1); _Pragma("unroll") for (int m = 0; m < 4; ++m) _Pragma("unroll") for (int n = 0; n < 2; ++n) _Pragma("unroll") for (int k = 0; k < 2; ++k) \
;         acc[ai][bj][m][n] = mma_<I8>(Bt[n][k], At[m][k], acc[ai][bj][m][n]); __builtin_amdgcn_s_setprio(0); } while (0)
; #define PG8_WAIT_V(n) asm volatile("s_waitcnt vmcnt(" #n ")" ::: "memory")
; #define PG8_WAIT_L(n) asm volatile("s_waitcnt lgkmcnt(" #n ")" ::: "memory")
; #define PG8_BAR __builtin_amdgcn_s_barrier()
; #define PG8_SCHED __builtin_amdgcn_sched_barrier(0)
; template <class Epi, class Sched, bool ALIGN_EPI = false, bool SP2 = false, bool I8 = false>
; __device__ __forceinline__ void gemm_phase(PG8_LAS unsigned char* lds, const Gemm g, const Sched& S, const Epi& E) {
;     ...
;         for (int t = 0; t < nt; t += 2) {
;             const bool last = (t == nt - 2);
;     ...
;             PG8_LDB(B0, 1, 0); PG8_LDB(B1, 1, 1); PG8_SCHED; PG8_LDA(At, 1, 0); PG8_STAGE(PG8_SA(0, 1), a2 + hstepA, voffA);
;             PG8_WAIT_V(8); PG8_WAIT_L(0); PG8_BAR; PG8_MMA(0, 0, At, B0); PG8_MMA(0, 1, At, B1); PG8_BAR; PG8_SCHED;
;             PG8_LDA(At, 1, 1); PG8_STAGE(PG8_SB(1, 0), b3, voffB); PG8_STAGE(PG8_SB(1, 1), b3 + hstepB, voffB); PG8_STAGE(PG8_SA(1, 0), a3, voffA);
;             PG8_WAIT_V(8); PG8_WAIT_L(0); PG8_BAR; PG8_MMA(1, 0, At, B0); PG8_MMA(1, 1, At, B1); PG8_BAR; PG8_SCHED;
	s_add_i32 s55, 0, 0x18000
	s_add_i32 s56, 0, 0x1c000
	v_add_u32_e32 v142, s55, v1
	v_add_u32_e32 v180, s56, v1
	ds_read_b128 v[130:133], v142
	ds_read_b128 v[134:137], v142 offset:1024
	ds_read_b128 v[138:141], v142 offset:2048
	ds_read_b128 v[142:145], v142 offset:3072
	ds_read_b128 v[162:165], v180
	ds_read_b128 v[166:169], v180 offset:1024
	ds_read_b128 v[170:173], v180 offset:2048
	ds_read_b128 v[180:183], v180 offset:3072
	s_add_u32 s34, s34, 0x80000
	s_addc_u32 s35, s35, 0
	s_mov_b32 m0, s42
	ds_read_b128 v[184:187], v178 offset:32768
	ds_read_b128 v[188:191], v178 offset:33792
	ds_read_b128 v[192:195], v178 offset:34816
	ds_read_b128 v[196:199], v178 offset:35840
	ds_read_b128 v[200:203], v178 offset:36864
	ds_read_b128 v[204:207], v178 offset:37888
	ds_read_b128 v[208:211], v178 offset:38912
	ds_read_b128 v[212:215], v178 offset:39936
	global_load_lds_dwordx4 v146, s[34:35]
	s_mov_b32 m0, s43
	s_nop 0
	global_load_lds_dwordx4 v150, s[34:35]
	s_waitcnt vmcnt(8)
	s_waitcnt lgkmcnt(0)
	s_barrier
	s_waitcnt lgkmcnt(0)
	v_mfma_f32_16x16x32_bf16 v[126:129], v[130:133], v[184:187], v[126:129]
	v_mfma_f32_16x16x32_bf16 v[122:125], v[138:141], v[184:187], v[122:125]
	v_mfma_f32_16x16x32_bf16 v[110:113], v[130:133], v[192:195], v[110:113]
	v_mfma_f32_16x16x32_bf16 v[106:109], v[138:141], v[192:195], v[106:109]
	v_mfma_f32_16x16x32_bf16 v[94:97], v[130:133], v[200:203], v[94:97]
	v_mfma_f32_16x16x32_bf16 v[90:93], v[138:141], v[200:203], v[90:93]
	v_mfma_f32_16x16x32_bf16 v[78:81], v[130:133], v[208:211], v[78:81]
	v_mfma_f32_16x16x32_bf16 v[74:77], v[138:141], v[208:211], v[74:77]
	v_mfma_f32_16x16x32_bf16 v[126:129], v[134:137], v[188:191], v[126:129]
	v_mfma_f32_16x16x32_bf16 v[122:125], v[142:145], v[188:191], v[122:125]
	v_mfma_f32_16x16x32_bf16 v[110:113], v[134:137], v[196:199], v[110:113]
	v_mfma_f32_16x16x32_bf16 v[106:109], v[142:145], v[196:199], v[106:109]
	v_mfma_f32_16x16x32_bf16 v[94:97], v[134:137], v[204:207], v[94:97]
	v_mfma_f32_16x16x32_bf16 v[90:93], v[142:145], v[204:207], v[90:93]
	v_mfma_f32_16x16x32_bf16 v[78:81], v[134:137], v[212:215], v[78:81]
	v_mfma_f32_16x16x32_bf16 v[74:77], v[142:145], v[212:215], v[74:77]
	v_mfma_f32_16x16x32_bf16 v[118:121], v[162:165], v[184:187], v[118:121]
	v_mfma_f32_16x16x32_bf16 v[114:117], v[170:173], v[184:187], v[114:117]
	v_mfma_f32_16x16x32_bf16 v[102:105], v[162:165], v[192:195], v[102:105]
	v_mfma_f32_16x16x32_bf16 v[98:101], v[170:173], v[192:195], v[98:101]
	v_mfma_f32_16x16x32_bf16 v[86:89], v[162:165], v[200:203], v[86:89]
	v_mfma_f32_16x16x32_bf16 v[82:85], v[170:173], v[200:203], v[82:85]
	v_mfma_f32_16x16x32_bf16 v[70:73], v[162:165], v[208:211], v[70:73]
	v_mfma_f32_16x16x32_bf16 v[66:69], v[170:173], v[208:211], v[66:69]
	v_mfma_f32_16x16x32_bf16 v[118:121], v[166:169], v[188:191], v[118:121]
	v_mfma_f32_16x16x32_bf16 v[114:117], v[180:183], v[188:191], v[114:117]
	v_mfma_f32_16x16x32_bf16 v[102:105], v[166:169], v[196:199], v[102:105]
	v_mfma_f32_16x16x32_bf16 v[98:101], v[180:183], v[196:199], v[98:101]
	v_mfma_f32_16x16x32_bf16 v[86:89], v[166:169], v[204:207], v[86:89]
	v_mfma_f32_16x16x32_bf16 v[82:85], v[180:183], v[204:207], v[82:85]
	v_mfma_f32_16x16x32_bf16 v[70:73], v[166:169], v[212:215], v[70:73]
	v_mfma_f32_16x16x32_bf16 v[66:69], v[180:183], v[212:215], v[66:69]
	s_barrier
	s_add_i32 s34, s55, s39
	v_lshl_add_u64 v[174:175], v[174:175], 0, s[14:15]
	s_mov_b32 m0, s34
	ds_read_b128 v[184:187], v178 offset:49152
	ds_read_b128 v[188:191], v178 offset:50176
	ds_read_b128 v[192:195], v178 offset:51200
	ds_read_b128 v[196:199], v178 offset:52224
	ds_read_b128 v[200:203], v178 offset:53248
	ds_read_b128 v[204:207], v178 offset:54272
	ds_read_b128 v[208:211], v178 offset:55296
	ds_read_b128 v[212:215], v178 offset:56320
	global_load_lds_dwordx4 v[174:175], off
	s_add_i32 m0, s34, 0x2000
	s_add_u32 s30, s30, 0x80080
	v_lshl_add_u64 v[174:175], v[216:217], 0, s[14:15]
	s_addc_u32 s31, s31, 0
	s_add_i32 s34, s56, s39
	global_load_lds_dwordx4 v[174:175], off
	s_mov_b32 m0, s34
	s_nop 0
	global_load_lds_dwordx4 v148, s[30:31]
	s_add_i32 m0, s34, 0x2000
	s_nop 0
	global_load_lds_dwordx4 v152, s[30:31]
	v_lshl_add_u64 v[174:175], v[218:219], 0, s[14:15]
	s_mov_b32 m0, s46
	s_nop 0
	global_load_lds_dwordx4 v[174:175], off
	v_lshl_add_u64 v[174:175], v[220:221], 0, s[14:15]
	s_mov_b32 m0, s47
	s_nop 0
	global_load_lds_dwordx4 v[174:175], off
	s_waitcnt vmcnt(8)
	s_waitcnt lgkmcnt(0)
	s_barrier
	s_waitcnt lgkmcnt(0)
	v_mfma_f32_16x16x32_bf16 v[62:65], v[130:133], v[184:187], v[62:65]
	v_mfma_f32_16x16x32_bf16 v[58:61], v[138:141], v[184:187], v[58:61]
	v_mfma_f32_16x16x32_bf16 v[46:49], v[130:133], v[192:195], v[46:49]
	v_mfma_f32_16x16x32_bf16 v[42:45], v[138:141], v[192:195], v[42:45]
	v_mfma_f32_16x16x32_bf16 v[30:33], v[130:133], v[200:203], v[30:33]
	v_mfma_f32_16x16x32_bf16 v[26:29], v[138:141], v[200:203], v[26:29]
	v_mfma_f32_16x16x32_bf16 v[14:17], v[130:133], v[208:211], v[14:17]
	v_mfma_f32_16x16x32_bf16 v[10:13], v[138:141], v[208:211], v[10:13]
	v_mfma_f32_16x16x32_bf16 v[62:65], v[134:137], v[188:191], v[62:65]
	v_mfma_f32_16x16x32_bf16 v[58:61], v[142:145], v[188:191], v[58:61]
	v_mfma_f32_16x16x32_bf16 v[46:49], v[134:137], v[196:199], v[46:49]
	v_mfma_f32_16x16x32_bf16 v[42:45], v[142:145], v[196:199], v[42:45]
	v_mfma_f32_16x16x32_bf16 v[30:33], v[134:137], v[204:207], v[30:33]
	v_mfma_f32_16x16x32_bf16 v[26:29], v[142:145], v[204:207], v[26:29]
	v_mfma_f32_16x16x32_bf16 v[14:17], v[134:137], v[212:215], v[14:17]
	v_mfma_f32_16x16x32_bf16 v[10:13], v[142:145], v[212:215], v[10:13]
	v_mfma_f32_16x16x32_bf16 v[54:57], v[162:165], v[184:187], v[54:57]
	v_mfma_f32_16x16x32_bf16 v[50:53], v[170:173], v[184:187], v[50:53]
	v_mfma_f32_16x16x32_bf16 v[38:41], v[162:165], v[192:195], v[38:41]
	v_mfma_f32_16x16x32_bf16 v[34:37], v[170:173], v[192:195], v[34:37]
	v_mfma_f32_16x16x32_bf16 v[22:25], v[162:165], v[200:203], v[22:25]
	v_mfma_f32_16x16x32_bf16 v[18:21], v[170:173], v[200:203], v[18:21]
	v_mfma_f32_16x16x32_bf16 v[6:9], v[162:165], v[208:211], v[6:9]
	v_mfma_f32_16x16x32_bf16 v[2:5], v[170:173], v[208:211], v[2:5]
	v_mfma_f32_16x16x32_bf16 v[54:57], v[166:169], v[188:191], v[54:57]
	v_mfma_f32_16x16x32_bf16 v[50:53], v[180:183], v[188:191], v[50:53]
	v_mfma_f32_16x16x32_bf16 v[38:41], v[166:169], v[196:199], v[38:41]
	v_mfma_f32_16x16x32_bf16 v[34:37], v[180:183], v[196:199], v[34:37]
	v_mfma_f32_16x16x32_bf16 v[22:25], v[166:169], v[204:207], v[22:25]
	v_mfma_f32_16x16x32_bf16 v[18:21], v[180:183], v[204:207], v[18:21]
	v_mfma_f32_16x16x32_bf16 v[6:9], v[166:169], v[212:215], v[6:9]
	v_mfma_f32_16x16x32_bf16 v[2:5], v[180:183], v[212:215], v[2:5]
	s_barrier
	s_add_i32 s54, s54, 2
	s_add_u32 s28, s28, 0x100
	s_addc_u32 s29, s29, 0
	s_add_u32 s52, s52, 0x100
	s_addc_u32 s53, s53, 0
	s_cmp_gt_u32 s54, 29
	s_cbranch_scc0 .LBB0_1565
	s_and_b64 vcc, exec, s[16:17]
	s_cbranch_vccz .LBB0_1568
	s_barrier

; #define PG8_STAGE(bufoff, gbase, voff) do { _Pragma("unroll") for (int _i = 0; _i < 2; ++_i) \
;         __builtin_amdgcn_global_load_lds((const unsigned*)((const char*)(gbase) + (voff)[_i]), (PG8_LAS unsigned*)(lds + (bufoff) + ldsw + _i * 8192), 16, 0, 0); } while (0)
; #define PG8_LDA(dst, b, h) do { _Pragma("unroll") for (int m = 0; m < 4; ++m) _Pragma("unroll") for (int k = 0; k < 2; ++k) dst[m][k] = *(const PG8_LAS bf16x8*)(lds + PG8_SA(b, h) + aoff + m * 2048 + k * 1024); } while (0)
; #define PG8_LDB(dst, b, h) do { _Pragma("unroll") for (int n = 0; n < 2; ++n) _Pragma("unroll") for (int k = 0; k < 2; ++k) dst[n][k] = *(const PG8_LAS bf16x8*)(lds + PG8_SB(b, h) + boff + n * 2048 + k * 1024); } while (0)
; #define PG8_MMA(ai, bj, At, Bt) do { __builtin_amdgcn_s_setprio(1); _Pragma("unroll") for (int m = 0; m < 4; ++m) _Pragma("unroll") for (int n = 0; n < 2; ++n) _Pragma("unroll") for (int k = 0; k < 2; ++k) \
;         acc[ai][bj][m][n] = mma_<I8>(Bt[n][k], At[m][k], acc[ai][bj][m][n]); __builtin_amdgcn_s_setprio(0); } while (0)
; #define PG8_WAIT_V(n) asm volatile("s_waitcnt vmcnt(" #n ")" ::: "memory")
; #define PG8_WAIT_L(n) asm volatile("s_waitcnt lgkmcnt(" #n ")" ::: "memory")
; #define PG8_BAR __builtin_amdgcn_s_barrier()
; #define PG8_SCHED __builtin_amdgcn_sched_barrier(0)
; template <class Epi, class Sched, bool ALIGN_EPI = false, bool SP2 = false, bool I8 = false>
; __device__ __forceinline__ void gemm_phase(PG8_LAS unsigned char* lds, const Gemm g, const Sched& S, const Epi& E) {
;     ...
;             const char* a1 = cA + (size_t)(t + 1) * kstep;
;             const char* a2 = last ? nA : cA + (size_t)(t + 2) * kstep; const char* b2 = last ? nB : cB + (size_t)(t + 2) * kstep;
;             const char* a3 = a2 + kstep; const char* b3 = b2 + kstep;
;             if (last && has_next) S.a_ready(nxt);
;             if constexpr (SP2) {
;             PG8_LDB(B0, 0, 0); PG8_LDB(B1, 0, 1); PG8_SCHED; PG8_LDA(At, 0, 0); PG8_STAGE(PG8_SA(1, 1), a1 + hstepA, voffA);
;             PG8_WAIT_V(8); PG8_WAIT_L(0); PG8_BAR; PG8_MMA(0, 0, At, B0); PG8_MMA(0, 1, At, B1); PG8_BAR; PG8_SCHED;
;             PG8_LDA(At, 0, 1); PG8_STAGE(PG8_SB(0, 0), b2, voffB); PG8_STAGE(PG8_SB(0, 1), b2 + hstepB, voffB); PG8_STAGE(PG8_SA(0, 0), a2, voffA);
;             PG8_WAIT_V(8); PG8_WAIT_L(0); PG8_BAR; PG8_MMA(1, 0, At, B0); PG8_MMA(1, 1, At, B1); PG8_BAR; PG8_SCHED;
.LBB0_1721:
	ds_read_b128 v[34:37], v233
	ds_read_b128 v[38:41], v233 offset:1024
	ds_read_b128 v[42:45], v233 offset:2048
	ds_read_b128 v[62:65], v233 offset:3072
	ds_read_b128 v[146:149], v234
	ds_read_b128 v[150:153], v234 offset:1024
	ds_read_b128 v[154:157], v234 offset:2048
	ds_read_b128 v[158:161], v234 offset:3072
	s_add_u32 s34, s8, 0xfff80080
	s_addc_u32 s35, s9, -1
	s_cmp_eq_u32 s55, 28
	s_cselect_b32 s37, s3, s35
	s_cselect_b32 s36, s7, s34
	s_cselect_b32 s35, s25, s54
	s_cselect_b32 s34, s27, s33
	s_add_i32 m0, s43, 0xc000
	ds_read_b128 v[162:165], v235
	ds_read_b128 v[166:169], v235 offset:1024
	ds_read_b128 v[170:173], v235 offset:2048
	ds_read_b128 v[186:189], v235 offset:3072
	ds_read_b128 v[190:193], v235 offset:4096
	ds_read_b128 v[194:197], v235 offset:5120
	ds_read_b128 v[198:201], v235 offset:6144
	ds_read_b128 v[202:205], v235 offset:7168
	global_load_lds_dwordx4 v178, s[8:9]
	s_add_i32 m0, s43, 0xe000
	s_nop 0
	global_load_lds_dwordx4 v180, s[8:9]
	s_waitcnt vmcnt(8)
	s_waitcnt lgkmcnt(0)
	s_barrier
	s_waitcnt lgkmcnt(0)
	v_mfma_i32_16x16x64_i8 v[142:145], v[34:37], v[162:165], v[142:145]
	v_mfma_i32_16x16x64_i8 v[138:141], v[42:45], v[162:165], v[138:141]
	v_mfma_i32_16x16x64_i8 v[126:129], v[34:37], v[170:173], v[126:129]
	v_mfma_i32_16x16x64_i8 v[122:125], v[42:45], v[170:173], v[122:125]
	v_mfma_i32_16x16x64_i8 v[110:113], v[34:37], v[190:193], v[110:113]
	v_mfma_i32_16x16x64_i8 v[106:109], v[42:45], v[190:193], v[106:109]
	v_mfma_i32_16x16x64_i8 v[94:97], v[34:37], v[198:201], v[94:97]
	v_mfma_i32_16x16x64_i8 v[90:93], v[42:45], v[198:201], v[90:93]
	v_mfma_i32_16x16x64_i8 v[142:145], v[38:41], v[166:169], v[142:145]
	v_mfma_i32_16x16x64_i8 v[138:141], v[62:65], v[166:169], v[138:141]
	v_mfma_i32_16x16x64_i8 v[126:129], v[38:41], v[186:189], v[126:129]
	v_mfma_i32_16x16x64_i8 v[122:125], v[62:65], v[186:189], v[122:125]
	v_mfma_i32_16x16x64_i8 v[110:113], v[38:41], v[194:197], v[110:113]
	v_mfma_i32_16x16x64_i8 v[106:109], v[62:65], v[194:197], v[106:109]
	v_mfma_i32_16x16x64_i8 v[94:97], v[38:41], v[202:205], v[94:97]
	v_mfma_i32_16x16x64_i8 v[90:93], v[62:65], v[202:205], v[90:93]
	v_mfma_i32_16x16x64_i8 v[134:137], v[146:149], v[162:165], v[134:137]
	v_mfma_i32_16x16x64_i8 v[130:133], v[154:157], v[162:165], v[130:133]
	v_mfma_i32_16x16x64_i8 v[118:121], v[146:149], v[170:173], v[118:121]
	v_mfma_i32_16x16x64_i8 v[114:117], v[154:157], v[170:173], v[114:117]
	v_mfma_i32_16x16x64_i8 v[102:105], v[146:149], v[190:193], v[102:105]
	v_mfma_i32_16x16x64_i8 v[98:101], v[154:157], v[190:193], v[98:101]
	v_mfma_i32_16x16x64_i8 v[86:89], v[146:149], v[198:201], v[86:89]
	v_mfma_i32_16x16x64_i8 v[82:85], v[154:157], v[198:201], v[82:85]
	v_mfma_i32_16x16x64_i8 v[134:137], v[150:153], v[166:169], v[134:137]
	v_mfma_i32_16x16x64_i8 v[130:133], v[158:161], v[166:169], v[130:133]
	v_mfma_i32_16x16x64_i8 v[118:121], v[150:153], v[186:189], v[118:121]
	v_mfma_i32_16x16x64_i8 v[114:117], v[158:161], v[186:189], v[114:117]
	v_mfma_i32_16x16x64_i8 v[102:105], v[150:153], v[194:197], v[102:105]
	v_mfma_i32_16x16x64_i8 v[98:101], v[158:161], v[194:197], v[98:101]
	v_mfma_i32_16x16x64_i8 v[86:89], v[150:153], v[202:205], v[86:89]
	v_mfma_i32_16x16x64_i8 v[82:85], v[158:161], v[202:205], v[82:85]
	s_barrier
	s_add_i32 s56, s52, s40
	v_lshl_add_u64 v[206:207], s[34:35], 0, v[174:175]
	s_mov_b32 m0, s56
	ds_read_b128 v[162:165], v235 offset:16384
	ds_read_b128 v[166:169], v235 offset:17408
	ds_read_b128 v[170:173], v235 offset:18432
	ds_read_b128 v[186:189], v235 offset:19456
	ds_read_b128 v[190:193], v235 offset:20480
	ds_read_b128 v[194:197], v235 offset:21504
	ds_read_b128 v[198:201], v235 offset:22528
	ds_read_b128 v[202:205], v235 offset:23552
	global_load_lds_dwordx4 v174, s[34:35]
	s_add_i32 m0, s56, 0x2000
	s_add_u32 s56, s34, 0x80000
	v_lshl_add_u64 v[208:209], s[34:35], 0, v[176:177]
	s_addc_u32 s57, s35, 0
	s_add_i32 s58, s53, s40
	global_load_lds_dwordx4 v176, s[34:35]
	s_mov_b32 m0, s58
	v_lshl_add_u64 v[212:213], s[36:37], 0, v[176:177]
	global_load_lds_dwordx4 v174, s[56:57]
	s_add_i32 m0, s58, 0x2000
	s_nop 0
	global_load_lds_dwordx4 v176, s[56:57]
	v_lshl_add_u64 v[210:211], s[36:37], 0, v[174:175]
	s_mov_b32 m0, s43
	s_nop 0
	global_load_lds_dwordx4 v174, s[36:37]
	s_mov_b32 m0, s44
	s_nop 0
	global_load_lds_dwordx4 v[212:213], off
	s_waitcnt vmcnt(8)
	s_waitcnt lgkmcnt(0)
	s_barrier
	s_waitcnt lgkmcnt(0)
	v_mfma_i32_16x16x64_i8 v[78:81], v[34:37], v[162:165], v[78:81]
	v_mfma_i32_16x16x64_i8 v[74:77], v[42:45], v[162:165], v[74:77]
	v_mfma_i32_16x16x64_i8 v[58:61], v[34:37], v[170:173], v[58:61]
	v_mfma_i32_16x16x64_i8 v[54:57], v[42:45], v[170:173], v[54:57]
	v_mfma_i32_16x16x64_i8 v[30:33], v[34:37], v[190:193], v[30:33]
	v_mfma_i32_16x16x64_i8 v[26:29], v[42:45], v[190:193], v[26:29]
	v_mfma_i32_16x16x64_i8 v[14:17], v[34:37], v[198:201], v[14:17]
	v_mfma_i32_16x16x64_i8 v[10:13], v[42:45], v[198:201], v[10:13]
	v_mfma_i32_16x16x64_i8 v[78:81], v[38:41], v[166:169], v[78:81]
	v_mfma_i32_16x16x64_i8 v[74:77], v[62:65], v[166:169], v[74:77]
	v_mfma_i32_16x16x64_i8 v[58:61], v[38:41], v[186:189], v[58:61]
	v_mfma_i32_16x16x64_i8 v[54:57], v[62:65], v[186:189], v[54:57]
	v_mfma_i32_16x16x64_i8 v[30:33], v[38:41], v[194:197], v[30:33]
	v_mfma_i32_16x16x64_i8 v[26:29], v[62:65], v[194:197], v[26:29]
	v_mfma_i32_16x16x64_i8 v[14:17], v[38:41], v[202:205], v[14:17]
	v_mfma_i32_16x16x64_i8 v[10:13], v[62:65], v[202:205], v[10:13]
	v_mfma_i32_16x16x64_i8 v[46:49], v[154:157], v[170:173], v[46:49]
	v_mfma_i32_16x16x64_i8 v[22:25], v[146:149], v[190:193], v[22:25]
	v_mfma_i32_16x16x64_i8 v[18:21], v[154:157], v[190:193], v[18:21]
	v_mfma_i32_16x16x64_i8 v[6:9], v[146:149], v[198:201], v[6:9]
	v_mfma_i32_16x16x64_i8 v[2:5], v[154:157], v[198:201], v[2:5]
	v_mfma_i32_16x16x64_i8 v[34:37], v[146:149], v[162:165], v[70:73]
	v_mfma_i32_16x16x64_i8 v[38:41], v[154:157], v[162:165], v[66:69]
	v_mfma_i32_16x16x64_i8 v[42:45], v[146:149], v[170:173], v[50:53]
	v_mfma_i32_16x16x64_i8 v[46:49], v[158:161], v[186:189], v[46:49]
	v_mfma_i32_16x16x64_i8 v[22:25], v[150:153], v[194:197], v[22:25]
	v_mfma_i32_16x16x64_i8 v[18:21], v[158:161], v[194:197], v[18:21]
	v_mfma_i32_16x16x64_i8 v[6:9], v[150:153], v[202:205], v[6:9]
	v_mfma_i32_16x16x64_i8 v[2:5], v[158:161], v[202:205], v[2:5]
	v_mfma_i32_16x16x64_i8 v[34:37], v[150:153], v[166:169], v[34:37]
	v_mfma_i32_16x16x64_i8 v[38:41], v[158:161], v[166:169], v[38:41]
	v_mfma_i32_16x16x64_i8 v[42:45], v[150:153], v[186:189], v[42:45]
	s_barrier
; #define PG8_STAGE(bufoff, gbase, voff) do { _Pragma("unroll") for (int _i = 0; _i < 2; ++_i) \
;         __builtin_amdgcn_global_load_lds((const unsigned*)((const char*)(gbase) + (voff)[_i]), (PG8_LAS unsigned*)(lds + (bufoff) + ldsw + _i * 8192), 16, 0, 0); } while (0)
; #define PG8_LDA(dst, b, h) do { _Pragma("unroll") for (int m = 0; m < 4; ++m) _Pragma("unroll") for (int k = 0; k < 2; ++k) dst[m][k] = *(const PG8_LAS bf16x8*)(lds + PG8_SA(b, h) + aoff + m * 2048 + k * 1024); } while (0)
; #define PG8_LDB(dst, b, h) do { _Pragma("unroll") for (int n = 0; n < 2; ++n) _Pragma("unroll") for (int k = 0; k < 2; ++k) dst[n][k] = *(const PG8_LAS bf16x8*)(lds + PG8_SB(b, h) + boff + n * 2048 + k * 1024); } while (0)
; #define PG8_MMA(ai, bj, At, Bt) do { __builtin_amdgcn_s_setprio(1); _Pragma("unroll") for (int m = 0; m < 4; ++m) _Pragma("unroll") for (int n = 0; n < 2; ++n) _Pragma("unroll") for (int k = 0; k < 2; ++k) \
;         acc[ai][bj][m][n] = mma_<I8>(Bt[n][k], At[m][k], acc[ai][bj][m][n]); __builtin_amdgcn_s_setprio(0); } while (0)
; #define PG8_WAIT_V(n) asm volatile("s_waitcnt vmcnt(" #n ")" ::: "memory")
; #define PG8_WAIT_L(n) asm volatile("s_waitcnt lgkmcnt(" #n ")" ::: "memory")
; #define PG8_BAR __builtin_amdgcn_s_barrier()
; #define PG8_SCHED __builtin_amdgcn_sched_barrier(0)
; template <class Epi, class Sched, bool ALIGN_EPI = false, bool SP2 = false, bool I8 = false>
; __device__ __forceinline__ void gemm_phase(PG8_LAS unsigned char* lds, const Gemm g, const Sched& S, const Epi& E) {
;     ...
;         for (int t = 0; t < nt; t += 2) {
;             const bool last = (t == nt - 2);
;     ...
;             PG8_LDB(B0, 1, 0); PG8_LDB(B1, 1, 1); PG8_SCHED; PG8_LDA(At, 1, 0); PG8_STAGE(PG8_SA(0, 1), a2 + hstepA, voffA);
;             PG8_WAIT_V(8); PG8_WAIT_L(0); PG8_BAR; PG8_MMA(0, 0, At, B0); PG8_MMA(0, 1, At, B1); PG8_BAR; PG8_SCHED;
;             PG8_LDA(At, 1, 1); PG8_STAGE(PG8_SB(1, 0), b3, voffB); PG8_STAGE(PG8_SB(1, 1), b3 + hstepB, voffB); PG8_STAGE(PG8_SA(1, 0), a3, voffA);
;             PG8_WAIT_V(8); PG8_WAIT_L(0); PG8_BAR; PG8_MMA(1, 0, At, B0); PG8_MMA(1, 1, At, B1); PG8_BAR; PG8_SCHED;
	s_add_i32 s56, 0, 0x18000
	s_add_i32 s57, 0, 0x1c000
	v_add_u32_e32 v70, s56, v1
	v_add_u32_e32 v158, s57, v1
	ds_read_b128 v[50:53], v70
	ds_read_b128 v[62:65], v70 offset:1024
	ds_read_b128 v[66:69], v70 offset:2048
	ds_read_b128 v[70:73], v70 offset:3072
	ds_read_b128 v[146:149], v158
	ds_read_b128 v[150:153], v158 offset:1024
	ds_read_b128 v[154:157], v158 offset:2048
	ds_read_b128 v[158:161], v158 offset:3072
	s_add_u32 s36, s36, 0x80000
	s_addc_u32 s37, s37, 0
	s_mov_b32 m0, s45
	ds_read_b128 v[162:165], v235 offset:32768
	ds_read_b128 v[166:169], v235 offset:33792
	ds_read_b128 v[170:173], v235 offset:34816
	ds_read_b128 v[186:189], v235 offset:35840
	ds_read_b128 v[190:193], v235 offset:36864
	ds_read_b128 v[194:197], v235 offset:37888
	ds_read_b128 v[198:201], v235 offset:38912
	ds_read_b128 v[202:205], v235 offset:39936
	global_load_lds_dwordx4 v174, s[36:37]
	s_mov_b32 m0, s46
	s_nop 0
	global_load_lds_dwordx4 v176, s[36:37]
	s_waitcnt vmcnt(8)
	s_waitcnt lgkmcnt(0)
	s_barrier
	s_waitcnt lgkmcnt(0)
	v_mfma_i32_16x16x64_i8 v[142:145], v[50:53], v[162:165], v[142:145]
	v_mfma_i32_16x16x64_i8 v[138:141], v[66:69], v[162:165], v[138:141]
	v_mfma_i32_16x16x64_i8 v[126:129], v[50:53], v[170:173], v[126:129]
	v_mfma_i32_16x16x64_i8 v[122:125], v[66:69], v[170:173], v[122:125]
	v_mfma_i32_16x16x64_i8 v[110:113], v[50:53], v[190:193], v[110:113]
	v_mfma_i32_16x16x64_i8 v[106:109], v[66:69], v[190:193], v[106:109]
	v_mfma_i32_16x16x64_i8 v[94:97], v[50:53], v[198:201], v[94:97]
	v_mfma_i32_16x16x64_i8 v[90:93], v[66:69], v[198:201], v[90:93]
	v_mfma_i32_16x16x64_i8 v[142:145], v[62:65], v[166:169], v[142:145]
	v_mfma_i32_16x16x64_i8 v[138:141], v[70:73], v[166:169], v[138:141]
	v_mfma_i32_16x16x64_i8 v[126:129], v[62:65], v[186:189], v[126:129]
	v_mfma_i32_16x16x64_i8 v[122:125], v[70:73], v[186:189], v[122:125]
	v_mfma_i32_16x16x64_i8 v[110:113], v[62:65], v[194:197], v[110:113]
	v_mfma_i32_16x16x64_i8 v[106:109], v[70:73], v[194:197], v[106:109]
	v_mfma_i32_16x16x64_i8 v[94:97], v[62:65], v[202:205], v[94:97]
	v_mfma_i32_16x16x64_i8 v[90:93], v[70:73], v[202:205], v[90:93]
	v_mfma_i32_16x16x64_i8 v[134:137], v[146:149], v[162:165], v[134:137]
	v_mfma_i32_16x16x64_i8 v[130:133], v[154:157], v[162:165], v[130:133]
	v_mfma_i32_16x16x64_i8 v[118:121], v[146:149], v[170:173], v[118:121]
	v_mfma_i32_16x16x64_i8 v[114:117], v[154:157], v[170:173], v[114:117]
	v_mfma_i32_16x16x64_i8 v[102:105], v[146:149], v[190:193], v[102:105]
	v_mfma_i32_16x16x64_i8 v[98:101], v[154:157], v[190:193], v[98:101]
	v_mfma_i32_16x16x64_i8 v[86:89], v[146:149], v[198:201], v[86:89]
	v_mfma_i32_16x16x64_i8 v[82:85], v[154:157], v[198:201], v[82:85]
	v_mfma_i32_16x16x64_i8 v[134:137], v[150:153], v[166:169], v[134:137]
	v_mfma_i32_16x16x64_i8 v[130:133], v[158:161], v[166:169], v[130:133]
	v_mfma_i32_16x16x64_i8 v[118:121], v[150:153], v[186:189], v[118:121]
	v_mfma_i32_16x16x64_i8 v[114:117], v[158:161], v[186:189], v[114:117]
	v_mfma_i32_16x16x64_i8 v[102:105], v[150:153], v[194:197], v[102:105]
	v_mfma_i32_16x16x64_i8 v[98:101], v[158:161], v[194:197], v[98:101]
	v_mfma_i32_16x16x64_i8 v[86:89], v[150:153], v[202:205], v[86:89]
	v_mfma_i32_16x16x64_i8 v[82:85], v[158:161], v[202:205], v[82:85]
	s_barrier
	s_add_i32 s36, s56, s40
	v_lshl_add_u64 v[206:207], v[206:207], 0, s[18:19]
	s_mov_b32 m0, s36
	ds_read_b128 v[162:165], v235 offset:49152
	ds_read_b128 v[166:169], v235 offset:50176
	ds_read_b128 v[170:173], v235 offset:51200
	ds_read_b128 v[186:189], v235 offset:52224
	ds_read_b128 v[190:193], v235 offset:53248
	ds_read_b128 v[194:197], v235 offset:54272
	ds_read_b128 v[198:201], v235 offset:55296
	ds_read_b128 v[202:205], v235 offset:56320
	global_load_lds_dwordx4 v[206:207], off
	s_add_i32 m0, s36, 0x2000
	s_add_u32 s34, s34, 0x80080
	v_lshl_add_u64 v[206:207], v[208:209], 0, s[18:19]
	s_addc_u32 s35, s35, 0
	s_add_i32 s36, s57, s40
	global_load_lds_dwordx4 v[206:207], off
	s_mov_b32 m0, s36
	s_nop 0
	global_load_lds_dwordx4 v174, s[34:35]
	s_add_i32 m0, s36, 0x2000
	s_nop 0
	global_load_lds_dwordx4 v176, s[34:35]
	v_lshl_add_u64 v[206:207], v[210:211], 0, s[18:19]
	s_mov_b32 m0, s48
	s_nop 0
	global_load_lds_dwordx4 v[206:207], off
	v_lshl_add_u64 v[206:207], v[212:213], 0, s[18:19]
	s_mov_b32 m0, s49
	s_nop 0
	global_load_lds_dwordx4 v[206:207], off
	s_waitcnt vmcnt(8)
	s_waitcnt lgkmcnt(0)
	s_barrier
	s_waitcnt lgkmcnt(0)
	v_mfma_i32_16x16x64_i8 v[78:81], v[50:53], v[162:165], v[78:81]
	v_mfma_i32_16x16x64_i8 v[74:77], v[66:69], v[162:165], v[74:77]
	v_mfma_i32_16x16x64_i8 v[58:61], v[50:53], v[170:173], v[58:61]
	v_mfma_i32_16x16x64_i8 v[54:57], v[66:69], v[170:173], v[54:57]
	v_mfma_i32_16x16x64_i8 v[30:33], v[50:53], v[190:193], v[30:33]
	v_mfma_i32_16x16x64_i8 v[26:29], v[66:69], v[190:193], v[26:29]
	v_mfma_i32_16x16x64_i8 v[14:17], v[50:53], v[198:201], v[14:17]
	v_mfma_i32_16x16x64_i8 v[10:13], v[66:69], v[198:201], v[10:13]
	v_mfma_i32_16x16x64_i8 v[78:81], v[62:65], v[166:169], v[78:81]
	v_mfma_i32_16x16x64_i8 v[74:77], v[70:73], v[166:169], v[74:77]
	v_mfma_i32_16x16x64_i8 v[58:61], v[62:65], v[186:189], v[58:61]
	v_mfma_i32_16x16x64_i8 v[54:57], v[70:73], v[186:189], v[54:57]
	v_mfma_i32_16x16x64_i8 v[30:33], v[62:65], v[194:197], v[30:33]
	v_mfma_i32_16x16x64_i8 v[26:29], v[70:73], v[194:197], v[26:29]
	v_mfma_i32_16x16x64_i8 v[14:17], v[62:65], v[202:205], v[14:17]
	v_mfma_i32_16x16x64_i8 v[10:13], v[70:73], v[202:205], v[10:13]
	v_mfma_i32_16x16x64_i8 v[34:37], v[146:149], v[162:165], v[34:37]
	v_mfma_i32_16x16x64_i8 v[70:73], v[150:153], v[166:169], v[34:37]
	v_mfma_i32_16x16x64_i8 v[34:37], v[154:157], v[162:165], v[38:41]
	v_mfma_i32_16x16x64_i8 v[66:69], v[158:161], v[166:169], v[34:37]
	v_mfma_i32_16x16x64_i8 v[34:37], v[146:149], v[170:173], v[42:45]
	v_mfma_i32_16x16x64_i8 v[50:53], v[150:153], v[186:189], v[34:37]
	v_mfma_i32_16x16x64_i8 v[34:37], v[154:157], v[170:173], v[46:49]
	v_mfma_i32_16x16x64_i8 v[22:25], v[146:149], v[190:193], v[22:25]
	v_mfma_i32_16x16x64_i8 v[18:21], v[154:157], v[190:193], v[18:21]
	v_mfma_i32_16x16x64_i8 v[6:9], v[146:149], v[198:201], v[6:9]
	v_mfma_i32_16x16x64_i8 v[2:5], v[154:157], v[198:201], v[2:5]
	v_mfma_i32_16x16x64_i8 v[46:49], v[158:161], v[186:189], v[34:37]
	v_mfma_i32_16x16x64_i8 v[22:25], v[150:153], v[194:197], v[22:25]
	v_mfma_i32_16x16x64_i8 v[18:21], v[158:161], v[194:197], v[18:21]
	v_mfma_i32_16x16x64_i8 v[6:9], v[150:153], v[202:205], v[6:9]
	v_mfma_i32_16x16x64_i8 v[2:5], v[158:161], v[202:205], v[2:5]
	s_barrier
	s_add_i32 s55, s55, 2
	s_add_u32 s8, s8, 0x100
	s_addc_u32 s9, s9, 0
	s_add_u32 s33, s33, 0x100
	s_addc_u32 s54, s54, 0
	s_cmp_gt_u32 s55, 29
	s_cbranch_scc0 .LBB0_1721
	s_and_b64 vcc, exec, s[20:21]
	s_cbranch_vccz .LBB0_1724
	s_barrier

; #define PG8_STAGE(bufoff, gbase, voff) do { _Pragma("unroll") for (int _i = 0; _i < 2; ++_i) \
;         __builtin_amdgcn_global_load_lds((const unsigned*)((const char*)(gbase) + (voff)[_i]), (PG8_LAS unsigned*)(lds + (bufoff) + ldsw + _i * 8192), 16, 0, 0); } while (0)
; #define PG8_LDA(dst, b, h) do { _Pragma("unroll") for (int m = 0; m < 4; ++m) _Pragma("unroll") for (int k = 0; k < 2; ++k) dst[m][k] = *(const PG8_LAS bf16x8*)(lds + PG8_SA(b, h) + aoff + m * 2048 + k * 1024); } while (0)
; #define PG8_LDB(dst, b, h) do { _Pragma("unroll") for (int n = 0; n < 2; ++n) _Pragma("unroll") for (int k = 0; k < 2; ++k) dst[n][k] = *(const PG8_LAS bf16x8*)(lds + PG8_SB(b, h) + boff + n * 2048 + k * 1024); } while (0)
; #define PG8_MMA(ai, bj, At, Bt) do { __builtin_amdgcn_s_setprio(1); _Pragma("unroll") for (int m = 0; m < 4; ++m) _Pragma("unroll") for (int n = 0; n < 2; ++n) _Pragma("unroll") for (int k = 0; k < 2; ++k) \
;         acc[ai][bj][m][n] = mma_<I8>(Bt[n][k], At[m][k], acc[ai][bj][m][n]); __builtin_amdgcn_s_setprio(0); } while (0)
; #define PG8_WAIT_V(n) asm volatile("s_waitcnt vmcnt(" #n ")" ::: "memory")
; #define PG8_WAIT_L(n) asm volatile("s_waitcnt lgkmcnt(" #n ")" ::: "memory")
; #define PG8_BAR __builtin_amdgcn_s_barrier()
; #define PG8_SCHED __builtin_amdgcn_sched_barrier(0)
; template <class Epi, class Sched, bool ALIGN_EPI = false, bool SP2 = false, bool I8 = false>
; __device__ __forceinline__ void gemm_phase(PG8_LAS unsigned char* lds, const Gemm g, const Sched& S, const Epi& E) {
;     ...
;             const char* a1 = cA + (size_t)(t + 1) * kstep;
;             const char* a2 = last ? nA : cA + (size_t)(t + 2) * kstep; const char* b2 = last ? nB : cB + (size_t)(t + 2) * kstep;
;             const char* a3 = a2 + kstep; const char* b3 = b2 + kstep;
;             if (last && has_next) S.a_ready(nxt);
;             if constexpr (SP2) {
;             PG8_LDB(B0, 0, 0); PG8_LDB(B1, 0, 1); PG8_SCHED; PG8_LDA(At, 0, 0); PG8_STAGE(PG8_SA(1, 1), a1 + hstepA, voffA);
;             PG8_WAIT_V(8); PG8_WAIT_L(0); PG8_BAR; PG8_MMA(0, 0, At, B0); PG8_MMA(0, 1, At, B1); PG8_BAR; PG8_SCHED;
;             PG8_LDA(At, 0, 1); PG8_STAGE(PG8_SB(0, 0), b2, voffB); PG8_STAGE(PG8_SB(0, 1), b2 + hstepB, voffB); PG8_STAGE(PG8_SA(0, 0), a2, voffA);
;             PG8_WAIT_V(8); PG8_WAIT_L(0); PG8_BAR; PG8_MMA(1, 0, At, B0); PG8_MMA(1, 1, At, B1); PG8_BAR; PG8_SCHED;
.LBB0_2014:
	ds_read_b128 v[118:121], v163
	ds_read_b128 v[126:129], v163 offset:1024
	ds_read_b128 v[130:133], v163 offset:2048
	ds_read_b128 v[134:137], v163 offset:3072
	ds_read_b128 v[168:171], v167
	ds_read_b128 v[176:179], v167 offset:1024
	ds_read_b128 v[180:183], v167 offset:2048
	ds_read_b128 v[184:187], v167 offset:3072
	s_add_u32 s38, s36, 0xfff80080
	s_addc_u32 s39, s37, -1
	s_cmp_eq_u32 s65, 28
	s_cselect_b32 s41, s27, s39
	s_cselect_b32 s40, s61, s38
	s_cselect_b32 s39, s25, s64
	s_cselect_b32 s38, s62, s63
	s_add_i32 m0, s35, 0xc000
	ds_read_b128 v[188:191], v173
	ds_read_b128 v[192:195], v173 offset:1024
	ds_read_b128 v[196:199], v173 offset:2048
	ds_read_b128 v[200:203], v173 offset:3072
	ds_read_b128 v[204:207], v173 offset:4096
	ds_read_b128 v[208:211], v173 offset:5120
	ds_read_b128 v[212:215], v173 offset:6144
	ds_read_b128 v[216:219], v173 offset:7168
	global_load_lds_dwordx4 v154, s[36:37]
	s_add_i32 m0, s35, 0xe000
	s_nop 0
	global_load_lds_dwordx4 v156, s[36:37]
	s_waitcnt vmcnt(8)
	s_waitcnt lgkmcnt(0)
	s_barrier
	s_waitcnt lgkmcnt(0)
	v_mfma_i32_16x16x64_i8 v[142:145], v[118:121], v[188:191], v[142:145]
	v_mfma_i32_16x16x64_i8 v[138:141], v[130:133], v[188:191], v[138:141]
	v_mfma_i32_16x16x64_i8 v[110:113], v[118:121], v[196:199], v[110:113]
	v_mfma_i32_16x16x64_i8 v[106:109], v[130:133], v[196:199], v[106:109]
	v_mfma_i32_16x16x64_i8 v[94:97], v[118:121], v[204:207], v[94:97]
	v_mfma_i32_16x16x64_i8 v[90:93], v[130:133], v[204:207], v[90:93]
	v_mfma_i32_16x16x64_i8 v[78:81], v[118:121], v[212:215], v[78:81]
	v_mfma_i32_16x16x64_i8 v[74:77], v[130:133], v[212:215], v[74:77]
	v_mfma_i32_16x16x64_i8 v[142:145], v[126:129], v[192:195], v[142:145]
	v_mfma_i32_16x16x64_i8 v[138:141], v[134:137], v[192:195], v[138:141]
	v_mfma_i32_16x16x64_i8 v[110:113], v[126:129], v[200:203], v[110:113]
	v_mfma_i32_16x16x64_i8 v[106:109], v[134:137], v[200:203], v[106:109]
	v_mfma_i32_16x16x64_i8 v[94:97], v[126:129], v[208:211], v[94:97]
	v_mfma_i32_16x16x64_i8 v[90:93], v[134:137], v[208:211], v[90:93]
	v_mfma_i32_16x16x64_i8 v[78:81], v[126:129], v[216:219], v[78:81]
	v_mfma_i32_16x16x64_i8 v[74:77], v[134:137], v[216:219], v[74:77]
	v_mfma_i32_16x16x64_i8 v[122:125], v[168:171], v[188:191], v[122:125]
	v_mfma_i32_16x16x64_i8 v[114:117], v[180:183], v[188:191], v[114:117]
	v_mfma_i32_16x16x64_i8 v[102:105], v[168:171], v[196:199], v[102:105]
	v_mfma_i32_16x16x64_i8 v[98:101], v[180:183], v[196:199], v[98:101]
	v_mfma_i32_16x16x64_i8 v[86:89], v[168:171], v[204:207], v[86:89]
	v_mfma_i32_16x16x64_i8 v[82:85], v[180:183], v[204:207], v[82:85]
	v_mfma_i32_16x16x64_i8 v[70:73], v[168:171], v[212:215], v[70:73]
	v_mfma_i32_16x16x64_i8 v[66:69], v[180:183], v[212:215], v[66:69]
	v_mfma_i32_16x16x64_i8 v[122:125], v[176:179], v[192:195], v[122:125]
	v_mfma_i32_16x16x64_i8 v[114:117], v[184:187], v[192:195], v[114:117]
	v_mfma_i32_16x16x64_i8 v[102:105], v[176:179], v[200:203], v[102:105]
	v_mfma_i32_16x16x64_i8 v[98:101], v[184:187], v[200:203], v[98:101]
	v_mfma_i32_16x16x64_i8 v[86:89], v[176:179], v[208:211], v[86:89]
	v_mfma_i32_16x16x64_i8 v[82:85], v[184:187], v[208:211], v[82:85]
	v_mfma_i32_16x16x64_i8 v[70:73], v[176:179], v[216:219], v[70:73]
	v_mfma_i32_16x16x64_i8 v[66:69], v[184:187], v[216:219], v[66:69]
	s_barrier
	s_add_i32 s66, s54, s46
	v_lshl_add_u64 v[164:165], s[38:39], 0, v[148:149]
	s_mov_b32 m0, s66
	ds_read_b128 v[188:191], v173 offset:16384
	ds_read_b128 v[192:195], v173 offset:17408
	ds_read_b128 v[196:199], v173 offset:18432
	ds_read_b128 v[200:203], v173 offset:19456
	ds_read_b128 v[204:207], v173 offset:20480
	ds_read_b128 v[208:211], v173 offset:21504
	ds_read_b128 v[212:215], v173 offset:22528
	ds_read_b128 v[216:219], v173 offset:23552
	global_load_lds_dwordx4 v148, s[38:39]
	s_add_i32 m0, s66, 0x2000
	s_add_u32 s66, s38, 0x80000
	v_lshl_add_u64 v[220:221], s[38:39], 0, v[152:153]
	s_addc_u32 s67, s39, 0
	s_add_i32 s68, s55, s46
	global_load_lds_dwordx4 v152, s[38:39]
	s_mov_b32 m0, s68
	v_lshl_add_u64 v[224:225], s[40:41], 0, v[150:151]
	global_load_lds_dwordx4 v148, s[66:67]
	s_add_i32 m0, s68, 0x2000
	s_nop 0
	global_load_lds_dwordx4 v152, s[66:67]
	v_lshl_add_u64 v[222:223], s[40:41], 0, v[146:147]
	s_mov_b32 m0, s35
	s_nop 0
	global_load_lds_dwordx4 v146, s[40:41]
	s_mov_b32 m0, s47
	s_nop 0
	global_load_lds_dwordx4 v150, s[40:41]
	s_waitcnt vmcnt(8)
	s_waitcnt lgkmcnt(0)
	s_barrier
	s_waitcnt lgkmcnt(0)
	v_mfma_i32_16x16x64_i8 v[62:65], v[118:121], v[188:191], v[62:65]
	v_mfma_i32_16x16x64_i8 v[58:61], v[130:133], v[188:191], v[58:61]
	v_mfma_i32_16x16x64_i8 v[46:49], v[118:121], v[196:199], v[46:49]
	v_mfma_i32_16x16x64_i8 v[42:45], v[130:133], v[196:199], v[42:45]
	v_mfma_i32_16x16x64_i8 v[30:33], v[118:121], v[204:207], v[30:33]
	v_mfma_i32_16x16x64_i8 v[26:29], v[130:133], v[204:207], v[26:29]
	v_mfma_i32_16x16x64_i8 v[14:17], v[118:121], v[212:215], v[14:17]
	v_mfma_i32_16x16x64_i8 v[10:13], v[130:133], v[212:215], v[10:13]
	v_mfma_i32_16x16x64_i8 v[62:65], v[126:129], v[192:195], v[62:65]
	v_mfma_i32_16x16x64_i8 v[58:61], v[134:137], v[192:195], v[58:61]
	v_mfma_i32_16x16x64_i8 v[46:49], v[126:129], v[200:203], v[46:49]
	v_mfma_i32_16x16x64_i8 v[42:45], v[134:137], v[200:203], v[42:45]
	v_mfma_i32_16x16x64_i8 v[30:33], v[126:129], v[208:211], v[30:33]
	v_mfma_i32_16x16x64_i8 v[26:29], v[134:137], v[208:211], v[26:29]
	v_mfma_i32_16x16x64_i8 v[14:17], v[126:129], v[216:219], v[14:17]
	v_mfma_i32_16x16x64_i8 v[10:13], v[134:137], v[216:219], v[10:13]
	v_mfma_i32_16x16x64_i8 v[54:57], v[168:171], v[188:191], v[54:57]
	v_mfma_i32_16x16x64_i8 v[50:53], v[180:183], v[188:191], v[50:53]
	v_mfma_i32_16x16x64_i8 v[38:41], v[168:171], v[196:199], v[38:41]
	v_mfma_i32_16x16x64_i8 v[34:37], v[180:183], v[196:199], v[34:37]
	v_mfma_i32_16x16x64_i8 v[22:25], v[168:171], v[204:207], v[22:25]
	v_mfma_i32_16x16x64_i8 v[18:21], v[180:183], v[204:207], v[18:21]
	v_mfma_i32_16x16x64_i8 v[6:9], v[168:171], v[212:215], v[6:9]
	v_mfma_i32_16x16x64_i8 v[2:5], v[180:183], v[212:215], v[2:5]
	v_mfma_i32_16x16x64_i8 v[54:57], v[176:179], v[192:195], v[54:57]
	v_mfma_i32_16x16x64_i8 v[50:53], v[184:187], v[192:195], v[50:53]
	v_mfma_i32_16x16x64_i8 v[38:41], v[176:179], v[200:203], v[38:41]
	v_mfma_i32_16x16x64_i8 v[34:37], v[184:187], v[200:203], v[34:37]
	v_mfma_i32_16x16x64_i8 v[22:25], v[176:179], v[208:211], v[22:25]
	v_mfma_i32_16x16x64_i8 v[18:21], v[184:187], v[208:211], v[18:21]
	v_mfma_i32_16x16x64_i8 v[6:9], v[176:179], v[216:219], v[6:9]
	v_mfma_i32_16x16x64_i8 v[2:5], v[184:187], v[216:219], v[2:5]
	s_barrier
; #define PG8_STAGE(bufoff, gbase, voff) do { _Pragma("unroll") for (int _i = 0; _i < 2; ++_i) \
;         __builtin_amdgcn_global_load_lds((const unsigned*)((const char*)(gbase) + (voff)[_i]), (PG8_LAS unsigned*)(lds + (bufoff) + ldsw + _i * 8192), 16, 0, 0); } while (0)
; #define PG8_LDA(dst, b, h) do { _Pragma("unroll") for (int m = 0; m < 4; ++m) _Pragma("unroll") for (int k = 0; k < 2; ++k) dst[m][k] = *(const PG8_LAS bf16x8*)(lds + PG8_SA(b, h) + aoff + m * 2048 + k * 1024); } while (0)
; #define PG8_LDB(dst, b, h) do { _Pragma("unroll") for (int n = 0; n < 2; ++n) _Pragma("unroll") for (int k = 0; k < 2; ++k) dst[n][k] = *(const PG8_LAS bf16x8*)(lds + PG8_SB(b, h) + boff + n * 2048 + k * 1024); } while (0)
; #define PG8_MMA(ai, bj, At, Bt) do { __builtin_amdgcn_s_setprio(1); _Pragma("unroll") for (int m = 0; m < 4; ++m) _Pragma("unroll") for (int n = 0; n < 2; ++n) _Pragma("unroll") for (int k = 0; k < 2; ++k) \
;         acc[ai][bj][m][n] = mma_<I8>(Bt[n][k], At[m][k], acc[ai][bj][m][n]); __builtin_amdgcn_s_setprio(0); } while (0)
; #define PG8_WAIT_V(n) asm volatile("s_waitcnt vmcnt(" #n ")" ::: "memory")
; #define PG8_WAIT_L(n) asm volatile("s_waitcnt lgkmcnt(" #n ")" ::: "memory")
; #define PG8_BAR __builtin_amdgcn_s_barrier()
; #define PG8_SCHED __builtin_amdgcn_sched_barrier(0)
; template <class Epi, class Sched, bool ALIGN_EPI = false, bool SP2 = false, bool I8 = false>
; __device__ __forceinline__ void gemm_phase(PG8_LAS unsigned char* lds, const Gemm g, const Sched& S, const Epi& E) {
;     ...
;         for (int t = 0; t < nt; t += 2) {
;             const bool last = (t == nt - 2);
;     ...
;             PG8_LDB(B0, 1, 0); PG8_LDB(B1, 1, 1); PG8_SCHED; PG8_LDA(At, 1, 0); PG8_STAGE(PG8_SA(0, 1), a2 + hstepA, voffA);
;             PG8_WAIT_V(8); PG8_WAIT_L(0); PG8_BAR; PG8_MMA(0, 0, At, B0); PG8_MMA(0, 1, At, B1); PG8_BAR; PG8_SCHED;
;             PG8_LDA(At, 1, 1); PG8_STAGE(PG8_SB(1, 0), b3, voffB); PG8_STAGE(PG8_SB(1, 1), b3 + hstepB, voffB); PG8_STAGE(PG8_SA(1, 0), a3, voffA);
;             PG8_WAIT_V(8); PG8_WAIT_L(0); PG8_BAR; PG8_MMA(1, 0, At, B0); PG8_MMA(1, 1, At, B1); PG8_BAR; PG8_SCHED;
	s_add_i32 s66, 0, 0x18000
	s_add_i32 s67, 0, 0x1c000
	v_add_u32_e32 v134, s66, v1
	v_add_u32_e32 v162, s67, v1
	ds_read_b128 v[118:121], v134
	ds_read_b128 v[126:129], v134 offset:1024
	ds_read_b128 v[130:133], v134 offset:2048
	ds_read_b128 v[134:137], v134 offset:3072
	ds_read_b128 v[168:171], v162
	ds_read_b128 v[176:179], v162 offset:1024
	ds_read_b128 v[180:183], v162 offset:2048
	ds_read_b128 v[184:187], v162 offset:3072
	s_add_u32 s40, s40, 0x80000
	s_addc_u32 s41, s41, 0
	s_mov_b32 m0, s48
	ds_read_b128 v[188:191], v173 offset:32768
	ds_read_b128 v[192:195], v173 offset:33792
	ds_read_b128 v[196:199], v173 offset:34816
	ds_read_b128 v[200:203], v173 offset:35840
	ds_read_b128 v[204:207], v173 offset:36864
	ds_read_b128 v[208:211], v173 offset:37888
	ds_read_b128 v[212:215], v173 offset:38912
	ds_read_b128 v[216:219], v173 offset:39936
	global_load_lds_dwordx4 v146, s[40:41]
	s_mov_b32 m0, s49
	s_nop 0
	global_load_lds_dwordx4 v150, s[40:41]
	s_waitcnt vmcnt(8)
	s_waitcnt lgkmcnt(0)
	s_barrier
	s_waitcnt lgkmcnt(0)
	v_mfma_i32_16x16x64_i8 v[142:145], v[118:121], v[188:191], v[142:145]
	v_mfma_i32_16x16x64_i8 v[138:141], v[130:133], v[188:191], v[138:141]
	v_mfma_i32_16x16x64_i8 v[110:113], v[118:121], v[196:199], v[110:113]
	v_mfma_i32_16x16x64_i8 v[106:109], v[130:133], v[196:199], v[106:109]
	v_mfma_i32_16x16x64_i8 v[94:97], v[118:121], v[204:207], v[94:97]
	v_mfma_i32_16x16x64_i8 v[90:93], v[130:133], v[204:207], v[90:93]
	v_mfma_i32_16x16x64_i8 v[78:81], v[118:121], v[212:215], v[78:81]
	v_mfma_i32_16x16x64_i8 v[74:77], v[130:133], v[212:215], v[74:77]
	v_mfma_i32_16x16x64_i8 v[142:145], v[126:129], v[192:195], v[142:145]
	v_mfma_i32_16x16x64_i8 v[138:141], v[134:137], v[192:195], v[138:141]
	v_mfma_i32_16x16x64_i8 v[110:113], v[126:129], v[200:203], v[110:113]
	v_mfma_i32_16x16x64_i8 v[106:109], v[134:137], v[200:203], v[106:109]
	v_mfma_i32_16x16x64_i8 v[94:97], v[126:129], v[208:211], v[94:97]
	v_mfma_i32_16x16x64_i8 v[90:93], v[134:137], v[208:211], v[90:93]
	v_mfma_i32_16x16x64_i8 v[78:81], v[126:129], v[216:219], v[78:81]
	v_mfma_i32_16x16x64_i8 v[74:77], v[134:137], v[216:219], v[74:77]
	v_mfma_i32_16x16x64_i8 v[122:125], v[168:171], v[188:191], v[122:125]
	v_mfma_i32_16x16x64_i8 v[114:117], v[180:183], v[188:191], v[114:117]
	v_mfma_i32_16x16x64_i8 v[102:105], v[168:171], v[196:199], v[102:105]
	v_mfma_i32_16x16x64_i8 v[98:101], v[180:183], v[196:199], v[98:101]
	v_mfma_i32_16x16x64_i8 v[86:89], v[168:171], v[204:207], v[86:89]
	v_mfma_i32_16x16x64_i8 v[82:85], v[180:183], v[204:207], v[82:85]
	v_mfma_i32_16x16x64_i8 v[70:73], v[168:171], v[212:215], v[70:73]
	v_mfma_i32_16x16x64_i8 v[66:69], v[180:183], v[212:215], v[66:69]
	v_mfma_i32_16x16x64_i8 v[122:125], v[176:179], v[192:195], v[122:125]
	v_mfma_i32_16x16x64_i8 v[114:117], v[184:187], v[192:195], v[114:117]
	v_mfma_i32_16x16x64_i8 v[102:105], v[176:179], v[200:203], v[102:105]
	v_mfma_i32_16x16x64_i8 v[98:101], v[184:187], v[200:203], v[98:101]
	v_mfma_i32_16x16x64_i8 v[86:89], v[176:179], v[208:211], v[86:89]
	v_mfma_i32_16x16x64_i8 v[82:85], v[184:187], v[208:211], v[82:85]
	v_mfma_i32_16x16x64_i8 v[70:73], v[176:179], v[216:219], v[70:73]
	v_mfma_i32_16x16x64_i8 v[66:69], v[184:187], v[216:219], v[66:69]
	s_barrier
	s_add_i32 s40, s66, s46
	v_lshl_add_u64 v[164:165], v[164:165], 0, s[12:13]
	s_mov_b32 m0, s40
	ds_read_b128 v[188:191], v173 offset:49152
	ds_read_b128 v[192:195], v173 offset:50176
	ds_read_b128 v[196:199], v173 offset:51200
	ds_read_b128 v[200:203], v173 offset:52224
	ds_read_b128 v[204:207], v173 offset:53248
	ds_read_b128 v[208:211], v173 offset:54272
	ds_read_b128 v[212:215], v173 offset:55296
	ds_read_b128 v[216:219], v173 offset:56320
	global_load_lds_dwordx4 v[164:165], off
	s_add_i32 m0, s40, 0x2000
	s_add_u32 s38, s38, 0x80080
	v_lshl_add_u64 v[164:165], v[220:221], 0, s[12:13]
	s_addc_u32 s39, s39, 0
	s_add_i32 s40, s67, s46
	global_load_lds_dwordx4 v[164:165], off
	s_mov_b32 m0, s40
	s_nop 0
	global_load_lds_dwordx4 v148, s[38:39]
	s_add_i32 m0, s40, 0x2000
	s_nop 0
	global_load_lds_dwordx4 v152, s[38:39]
	v_lshl_add_u64 v[164:165], v[222:223], 0, s[12:13]
	s_mov_b32 m0, s51
	s_nop 0
	global_load_lds_dwordx4 v[164:165], off
	v_lshl_add_u64 v[164:165], v[224:225], 0, s[12:13]
	s_mov_b32 m0, s52
	s_nop 0
	global_load_lds_dwordx4 v[164:165], off
	s_waitcnt vmcnt(8)
	s_waitcnt lgkmcnt(0)
	s_barrier
	s_waitcnt lgkmcnt(0)
	v_mfma_i32_16x16x64_i8 v[62:65], v[118:121], v[188:191], v[62:65]
	v_mfma_i32_16x16x64_i8 v[58:61], v[130:133], v[188:191], v[58:61]
	v_mfma_i32_16x16x64_i8 v[46:49], v[118:121], v[196:199], v[46:49]
	v_mfma_i32_16x16x64_i8 v[42:45], v[130:133], v[196:199], v[42:45]
	v_mfma_i32_16x16x64_i8 v[30:33], v[118:121], v[204:207], v[30:33]
	v_mfma_i32_16x16x64_i8 v[26:29], v[130:133], v[204:207], v[26:29]
	v_mfma_i32_16x16x64_i8 v[14:17], v[118:121], v[212:215], v[14:17]
	v_mfma_i32_16x16x64_i8 v[10:13], v[130:133], v[212:215], v[10:13]
	v_mfma_i32_16x16x64_i8 v[62:65], v[126:129], v[192:195], v[62:65]
	v_mfma_i32_16x16x64_i8 v[58:61], v[134:137], v[192:195], v[58:61]
	v_mfma_i32_16x16x64_i8 v[46:49], v[126:129], v[200:203], v[46:49]
	v_mfma_i32_16x16x64_i8 v[42:45], v[134:137], v[200:203], v[42:45]
	v_mfma_i32_16x16x64_i8 v[30:33], v[126:129], v[208:211], v[30:33]
	v_mfma_i32_16x16x64_i8 v[26:29], v[134:137], v[208:211], v[26:29]
	v_mfma_i32_16x16x64_i8 v[14:17], v[126:129], v[216:219], v[14:17]
	v_mfma_i32_16x16x64_i8 v[10:13], v[134:137], v[216:219], v[10:13]
	v_mfma_i32_16x16x64_i8 v[54:57], v[168:171], v[188:191], v[54:57]
	v_mfma_i32_16x16x64_i8 v[50:53], v[180:183], v[188:191], v[50:53]
	v_mfma_i32_16x16x64_i8 v[38:41], v[168:171], v[196:199], v[38:41]
	v_mfma_i32_16x16x64_i8 v[34:37], v[180:183], v[196:199], v[34:37]
	v_mfma_i32_16x16x64_i8 v[22:25], v[168:171], v[204:207], v[22:25]
	v_mfma_i32_16x16x64_i8 v[18:21], v[180:183], v[204:207], v[18:21]
	v_mfma_i32_16x16x64_i8 v[6:9], v[168:171], v[212:215], v[6:9]
	v_mfma_i32_16x16x64_i8 v[2:5], v[180:183], v[212:215], v[2:5]
	v_mfma_i32_16x16x64_i8 v[54:57], v[176:179], v[192:195], v[54:57]
	v_mfma_i32_16x16x64_i8 v[50:53], v[184:187], v[192:195], v[50:53]
	v_mfma_i32_16x16x64_i8 v[38:41], v[176:179], v[200:203], v[38:41]
	v_mfma_i32_16x16x64_i8 v[34:37], v[184:187], v[200:203], v[34:37]
	v_mfma_i32_16x16x64_i8 v[22:25], v[176:179], v[208:211], v[22:25]
	v_mfma_i32_16x16x64_i8 v[18:21], v[184:187], v[208:211], v[18:21]
	v_mfma_i32_16x16x64_i8 v[6:9], v[176:179], v[216:219], v[6:9]
	v_mfma_i32_16x16x64_i8 v[2:5], v[184:187], v[216:219], v[2:5]
	s_barrier
	s_add_i32 s65, s65, 2
	s_add_u32 s36, s36, 0x100
	s_addc_u32 s37, s37, 0
	s_add_u32 s63, s63, 0x100
	s_addc_u32 s64, s64, 0
	s_cmp_gt_u32 s65, 29
	s_cbranch_scc0 .LBB0_2014
	s_and_b64 vcc, exec, s[14:15]
	s_cbranch_vccz .LBB0_2017
	s_barrier

; #define PG8_STAGE(bufoff, gbase, voff) do { _Pragma("unroll") for (int _i = 0; _i < 2; ++_i) \
;         __builtin_amdgcn_global_load_lds((const unsigned*)((const char*)(gbase) + (voff)[_i]), (PG8_LAS unsigned*)(lds + (bufoff) + ldsw + _i * 8192), 16, 0, 0); } while (0)
; #define PG8_LDA(dst, b, h) do { _Pragma("unroll") for (int m = 0; m < 4; ++m) _Pragma("unroll") for (int k = 0; k < 2; ++k) dst[m][k] = *(const PG8_LAS bf16x8*)(lds + PG8_SA(b, h) + aoff + m * 2048 + k * 1024); } while (0)
; #define PG8_LDB(dst, b, h) do { _Pragma("unroll") for (int n = 0; n < 2; ++n) _Pragma("unroll") for (int k = 0; k < 2; ++k) dst[n][k] = *(const PG8_LAS bf16x8*)(lds + PG8_SB(b, h) + boff + n * 2048 + k * 1024); } while (0)
; #define PG8_MMA(ai, bj, At, Bt) do { __builtin_amdgcn_s_setprio(1); _Pragma("unroll") for (int m = 0; m < 4; ++m) _Pragma("unroll") for (int n = 0; n < 2; ++n) _Pragma("unroll") for (int k = 0; k < 2; ++k) \
;         acc[ai][bj][m][n] = mma_<I8>(Bt[n][k], At[m][k], acc[ai][bj][m][n]); __builtin_amdgcn_s_setprio(0); } while (0)
; #define PG8_WAIT_V(n) asm volatile("s_waitcnt vmcnt(" #n ")" ::: "memory")
; #define PG8_WAIT_L(n) asm volatile("s_waitcnt lgkmcnt(" #n ")" ::: "memory")
; #define PG8_BAR __builtin_amdgcn_s_barrier()
; #define PG8_SCHED __builtin_amdgcn_sched_barrier(0)
; template <class Epi, class Sched, bool ALIGN_EPI = false, bool SP2 = false, bool I8 = false>
; __device__ __forceinline__ void gemm_phase(PG8_LAS unsigned char* lds, const Gemm g, const Sched& S, const Epi& E) {
;     ...
;             const char* a1 = cA + (size_t)(t + 1) * kstep;
;             const char* a2 = last ? nA : cA + (size_t)(t + 2) * kstep; const char* b2 = last ? nB : cB + (size_t)(t + 2) * kstep;
;             const char* a3 = a2 + kstep; const char* b3 = b2 + kstep;
;             if (last && has_next) S.a_ready(nxt);
;             if constexpr (SP2) {
;             PG8_LDB(B0, 0, 0); PG8_LDB(B1, 0, 1); PG8_SCHED; PG8_LDA(At, 0, 0); PG8_STAGE(PG8_SA(1, 1), a1 + hstepA, voffA);
;             PG8_WAIT_V(8); PG8_WAIT_L(0); PG8_BAR; PG8_MMA(0, 0, At, B0); PG8_MMA(0, 1, At, B1); PG8_BAR; PG8_SCHED;
;             PG8_LDA(At, 0, 1); PG8_STAGE(PG8_SB(0, 0), b2, voffB); PG8_STAGE(PG8_SB(0, 1), b2 + hstepB, voffB); PG8_STAGE(PG8_SA(0, 0), a2, voffA);
;             PG8_WAIT_V(8); PG8_WAIT_L(0); PG8_BAR; PG8_MMA(1, 0, At, B0); PG8_MMA(1, 1, At, B1); PG8_BAR; PG8_SCHED;
.LBB0_2092:
	ds_read_b128 v[130:133], v192
	ds_read_b128 v[134:137], v192 offset:1024
	ds_read_b128 v[138:141], v192 offset:2048
	ds_read_b128 v[142:145], v192 offset:3072
	ds_read_b128 v[146:149], v193
	ds_read_b128 v[150:153], v193 offset:1024
	ds_read_b128 v[154:157], v193 offset:2048
	ds_read_b128 v[158:161], v193 offset:3072
	s_add_u32 s28, s8, 0xffc00080
	s_addc_u32 s29, s9, -1
	s_cmpk_eq_i32 s51, 0xfc
	s_cselect_b32 s31, s3, s29
	s_cselect_b32 s30, s7, s28
	s_cselect_b32 s29, s21, s50
	s_cselect_b32 s28, s23, s49
	s_add_i32 m0, s38, 0xc000
	ds_read_b128 v[162:165], v194
	ds_read_b128 v[166:169], v194 offset:1024
	ds_read_b128 v[182:185], v194 offset:2048
	ds_read_b128 v[186:189], v194 offset:3072
	ds_read_b128 v[196:199], v194 offset:4096
	ds_read_b128 v[200:203], v194 offset:5120
	ds_read_b128 v[204:207], v194 offset:6144
	ds_read_b128 v[208:211], v194 offset:7168
	global_load_lds_dwordx4 v174, s[8:9]
	s_add_i32 m0, s38, 0xe000
	s_nop 0
	global_load_lds_dwordx4 v176, s[8:9]
	s_waitcnt vmcnt(8)
	s_waitcnt lgkmcnt(0)
	s_barrier
	s_waitcnt lgkmcnt(0)
	v_mfma_f32_16x16x32_bf16 v[126:129], v[130:133], v[162:165], v[126:129]
	v_mfma_f32_16x16x32_bf16 v[122:125], v[138:141], v[162:165], v[122:125]
	v_mfma_f32_16x16x32_bf16 v[110:113], v[130:133], v[182:185], v[110:113]
	v_mfma_f32_16x16x32_bf16 v[106:109], v[138:141], v[182:185], v[106:109]
	v_mfma_f32_16x16x32_bf16 v[94:97], v[130:133], v[196:199], v[94:97]
	v_mfma_f32_16x16x32_bf16 v[90:93], v[138:141], v[196:199], v[90:93]
	v_mfma_f32_16x16x32_bf16 v[78:81], v[130:133], v[204:207], v[78:81]
	v_mfma_f32_16x16x32_bf16 v[74:77], v[138:141], v[204:207], v[74:77]
	v_mfma_f32_16x16x32_bf16 v[126:129], v[134:137], v[166:169], v[126:129]
	v_mfma_f32_16x16x32_bf16 v[122:125], v[142:145], v[166:169], v[122:125]
	v_mfma_f32_16x16x32_bf16 v[110:113], v[134:137], v[186:189], v[110:113]
	v_mfma_f32_16x16x32_bf16 v[106:109], v[142:145], v[186:189], v[106:109]
	v_mfma_f32_16x16x32_bf16 v[94:97], v[134:137], v[200:203], v[94:97]
	v_mfma_f32_16x16x32_bf16 v[90:93], v[142:145], v[200:203], v[90:93]
	v_mfma_f32_16x16x32_bf16 v[78:81], v[134:137], v[208:211], v[78:81]
	v_mfma_f32_16x16x32_bf16 v[74:77], v[142:145], v[208:211], v[74:77]
	v_mfma_f32_16x16x32_bf16 v[118:121], v[146:149], v[162:165], v[118:121]
	v_mfma_f32_16x16x32_bf16 v[114:117], v[154:157], v[162:165], v[114:117]
	v_mfma_f32_16x16x32_bf16 v[102:105], v[146:149], v[182:185], v[102:105]
	v_mfma_f32_16x16x32_bf16 v[98:101], v[154:157], v[182:185], v[98:101]
	v_mfma_f32_16x16x32_bf16 v[86:89], v[146:149], v[196:199], v[86:89]
	v_mfma_f32_16x16x32_bf16 v[82:85], v[154:157], v[196:199], v[82:85]
	v_mfma_f32_16x16x32_bf16 v[70:73], v[146:149], v[204:207], v[70:73]
	v_mfma_f32_16x16x32_bf16 v[66:69], v[154:157], v[204:207], v[66:69]
	v_mfma_f32_16x16x32_bf16 v[118:121], v[150:153], v[166:169], v[118:121]
	v_mfma_f32_16x16x32_bf16 v[114:117], v[158:161], v[166:169], v[114:117]
	v_mfma_f32_16x16x32_bf16 v[102:105], v[150:153], v[186:189], v[102:105]
	v_mfma_f32_16x16x32_bf16 v[98:101], v[158:161], v[186:189], v[98:101]
	v_mfma_f32_16x16x32_bf16 v[86:89], v[150:153], v[200:203], v[86:89]
	v_mfma_f32_16x16x32_bf16 v[82:85], v[158:161], v[200:203], v[82:85]
	v_mfma_f32_16x16x32_bf16 v[70:73], v[150:153], v[208:211], v[70:73]
	v_mfma_f32_16x16x32_bf16 v[66:69], v[158:161], v[208:211], v[66:69]
	s_barrier
	s_add_i32 s52, s47, s33
	v_lshl_add_u64 v[190:191], s[28:29], 0, v[170:171]
	s_mov_b32 m0, s52
	ds_read_b128 v[162:165], v194 offset:16384
	ds_read_b128 v[166:169], v194 offset:17408
	ds_read_b128 v[182:185], v194 offset:18432
	ds_read_b128 v[186:189], v194 offset:19456
	ds_read_b128 v[196:199], v194 offset:20480
	ds_read_b128 v[200:203], v194 offset:21504
	ds_read_b128 v[204:207], v194 offset:22528
	ds_read_b128 v[208:211], v194 offset:23552
	global_load_lds_dwordx4 v170, s[28:29]
	s_add_i32 m0, s52, 0x2000
	s_add_u32 s52, s28, 0x400000
	v_lshl_add_u64 v[212:213], s[28:29], 0, v[172:173]
	s_addc_u32 s53, s29, 0
	s_add_i32 s54, s48, s33
	global_load_lds_dwordx4 v172, s[28:29]
	s_mov_b32 m0, s54
	v_lshl_add_u64 v[216:217], s[30:31], 0, v[172:173]
	global_load_lds_dwordx4 v170, s[52:53]
	s_add_i32 m0, s54, 0x2000
	s_nop 0
	global_load_lds_dwordx4 v172, s[52:53]
	v_lshl_add_u64 v[214:215], s[30:31], 0, v[170:171]
	s_mov_b32 m0, s38
	s_nop 0
	global_load_lds_dwordx4 v170, s[30:31]
	s_mov_b32 m0, s39
	s_nop 0
	global_load_lds_dwordx4 v[216:217], off
	s_waitcnt vmcnt(8)
	s_waitcnt lgkmcnt(0)
	s_barrier
	s_waitcnt lgkmcnt(0)
	v_mfma_f32_16x16x32_bf16 v[62:65], v[130:133], v[162:165], v[62:65]
	v_mfma_f32_16x16x32_bf16 v[58:61], v[138:141], v[162:165], v[58:61]
	v_mfma_f32_16x16x32_bf16 v[46:49], v[130:133], v[182:185], v[46:49]
	v_mfma_f32_16x16x32_bf16 v[42:45], v[138:141], v[182:185], v[42:45]
	v_mfma_f32_16x16x32_bf16 v[30:33], v[130:133], v[196:199], v[30:33]
	v_mfma_f32_16x16x32_bf16 v[26:29], v[138:141], v[196:199], v[26:29]
	v_mfma_f32_16x16x32_bf16 v[22:25], v[130:133], v[204:207], v[22:25]
	v_mfma_f32_16x16x32_bf16 v[10:13], v[138:141], v[204:207], v[10:13]
	v_mfma_f32_16x16x32_bf16 v[62:65], v[134:137], v[166:169], v[62:65]
	v_mfma_f32_16x16x32_bf16 v[58:61], v[142:145], v[166:169], v[58:61]
	v_mfma_f32_16x16x32_bf16 v[46:49], v[134:137], v[186:189], v[46:49]
	v_mfma_f32_16x16x32_bf16 v[42:45], v[142:145], v[186:189], v[42:45]
	v_mfma_f32_16x16x32_bf16 v[30:33], v[134:137], v[200:203], v[30:33]
	v_mfma_f32_16x16x32_bf16 v[26:29], v[142:145], v[200:203], v[26:29]
	v_mfma_f32_16x16x32_bf16 v[22:25], v[134:137], v[208:211], v[22:25]
	v_mfma_f32_16x16x32_bf16 v[10:13], v[142:145], v[208:211], v[10:13]
	v_mfma_f32_16x16x32_bf16 v[54:57], v[146:149], v[162:165], v[54:57]
	v_mfma_f32_16x16x32_bf16 v[50:53], v[154:157], v[162:165], v[50:53]
	v_mfma_f32_16x16x32_bf16 v[38:41], v[146:149], v[182:185], v[38:41]
	v_mfma_f32_16x16x32_bf16 v[34:37], v[154:157], v[182:185], v[34:37]
	v_mfma_f32_16x16x32_bf16 v[18:21], v[146:149], v[196:199], v[18:21]
	v_mfma_f32_16x16x32_bf16 v[14:17], v[154:157], v[196:199], v[14:17]
	v_mfma_f32_16x16x32_bf16 v[6:9], v[146:149], v[204:207], v[6:9]
	v_mfma_f32_16x16x32_bf16 v[2:5], v[154:157], v[204:207], v[2:5]
	v_mfma_f32_16x16x32_bf16 v[54:57], v[150:153], v[166:169], v[54:57]
	v_mfma_f32_16x16x32_bf16 v[50:53], v[158:161], v[166:169], v[50:53]
	v_mfma_f32_16x16x32_bf16 v[38:41], v[150:153], v[186:189], v[38:41]
	v_mfma_f32_16x16x32_bf16 v[34:37], v[158:161], v[186:189], v[34:37]
	v_mfma_f32_16x16x32_bf16 v[18:21], v[150:153], v[200:203], v[18:21]
	v_mfma_f32_16x16x32_bf16 v[14:17], v[158:161], v[200:203], v[14:17]
	v_mfma_f32_16x16x32_bf16 v[6:9], v[150:153], v[208:211], v[6:9]
	v_mfma_f32_16x16x32_bf16 v[2:5], v[158:161], v[208:211], v[2:5]
	s_barrier
; #define PG8_STAGE(bufoff, gbase, voff) do { _Pragma("unroll") for (int _i = 0; _i < 2; ++_i) \
;         __builtin_amdgcn_global_load_lds((const unsigned*)((const char*)(gbase) + (voff)[_i]), (PG8_LAS unsigned*)(lds + (bufoff) + ldsw + _i * 8192), 16, 0, 0); } while (0)
; #define PG8_LDA(dst, b, h) do { _Pragma("unroll") for (int m = 0; m < 4; ++m) _Pragma("unroll") for (int k = 0; k < 2; ++k) dst[m][k] = *(const PG8_LAS bf16x8*)(lds + PG8_SA(b, h) + aoff + m * 2048 + k * 1024); } while (0)
; #define PG8_LDB(dst, b, h) do { _Pragma("unroll") for (int n = 0; n < 2; ++n) _Pragma("unroll") for (int k = 0; k < 2; ++k) dst[n][k] = *(const PG8_LAS bf16x8*)(lds + PG8_SB(b, h) + boff + n * 2048 + k * 1024); } while (0)
; #define PG8_MMA(ai, bj, At, Bt) do { __builtin_amdgcn_s_setprio(1); _Pragma("unroll") for (int m = 0; m < 4; ++m) _Pragma("unroll") for (int n = 0; n < 2; ++n) _Pragma("unroll") for (int k = 0; k < 2; ++k) \
;         acc[ai][bj][m][n] = mma_<I8>(Bt[n][k], At[m][k], acc[ai][bj][m][n]); __builtin_amdgcn_s_setprio(0); } while (0)
; #define PG8_WAIT_V(n) asm volatile("s_waitcnt vmcnt(" #n ")" ::: "memory")
; #define PG8_WAIT_L(n) asm volatile("s_waitcnt lgkmcnt(" #n ")" ::: "memory")
; #define PG8_BAR __builtin_amdgcn_s_barrier()
; #define PG8_SCHED __builtin_amdgcn_sched_barrier(0)
; template <class Epi, class Sched, bool ALIGN_EPI = false, bool SP2 = false, bool I8 = false>
; __device__ __forceinline__ void gemm_phase(PG8_LAS unsigned char* lds, const Gemm g, const Sched& S, const Epi& E) {
;     ...
;         for (int t = 0; t < nt; t += 2) {
;             const bool last = (t == nt - 2);
;     ...
;             PG8_LDB(B0, 1, 0); PG8_LDB(B1, 1, 1); PG8_SCHED; PG8_LDA(At, 1, 0); PG8_STAGE(PG8_SA(0, 1), a2 + hstepA, voffA);
;             PG8_WAIT_V(8); PG8_WAIT_L(0); PG8_BAR; PG8_MMA(0, 0, At, B0); PG8_MMA(0, 1, At, B1); PG8_BAR; PG8_SCHED;
;             PG8_LDA(At, 1, 1); PG8_STAGE(PG8_SB(1, 0), b3, voffB); PG8_STAGE(PG8_SB(1, 1), b3 + hstepB, voffB); PG8_STAGE(PG8_SA(1, 0), a3, voffA);
;             PG8_WAIT_V(8); PG8_WAIT_L(0); PG8_BAR; PG8_MMA(1, 0, At, B0); PG8_MMA(1, 1, At, B1); PG8_BAR; PG8_SCHED;
	s_add_i32 s52, 0, 0x18000
	s_add_i32 s53, 0, 0x1c000
	v_add_u32_e32 v142, s52, v1
	v_add_u32_e32 v158, s53, v1
	ds_read_b128 v[130:133], v142
	ds_read_b128 v[134:137], v142 offset:1024
	ds_read_b128 v[138:141], v142 offset:2048
	ds_read_b128 v[142:145], v142 offset:3072
	ds_read_b128 v[146:149], v158
	ds_read_b128 v[150:153], v158 offset:1024
	ds_read_b128 v[154:157], v158 offset:2048
	ds_read_b128 v[158:161], v158 offset:3072
	s_add_u32 s30, s30, 0x400000
	s_addc_u32 s31, s31, 0
	s_mov_b32 m0, s40
	ds_read_b128 v[162:165], v194 offset:32768
	ds_read_b128 v[166:169], v194 offset:33792
	ds_read_b128 v[182:185], v194 offset:34816
	ds_read_b128 v[186:189], v194 offset:35840
	ds_read_b128 v[196:199], v194 offset:36864
	ds_read_b128 v[200:203], v194 offset:37888
	ds_read_b128 v[204:207], v194 offset:38912
	ds_read_b128 v[208:211], v194 offset:39936
	global_load_lds_dwordx4 v170, s[30:31]
	s_mov_b32 m0, s41
	s_nop 0
	global_load_lds_dwordx4 v172, s[30:31]
	s_waitcnt vmcnt(8)
	s_waitcnt lgkmcnt(0)
	s_barrier
	s_waitcnt lgkmcnt(0)
	v_mfma_f32_16x16x32_bf16 v[126:129], v[130:133], v[162:165], v[126:129]
	v_mfma_f32_16x16x32_bf16 v[122:125], v[138:141], v[162:165], v[122:125]
	v_mfma_f32_16x16x32_bf16 v[110:113], v[130:133], v[182:185], v[110:113]
	v_mfma_f32_16x16x32_bf16 v[106:109], v[138:141], v[182:185], v[106:109]
	v_mfma_f32_16x16x32_bf16 v[94:97], v[130:133], v[196:199], v[94:97]
	v_mfma_f32_16x16x32_bf16 v[90:93], v[138:141], v[196:199], v[90:93]
	v_mfma_f32_16x16x32_bf16 v[78:81], v[130:133], v[204:207], v[78:81]
	v_mfma_f32_16x16x32_bf16 v[74:77], v[138:141], v[204:207], v[74:77]
	v_mfma_f32_16x16x32_bf16 v[126:129], v[134:137], v[166:169], v[126:129]
	v_mfma_f32_16x16x32_bf16 v[122:125], v[142:145], v[166:169], v[122:125]
	v_mfma_f32_16x16x32_bf16 v[110:113], v[134:137], v[186:189], v[110:113]
	v_mfma_f32_16x16x32_bf16 v[106:109], v[142:145], v[186:189], v[106:109]
	v_mfma_f32_16x16x32_bf16 v[94:97], v[134:137], v[200:203], v[94:97]
	v_mfma_f32_16x16x32_bf16 v[90:93], v[142:145], v[200:203], v[90:93]
	v_mfma_f32_16x16x32_bf16 v[78:81], v[134:137], v[208:211], v[78:81]
	v_mfma_f32_16x16x32_bf16 v[74:77], v[142:145], v[208:211], v[74:77]
	v_mfma_f32_16x16x32_bf16 v[118:121], v[146:149], v[162:165], v[118:121]
	v_mfma_f32_16x16x32_bf16 v[114:117], v[154:157], v[162:165], v[114:117]
	v_mfma_f32_16x16x32_bf16 v[102:105], v[146:149], v[182:185], v[102:105]
	v_mfma_f32_16x16x32_bf16 v[98:101], v[154:157], v[182:185], v[98:101]
	v_mfma_f32_16x16x32_bf16 v[86:89], v[146:149], v[196:199], v[86:89]
	v_mfma_f32_16x16x32_bf16 v[82:85], v[154:157], v[196:199], v[82:85]
	v_mfma_f32_16x16x32_bf16 v[70:73], v[146:149], v[204:207], v[70:73]
	v_mfma_f32_16x16x32_bf16 v[66:69], v[154:157], v[204:207], v[66:69]
	v_mfma_f32_16x16x32_bf16 v[118:121], v[150:153], v[166:169], v[118:121]
	v_mfma_f32_16x16x32_bf16 v[114:117], v[158:161], v[166:169], v[114:117]
	v_mfma_f32_16x16x32_bf16 v[102:105], v[150:153], v[186:189], v[102:105]
	v_mfma_f32_16x16x32_bf16 v[98:101], v[158:161], v[186:189], v[98:101]
	v_mfma_f32_16x16x32_bf16 v[86:89], v[150:153], v[200:203], v[86:89]
	v_mfma_f32_16x16x32_bf16 v[82:85], v[158:161], v[200:203], v[82:85]
	v_mfma_f32_16x16x32_bf16 v[70:73], v[150:153], v[208:211], v[70:73]
	v_mfma_f32_16x16x32_bf16 v[66:69], v[158:161], v[208:211], v[66:69]
	s_barrier
	s_add_i32 s30, s52, s33
	v_lshl_add_u64 v[190:191], v[190:191], 0, s[14:15]
	s_mov_b32 m0, s30
	ds_read_b128 v[162:165], v194 offset:49152
	ds_read_b128 v[166:169], v194 offset:50176
	ds_read_b128 v[182:185], v194 offset:51200
	ds_read_b128 v[186:189], v194 offset:52224
	ds_read_b128 v[196:199], v194 offset:53248
	ds_read_b128 v[200:203], v194 offset:54272
	ds_read_b128 v[204:207], v194 offset:55296
	ds_read_b128 v[208:211], v194 offset:56320
	global_load_lds_dwordx4 v[190:191], off
	s_add_i32 m0, s30, 0x2000
	s_add_u32 s28, s28, 0x400080
	v_lshl_add_u64 v[190:191], v[212:213], 0, s[14:15]
	s_addc_u32 s29, s29, 0
	s_add_i32 s30, s53, s33
	global_load_lds_dwordx4 v[190:191], off
	s_mov_b32 m0, s30
	s_nop 0
	global_load_lds_dwordx4 v170, s[28:29]
	s_add_i32 m0, s30, 0x2000
	s_nop 0
	global_load_lds_dwordx4 v172, s[28:29]
	v_lshl_add_u64 v[190:191], v[214:215], 0, s[14:15]
	s_mov_b32 m0, s43
	s_nop 0
	global_load_lds_dwordx4 v[190:191], off
	v_lshl_add_u64 v[190:191], v[216:217], 0, s[14:15]
	s_mov_b32 m0, s44
	s_nop 0
	global_load_lds_dwordx4 v[190:191], off
	s_waitcnt vmcnt(8)
	s_waitcnt lgkmcnt(0)
	s_barrier
	s_waitcnt lgkmcnt(0)
	v_mfma_f32_16x16x32_bf16 v[62:65], v[130:133], v[162:165], v[62:65]
	v_mfma_f32_16x16x32_bf16 v[58:61], v[138:141], v[162:165], v[58:61]
	v_mfma_f32_16x16x32_bf16 v[46:49], v[130:133], v[182:185], v[46:49]
	v_mfma_f32_16x16x32_bf16 v[42:45], v[138:141], v[182:185], v[42:45]
	v_mfma_f32_16x16x32_bf16 v[30:33], v[130:133], v[196:199], v[30:33]
	v_mfma_f32_16x16x32_bf16 v[26:29], v[138:141], v[196:199], v[26:29]
	v_mfma_f32_16x16x32_bf16 v[22:25], v[130:133], v[204:207], v[22:25]
	v_mfma_f32_16x16x32_bf16 v[10:13], v[138:141], v[204:207], v[10:13]
	v_mfma_f32_16x16x32_bf16 v[62:65], v[134:137], v[166:169], v[62:65]
	v_mfma_f32_16x16x32_bf16 v[58:61], v[142:145], v[166:169], v[58:61]
	v_mfma_f32_16x16x32_bf16 v[46:49], v[134:137], v[186:189], v[46:49]
	v_mfma_f32_16x16x32_bf16 v[42:45], v[142:145], v[186:189], v[42:45]
	v_mfma_f32_16x16x32_bf16 v[30:33], v[134:137], v[200:203], v[30:33]
	v_mfma_f32_16x16x32_bf16 v[26:29], v[142:145], v[200:203], v[26:29]
	v_mfma_f32_16x16x32_bf16 v[22:25], v[134:137], v[208:211], v[22:25]
	v_mfma_f32_16x16x32_bf16 v[10:13], v[142:145], v[208:211], v[10:13]
	v_mfma_f32_16x16x32_bf16 v[54:57], v[146:149], v[162:165], v[54:57]
	v_mfma_f32_16x16x32_bf16 v[50:53], v[154:157], v[162:165], v[50:53]
	v_mfma_f32_16x16x32_bf16 v[38:41], v[146:149], v[182:185], v[38:41]
	v_mfma_f32_16x16x32_bf16 v[34:37], v[154:157], v[182:185], v[34:37]
	v_mfma_f32_16x16x32_bf16 v[18:21], v[146:149], v[196:199], v[18:21]
	v_mfma_f32_16x16x32_bf16 v[14:17], v[154:157], v[196:199], v[14:17]
	v_mfma_f32_16x16x32_bf16 v[6:9], v[146:149], v[204:207], v[6:9]
	v_mfma_f32_16x16x32_bf16 v[2:5], v[154:157], v[204:207], v[2:5]
	v_mfma_f32_16x16x32_bf16 v[54:57], v[150:153], v[166:169], v[54:57]
	v_mfma_f32_16x16x32_bf16 v[50:53], v[158:161], v[166:169], v[50:53]
	v_mfma_f32_16x16x32_bf16 v[38:41], v[150:153], v[186:189], v[38:41]
	v_mfma_f32_16x16x32_bf16 v[34:37], v[158:161], v[186:189], v[34:37]
	v_mfma_f32_16x16x32_bf16 v[18:21], v[150:153], v[200:203], v[18:21]
	v_mfma_f32_16x16x32_bf16 v[14:17], v[158:161], v[200:203], v[14:17]
	v_mfma_f32_16x16x32_bf16 v[6:9], v[150:153], v[208:211], v[6:9]
	v_mfma_f32_16x16x32_bf16 v[2:5], v[158:161], v[208:211], v[2:5]
	s_barrier
	s_add_i32 s51, s51, 2
	s_add_u32 s8, s8, 0x100
	s_addc_u32 s9, s9, 0
	s_add_u32 s49, s49, 0x100
	s_addc_u32 s50, s50, 0
	s_cmpk_gt_u32 s51, 0xfd
	s_cbranch_scc0 .LBB0_2092
	s_and_b64 vcc, exec, s[16:17]
	s_cbranch_vccz .LBB0_2095
	s_barrier

; #define PG8_STAGE(bufoff, gbase, voff) do { _Pragma("unroll") for (int _i = 0; _i < 2; ++_i) \
;         __builtin_amdgcn_global_load_lds((const unsigned*)((const char*)(gbase) + (voff)[_i]), (PG8_LAS unsigned*)(lds + (bufoff) + ldsw + _i * 8192), 16, 0, 0); } while (0)
; #define PG8_LDA(dst, b, h) do { _Pragma("unroll") for (int m = 0; m < 4; ++m) _Pragma("unroll") for (int k = 0; k < 2; ++k) dst[m][k] = *(const PG8_LAS bf16x8*)(lds + PG8_SA(b, h) + aoff + m * 2048 + k * 1024); } while (0)
; #define PG8_LDB(dst, b, h) do { _Pragma("unroll") for (int n = 0; n < 2; ++n) _Pragma("unroll") for (int k = 0; k < 2; ++k) dst[n][k] = *(const PG8_LAS bf16x8*)(lds + PG8_SB(b, h) + boff + n * 2048 + k * 1024); } while (0)
; #define PG8_MMA(ai, bj, At, Bt) do { __builtin_amdgcn_s_setprio(1); _Pragma("unroll") for (int m = 0; m < 4; ++m) _Pragma("unroll") for (int n = 0; n < 2; ++n) _Pragma("unroll") for (int k = 0; k < 2; ++k) \
;         acc[ai][bj][m][n] = mma_<I8>(Bt[n][k], At[m][k], acc[ai][bj][m][n]); __builtin_amdgcn_s_setprio(0); } while (0)
; #define PG8_WAIT_V(n) asm volatile("s_waitcnt vmcnt(" #n ")" ::: "memory")
; #define PG8_WAIT_L(n) asm volatile("s_waitcnt lgkmcnt(" #n ")" ::: "memory")
; #define PG8_BAR __builtin_amdgcn_s_barrier()
; #define PG8_SCHED __builtin_amdgcn_sched_barrier(0)
; template <class Epi, class Sched, bool ALIGN_EPI = false, bool SP2 = false, bool I8 = false>
; __device__ __forceinline__ void gemm_phase(PG8_LAS unsigned char* lds, const Gemm g, const Sched& S, const Epi& E) {
;     ...
;             const char* a1 = cA + (size_t)(t + 1) * kstep;
;             const char* a2 = last ? nA : cA + (size_t)(t + 2) * kstep; const char* b2 = last ? nB : cB + (size_t)(t + 2) * kstep;
;             const char* a3 = a2 + kstep; const char* b3 = b2 + kstep;
;             if (last && has_next) S.a_ready(nxt);
;             if constexpr (SP2) {
;             PG8_LDB(B0, 0, 0); PG8_LDB(B1, 0, 1); PG8_SCHED; PG8_LDA(At, 0, 0); PG8_STAGE(PG8_SA(1, 1), a1 + hstepA, voffA);
;             PG8_WAIT_V(8); PG8_WAIT_L(0); PG8_BAR; PG8_MMA(0, 0, At, B0); PG8_MMA(0, 1, At, B1); PG8_BAR; PG8_SCHED;
;             PG8_LDA(At, 0, 1); PG8_STAGE(PG8_SB(0, 0), b2, voffB); PG8_STAGE(PG8_SB(0, 1), b2 + hstepB, voffB); PG8_STAGE(PG8_SA(0, 0), a2, voffA);
;             PG8_WAIT_V(8); PG8_WAIT_L(0); PG8_BAR; PG8_MMA(1, 0, At, B0); PG8_MMA(1, 1, At, B1); PG8_BAR; PG8_SCHED;
.LBB0_2322:
	ds_read_b128 v[58:61], v183
	ds_read_b128 v[66:69], v183 offset:1024
	ds_read_b128 v[74:77], v183 offset:2048
	ds_read_b128 v[78:81], v183 offset:3072
	ds_read_b128 v[146:149], v189
	ds_read_b128 v[150:153], v189 offset:1024
	ds_read_b128 v[154:157], v189 offset:2048
	ds_read_b128 v[158:161], v189 offset:3072
	s_add_u32 s28, s26, 0xfff80080
	s_addc_u32 s29, s27, -1
	s_cmp_eq_u32 s53, 28
	s_cselect_b32 s31, s21, s29
	s_cselect_b32 s30, s49, s28
	s_cselect_b32 s29, s19, s52
	s_cselect_b32 s28, s50, s51
	s_add_i32 m0, s3, 0xc000
	ds_read_b128 v[162:165], v193
	ds_read_b128 v[178:181], v193 offset:1024
	ds_read_b128 v[184:187], v193 offset:2048
	ds_read_b128 v[198:201], v193 offset:3072
	ds_read_b128 v[202:205], v193 offset:4096
	ds_read_b128 v[206:209], v193 offset:5120
	ds_read_b128 v[210:213], v193 offset:6144
	ds_read_b128 v[214:217], v193 offset:7168
	global_load_lds_dwordx4 v170, s[26:27]
	s_add_i32 m0, s3, 0xe000
	s_nop 0
	global_load_lds_dwordx4 v172, s[26:27]
	s_waitcnt vmcnt(8)
	s_waitcnt lgkmcnt(0)
	s_barrier
	s_waitcnt lgkmcnt(0)
	v_mfma_i32_16x16x64_i8 v[142:145], v[58:61], v[162:165], v[142:145]
	v_mfma_i32_16x16x64_i8 v[138:141], v[74:77], v[162:165], v[138:141]
	v_mfma_i32_16x16x64_i8 v[126:129], v[58:61], v[184:187], v[126:129]
	v_mfma_i32_16x16x64_i8 v[122:125], v[74:77], v[184:187], v[122:125]
	v_mfma_i32_16x16x64_i8 v[110:113], v[58:61], v[202:205], v[110:113]
	v_mfma_i32_16x16x64_i8 v[106:109], v[74:77], v[202:205], v[106:109]
	v_mfma_i32_16x16x64_i8 v[94:97], v[58:61], v[210:213], v[94:97]
	v_mfma_i32_16x16x64_i8 v[90:93], v[74:77], v[210:213], v[90:93]
	v_mfma_i32_16x16x64_i8 v[142:145], v[66:69], v[178:181], v[142:145]
	v_mfma_i32_16x16x64_i8 v[138:141], v[78:81], v[178:181], v[138:141]
	v_mfma_i32_16x16x64_i8 v[126:129], v[66:69], v[198:201], v[126:129]
	v_mfma_i32_16x16x64_i8 v[122:125], v[78:81], v[198:201], v[122:125]
	v_mfma_i32_16x16x64_i8 v[110:113], v[66:69], v[206:209], v[110:113]
	v_mfma_i32_16x16x64_i8 v[106:109], v[78:81], v[206:209], v[106:109]
	v_mfma_i32_16x16x64_i8 v[94:97], v[66:69], v[214:217], v[94:97]
	v_mfma_i32_16x16x64_i8 v[90:93], v[78:81], v[214:217], v[90:93]
	v_mfma_i32_16x16x64_i8 v[134:137], v[146:149], v[162:165], v[134:137]
	v_mfma_i32_16x16x64_i8 v[130:133], v[154:157], v[162:165], v[130:133]
	v_mfma_i32_16x16x64_i8 v[118:121], v[146:149], v[184:187], v[118:121]
	v_mfma_i32_16x16x64_i8 v[114:117], v[154:157], v[184:187], v[114:117]
	v_mfma_i32_16x16x64_i8 v[102:105], v[146:149], v[202:205], v[102:105]
	v_mfma_i32_16x16x64_i8 v[98:101], v[154:157], v[202:205], v[98:101]
	v_mfma_i32_16x16x64_i8 v[86:89], v[146:149], v[210:213], v[86:89]
	v_mfma_i32_16x16x64_i8 v[82:85], v[154:157], v[210:213], v[82:85]
	v_mfma_i32_16x16x64_i8 v[134:137], v[150:153], v[178:181], v[134:137]
	v_mfma_i32_16x16x64_i8 v[130:133], v[158:161], v[178:181], v[130:133]
	v_mfma_i32_16x16x64_i8 v[118:121], v[150:153], v[198:201], v[118:121]
	v_mfma_i32_16x16x64_i8 v[114:117], v[158:161], v[198:201], v[114:117]
	v_mfma_i32_16x16x64_i8 v[102:105], v[150:153], v[206:209], v[102:105]
	v_mfma_i32_16x16x64_i8 v[98:101], v[158:161], v[206:209], v[98:101]
	v_mfma_i32_16x16x64_i8 v[86:89], v[150:153], v[214:217], v[86:89]
	v_mfma_i32_16x16x64_i8 v[82:85], v[158:161], v[214:217], v[82:85]
	s_barrier
	s_add_i32 s54, s46, s38
	v_lshl_add_u64 v[190:191], s[28:29], 0, v[166:167]
	s_mov_b32 m0, s54
	ds_read_b128 v[162:165], v193 offset:16384
	ds_read_b128 v[178:181], v193 offset:17408
	ds_read_b128 v[184:187], v193 offset:18432
	ds_read_b128 v[198:201], v193 offset:19456
	ds_read_b128 v[202:205], v193 offset:20480
	ds_read_b128 v[206:209], v193 offset:21504
	ds_read_b128 v[210:213], v193 offset:22528
	ds_read_b128 v[214:217], v193 offset:23552
	global_load_lds_dwordx4 v166, s[28:29]
	s_add_i32 m0, s54, 0x2000
	s_add_u32 s54, s28, 0x80000
	v_lshl_add_u64 v[194:195], s[28:29], 0, v[168:169]
	s_addc_u32 s55, s29, 0
	s_add_i32 s56, s47, s38
	global_load_lds_dwordx4 v168, s[28:29]
	s_mov_b32 m0, s56
	v_lshl_add_u64 v[220:221], s[30:31], 0, v[168:169]
	global_load_lds_dwordx4 v166, s[54:55]
	s_add_i32 m0, s56, 0x2000
	s_nop 0
	global_load_lds_dwordx4 v168, s[54:55]
	v_lshl_add_u64 v[218:219], s[30:31], 0, v[166:167]
	s_mov_b32 m0, s3
	s_nop 0
	global_load_lds_dwordx4 v166, s[30:31]
	s_mov_b32 m0, s39
	s_nop 0
	global_load_lds_dwordx4 v[220:221], off
	s_waitcnt vmcnt(8)
	s_waitcnt lgkmcnt(0)
	s_barrier
	s_waitcnt lgkmcnt(0)
	v_mfma_i32_16x16x64_i8 v[70:73], v[58:61], v[162:165], v[70:73]
	v_mfma_i32_16x16x64_i8 v[62:65], v[74:77], v[162:165], v[62:65]
	v_mfma_i32_16x16x64_i8 v[46:49], v[58:61], v[184:187], v[46:49]
	v_mfma_i32_16x16x64_i8 v[42:45], v[74:77], v[184:187], v[42:45]
	v_mfma_i32_16x16x64_i8 v[30:33], v[58:61], v[202:205], v[30:33]
	v_mfma_i32_16x16x64_i8 v[26:29], v[74:77], v[202:205], v[26:29]
	v_mfma_i32_16x16x64_i8 v[14:17], v[58:61], v[210:213], v[14:17]
	v_mfma_i32_16x16x64_i8 v[10:13], v[74:77], v[210:213], v[10:13]
	v_mfma_i32_16x16x64_i8 v[70:73], v[66:69], v[178:181], v[70:73]
	v_mfma_i32_16x16x64_i8 v[62:65], v[78:81], v[178:181], v[62:65]
	v_mfma_i32_16x16x64_i8 v[46:49], v[66:69], v[198:201], v[46:49]
	v_mfma_i32_16x16x64_i8 v[42:45], v[78:81], v[198:201], v[42:45]
	v_mfma_i32_16x16x64_i8 v[30:33], v[66:69], v[206:209], v[30:33]
	v_mfma_i32_16x16x64_i8 v[26:29], v[78:81], v[206:209], v[26:29]
	v_mfma_i32_16x16x64_i8 v[14:17], v[66:69], v[214:217], v[14:17]
	v_mfma_i32_16x16x64_i8 v[10:13], v[78:81], v[214:217], v[10:13]
	v_mfma_i32_16x16x64_i8 v[54:57], v[146:149], v[162:165], v[54:57]
	v_mfma_i32_16x16x64_i8 v[50:53], v[154:157], v[162:165], v[50:53]
	v_mfma_i32_16x16x64_i8 v[38:41], v[146:149], v[184:187], v[38:41]
	v_mfma_i32_16x16x64_i8 v[34:37], v[154:157], v[184:187], v[34:37]
	v_mfma_i32_16x16x64_i8 v[22:25], v[146:149], v[202:205], v[22:25]
	v_mfma_i32_16x16x64_i8 v[18:21], v[154:157], v[202:205], v[18:21]
	v_mfma_i32_16x16x64_i8 v[6:9], v[146:149], v[210:213], v[6:9]
	v_mfma_i32_16x16x64_i8 v[2:5], v[154:157], v[210:213], v[2:5]
	v_mfma_i32_16x16x64_i8 v[54:57], v[150:153], v[178:181], v[54:57]
	v_mfma_i32_16x16x64_i8 v[50:53], v[158:161], v[178:181], v[50:53]
	v_mfma_i32_16x16x64_i8 v[38:41], v[150:153], v[198:201], v[38:41]
	v_mfma_i32_16x16x64_i8 v[34:37], v[158:161], v[198:201], v[34:37]
	v_mfma_i32_16x16x64_i8 v[22:25], v[150:153], v[206:209], v[22:25]
	v_mfma_i32_16x16x64_i8 v[18:21], v[158:161], v[206:209], v[18:21]
	v_mfma_i32_16x16x64_i8 v[6:9], v[150:153], v[214:217], v[6:9]
	v_mfma_i32_16x16x64_i8 v[2:5], v[158:161], v[214:217], v[2:5]
	s_barrier
; #define PG8_STAGE(bufoff, gbase, voff) do { _Pragma("unroll") for (int _i = 0; _i < 2; ++_i) \
;         __builtin_amdgcn_global_load_lds((const unsigned*)((const char*)(gbase) + (voff)[_i]), (PG8_LAS unsigned*)(lds + (bufoff) + ldsw + _i * 8192), 16, 0, 0); } while (0)
; #define PG8_LDA(dst, b, h) do { _Pragma("unroll") for (int m = 0; m < 4; ++m) _Pragma("unroll") for (int k = 0; k < 2; ++k) dst[m][k] = *(const PG8_LAS bf16x8*)(lds + PG8_SA(b, h) + aoff + m * 2048 + k * 1024); } while (0)
; #define PG8_LDB(dst, b, h) do { _Pragma("unroll") for (int n = 0; n < 2; ++n) _Pragma("unroll") for (int k = 0; k < 2; ++k) dst[n][k] = *(const PG8_LAS bf16x8*)(lds + PG8_SB(b, h) + boff + n * 2048 + k * 1024); } while (0)
; #define PG8_MMA(ai, bj, At, Bt) do { __builtin_amdgcn_s_setprio(1); _Pragma("unroll") for (int m = 0; m < 4; ++m) _Pragma("unroll") for (int n = 0; n < 2; ++n) _Pragma("unroll") for (int k = 0; k < 2; ++k) \
;         acc[ai][bj][m][n] = mma_<I8>(Bt[n][k], At[m][k], acc[ai][bj][m][n]); __builtin_amdgcn_s_setprio(0); } while (0)
; #define PG8_WAIT_V(n) asm volatile("s_waitcnt vmcnt(" #n ")" ::: "memory")
; #define PG8_WAIT_L(n) asm volatile("s_waitcnt lgkmcnt(" #n ")" ::: "memory")
; #define PG8_BAR __builtin_amdgcn_s_barrier()
; #define PG8_SCHED __builtin_amdgcn_sched_barrier(0)
; template <class Epi, class Sched, bool ALIGN_EPI = false, bool SP2 = false, bool I8 = false>
; __device__ __forceinline__ void gemm_phase(PG8_LAS unsigned char* lds, const Gemm g, const Sched& S, const Epi& E) {
;     ...
;         for (int t = 0; t < nt; t += 2) {
;             const bool last = (t == nt - 2);
;     ...
;             PG8_LDB(B0, 1, 0); PG8_LDB(B1, 1, 1); PG8_SCHED; PG8_LDA(At, 1, 0); PG8_STAGE(PG8_SA(0, 1), a2 + hstepA, voffA);
;             PG8_WAIT_V(8); PG8_WAIT_L(0); PG8_BAR; PG8_MMA(0, 0, At, B0); PG8_MMA(0, 1, At, B1); PG8_BAR; PG8_SCHED;
;             PG8_LDA(At, 1, 1); PG8_STAGE(PG8_SB(1, 0), b3, voffB); PG8_STAGE(PG8_SB(1, 1), b3 + hstepB, voffB); PG8_STAGE(PG8_SA(1, 0), a3, voffA);
;             PG8_WAIT_V(8); PG8_WAIT_L(0); PG8_BAR; PG8_MMA(1, 0, At, B0); PG8_MMA(1, 1, At, B1); PG8_BAR; PG8_SCHED;
	s_add_i32 s54, 0, 0x18000
	s_add_i32 s55, 0, 0x1c000
	v_add_u32_e32 v78, s54, v1
	v_add_u32_e32 v158, s55, v1
	ds_read_b128 v[58:61], v78
	ds_read_b128 v[66:69], v78 offset:1024
	ds_read_b128 v[74:77], v78 offset:2048
	ds_read_b128 v[78:81], v78 offset:3072
	ds_read_b128 v[146:149], v158
	ds_read_b128 v[150:153], v158 offset:1024
	ds_read_b128 v[154:157], v158 offset:2048
	ds_read_b128 v[158:161], v158 offset:3072
	s_add_u32 s30, s30, 0x80000
	s_addc_u32 s31, s31, 0
	s_mov_b32 m0, s40
	ds_read_b128 v[162:165], v193 offset:32768
	ds_read_b128 v[178:181], v193 offset:33792
	ds_read_b128 v[184:187], v193 offset:34816
	ds_read_b128 v[198:201], v193 offset:35840
	ds_read_b128 v[202:205], v193 offset:36864
	ds_read_b128 v[206:209], v193 offset:37888
	ds_read_b128 v[210:213], v193 offset:38912
	ds_read_b128 v[214:217], v193 offset:39936
	global_load_lds_dwordx4 v166, s[30:31]
	s_mov_b32 m0, s41
	s_nop 0
	global_load_lds_dwordx4 v168, s[30:31]
	s_waitcnt vmcnt(8)
	s_waitcnt lgkmcnt(0)
	s_barrier
	s_waitcnt lgkmcnt(0)
	v_mfma_i32_16x16x64_i8 v[142:145], v[58:61], v[162:165], v[142:145]
	v_mfma_i32_16x16x64_i8 v[138:141], v[74:77], v[162:165], v[138:141]
	v_mfma_i32_16x16x64_i8 v[126:129], v[58:61], v[184:187], v[126:129]
	v_mfma_i32_16x16x64_i8 v[122:125], v[74:77], v[184:187], v[122:125]
	v_mfma_i32_16x16x64_i8 v[110:113], v[58:61], v[202:205], v[110:113]
	v_mfma_i32_16x16x64_i8 v[106:109], v[74:77], v[202:205], v[106:109]
	v_mfma_i32_16x16x64_i8 v[94:97], v[58:61], v[210:213], v[94:97]
	v_mfma_i32_16x16x64_i8 v[90:93], v[74:77], v[210:213], v[90:93]
	v_mfma_i32_16x16x64_i8 v[142:145], v[66:69], v[178:181], v[142:145]
	v_mfma_i32_16x16x64_i8 v[138:141], v[78:81], v[178:181], v[138:141]
	v_mfma_i32_16x16x64_i8 v[126:129], v[66:69], v[198:201], v[126:129]
	v_mfma_i32_16x16x64_i8 v[122:125], v[78:81], v[198:201], v[122:125]
	v_mfma_i32_16x16x64_i8 v[110:113], v[66:69], v[206:209], v[110:113]
	v_mfma_i32_16x16x64_i8 v[106:109], v[78:81], v[206:209], v[106:109]
	v_mfma_i32_16x16x64_i8 v[94:97], v[66:69], v[214:217], v[94:97]
	v_mfma_i32_16x16x64_i8 v[90:93], v[78:81], v[214:217], v[90:93]
	v_mfma_i32_16x16x64_i8 v[134:137], v[146:149], v[162:165], v[134:137]
	v_mfma_i32_16x16x64_i8 v[130:133], v[154:157], v[162:165], v[130:133]
	v_mfma_i32_16x16x64_i8 v[118:121], v[146:149], v[184:187], v[118:121]
	v_mfma_i32_16x16x64_i8 v[114:117], v[154:157], v[184:187], v[114:117]
	v_mfma_i32_16x16x64_i8 v[102:105], v[146:149], v[202:205], v[102:105]
	v_mfma_i32_16x16x64_i8 v[98:101], v[154:157], v[202:205], v[98:101]
	v_mfma_i32_16x16x64_i8 v[86:89], v[146:149], v[210:213], v[86:89]
	v_mfma_i32_16x16x64_i8 v[82:85], v[154:157], v[210:213], v[82:85]
	v_mfma_i32_16x16x64_i8 v[134:137], v[150:153], v[178:181], v[134:137]
	v_mfma_i32_16x16x64_i8 v[130:133], v[158:161], v[178:181], v[130:133]
	v_mfma_i32_16x16x64_i8 v[118:121], v[150:153], v[198:201], v[118:121]
	v_mfma_i32_16x16x64_i8 v[114:117], v[158:161], v[198:201], v[114:117]
	v_mfma_i32_16x16x64_i8 v[102:105], v[150:153], v[206:209], v[102:105]
	v_mfma_i32_16x16x64_i8 v[98:101], v[158:161], v[206:209], v[98:101]
	v_mfma_i32_16x16x64_i8 v[86:89], v[150:153], v[214:217], v[86:89]
	v_mfma_i32_16x16x64_i8 v[82:85], v[158:161], v[214:217], v[82:85]
	s_barrier
	s_add_i32 s30, s54, s38
	v_lshl_add_u64 v[190:191], v[190:191], 0, s[14:15]
	s_mov_b32 m0, s30
	ds_read_b128 v[162:165], v193 offset:49152
	ds_read_b128 v[178:181], v193 offset:50176
	ds_read_b128 v[184:187], v193 offset:51200
	ds_read_b128 v[198:201], v193 offset:52224
	ds_read_b128 v[202:205], v193 offset:53248
	ds_read_b128 v[206:209], v193 offset:54272
	ds_read_b128 v[210:213], v193 offset:55296
	ds_read_b128 v[214:217], v193 offset:56320
	global_load_lds_dwordx4 v[190:191], off
	s_add_i32 m0, s30, 0x2000
	s_add_u32 s28, s28, 0x80080
	v_lshl_add_u64 v[190:191], v[194:195], 0, s[14:15]
	s_addc_u32 s29, s29, 0
	s_add_i32 s30, s55, s38
	global_load_lds_dwordx4 v[190:191], off
	s_mov_b32 m0, s30
	s_nop 0
	global_load_lds_dwordx4 v166, s[28:29]
	s_add_i32 m0, s30, 0x2000
	s_nop 0
	global_load_lds_dwordx4 v168, s[28:29]
	v_lshl_add_u64 v[190:191], v[218:219], 0, s[14:15]
	s_mov_b32 m0, s43
	s_nop 0
	global_load_lds_dwordx4 v[190:191], off
	v_lshl_add_u64 v[190:191], v[220:221], 0, s[14:15]
	s_mov_b32 m0, s44
	s_nop 0
	global_load_lds_dwordx4 v[190:191], off
	s_waitcnt vmcnt(8)
	s_waitcnt lgkmcnt(0)
	s_barrier
	s_waitcnt lgkmcnt(0)
	v_mfma_i32_16x16x64_i8 v[70:73], v[58:61], v[162:165], v[70:73]
	v_mfma_i32_16x16x64_i8 v[62:65], v[74:77], v[162:165], v[62:65]
	v_mfma_i32_16x16x64_i8 v[46:49], v[58:61], v[184:187], v[46:49]
	v_mfma_i32_16x16x64_i8 v[42:45], v[74:77], v[184:187], v[42:45]
	v_mfma_i32_16x16x64_i8 v[30:33], v[58:61], v[202:205], v[30:33]
	v_mfma_i32_16x16x64_i8 v[26:29], v[74:77], v[202:205], v[26:29]
	v_mfma_i32_16x16x64_i8 v[14:17], v[58:61], v[210:213], v[14:17]
	v_mfma_i32_16x16x64_i8 v[10:13], v[74:77], v[210:213], v[10:13]
	v_mfma_i32_16x16x64_i8 v[70:73], v[66:69], v[178:181], v[70:73]
	v_mfma_i32_16x16x64_i8 v[62:65], v[78:81], v[178:181], v[62:65]
	v_mfma_i32_16x16x64_i8 v[46:49], v[66:69], v[198:201], v[46:49]
	v_mfma_i32_16x16x64_i8 v[42:45], v[78:81], v[198:201], v[42:45]
	v_mfma_i32_16x16x64_i8 v[30:33], v[66:69], v[206:209], v[30:33]
	v_mfma_i32_16x16x64_i8 v[26:29], v[78:81], v[206:209], v[26:29]
	v_mfma_i32_16x16x64_i8 v[14:17], v[66:69], v[214:217], v[14:17]
	v_mfma_i32_16x16x64_i8 v[10:13], v[78:81], v[214:217], v[10:13]
	v_mfma_i32_16x16x64_i8 v[54:57], v[146:149], v[162:165], v[54:57]
	v_mfma_i32_16x16x64_i8 v[50:53], v[154:157], v[162:165], v[50:53]
	v_mfma_i32_16x16x64_i8 v[38:41], v[146:149], v[184:187], v[38:41]
	v_mfma_i32_16x16x64_i8 v[34:37], v[154:157], v[184:187], v[34:37]
	v_mfma_i32_16x16x64_i8 v[22:25], v[146:149], v[202:205], v[22:25]
	v_mfma_i32_16x16x64_i8 v[18:21], v[154:157], v[202:205], v[18:21]
	v_mfma_i32_16x16x64_i8 v[6:9], v[146:149], v[210:213], v[6:9]
	v_mfma_i32_16x16x64_i8 v[2:5], v[154:157], v[210:213], v[2:5]
	v_mfma_i32_16x16x64_i8 v[54:57], v[150:153], v[178:181], v[54:57]
	v_mfma_i32_16x16x64_i8 v[50:53], v[158:161], v[178:181], v[50:53]
	v_mfma_i32_16x16x64_i8 v[38:41], v[150:153], v[198:201], v[38:41]
	v_mfma_i32_16x16x64_i8 v[34:37], v[158:161], v[198:201], v[34:37]
	v_mfma_i32_16x16x64_i8 v[22:25], v[150:153], v[206:209], v[22:25]
	v_mfma_i32_16x16x64_i8 v[18:21], v[158:161], v[206:209], v[18:21]
	v_mfma_i32_16x16x64_i8 v[6:9], v[150:153], v[214:217], v[6:9]
	v_mfma_i32_16x16x64_i8 v[2:5], v[158:161], v[214:217], v[2:5]
	s_barrier
	s_add_i32 s53, s53, 2
	s_add_u32 s26, s26, 0x100
	s_addc_u32 s27, s27, 0
	s_add_u32 s51, s51, 0x100
	s_addc_u32 s52, s52, 0
	s_cmp_gt_u32 s53, 29
	s_cbranch_scc0 .LBB0_2322
	s_and_b64 vcc, exec, s[16:17]
	s_cbranch_vccz .LBB0_2325
	s_barrier
